# D1 l2norm reductions: 16-lane xor butterflies via DPP row permutes (quad_perm, row_half_mirror, row_mirror) instead of ds_bpermute round trips
# speedup vs baseline: 1.0074x; 1.0041x over previous
.LBB0_505:
	s_waitcnt vmcnt(0)
	v_lshlrev_b32_e32 v206, 16, v170
	v_and_b32_e32 v207, 0xffff0000, v170
	v_and_b32_e32 v205, 0xffff0000, v171
	v_lshlrev_b32_e32 v204, 16, v171
	v_and_b32_e32 v181, 0xffff0000, v172
	v_lshlrev_b32_e32 v180, 16, v172
	v_and_b32_e32 v171, 0xffff0000, v173
	v_lshlrev_b32_e32 v170, 16, v173
	v_lshlrev_b32_e32 v172, 16, v162
	v_and_b32_e32 v173, 0xffff0000, v162
	v_pk_mul_f32 v[202:203], v[150:151], v[206:207]
	v_lshlrev_b32_e32 v208, 16, v166
	v_and_b32_e32 v209, 0xffff0000, v166
	v_pk_fma_f32 v[172:173], v[146:147], v[172:173], v[202:203]
	v_lshlrev_b32_e32 v196, 16, v0
	v_and_b32_e32 v197, 0xffff0000, v0
	v_pk_fma_f32 v[172:173], v[154:155], v[208:209], v[172:173]
	v_and_b32_e32 v177, 0xffff0000, v169
	v_pk_fma_f32 v[172:173], v[158:159], v[196:197], v[172:173]
	v_lshlrev_b32_e32 v176, 16, v169
	v_mul_f32_e32 v169, 0xbfb8aa3b, v172
	v_exp_f32_e32 v169, v169
	v_and_b32_e32 v185, 0xffff0000, v163
	v_lshlrev_b32_e32 v184, 16, v163
	v_and_b32_e32 v201, 0xffff0000, v167
	v_add_f32_e32 v169, 1.0, v169
	v_rcp_f32_e32 v202, v169
	v_mul_f32_e32 v169, 0xbfb8aa3b, v173
	v_exp_f32_e32 v169, v169
	v_lshlrev_b32_e32 v200, 16, v167
	v_and_b32_e32 v175, 0xffff0000, v1
	v_lshlrev_b32_e32 v174, 16, v1
	v_add_f32_e32 v169, 1.0, v169
	v_rcp_f32_e32 v203, v169
	v_and_b32_e32 v163, 0xffff0000, v164
	v_lshlrev_b32_e32 v162, 16, v164
	v_and_b32_e32 v199, 0xffff0000, v168
	v_pk_mul_f32 v[172:173], v[172:173], v[202:203]
	v_pk_mul_f32 v[202:203], v[152:153], v[204:205]
	v_lshlrev_b32_e32 v198, 16, v168
	v_pk_fma_f32 v[184:185], v[148:149], v[184:185], v[202:203]
	v_and_b32_e32 v167, 0xffff0000, v2
	v_pk_fma_f32 v[184:185], v[156:157], v[200:201], v[184:185]
	v_lshlrev_b32_e32 v166, 16, v2
	v_pk_fma_f32 v[184:185], v[160:161], v[174:175], v[184:185]
	v_and_b32_e32 v187, 0xffff0000, v165
	v_mul_f32_e32 v169, 0xbfb8aa3b, v184
	v_exp_f32_e32 v169, v169
	v_lshlrev_b32_e32 v186, 16, v165
	v_and_b32_e32 v165, 0xffff0000, v3
	v_lshlrev_b32_e32 v164, 16, v3
	v_add_f32_e32 v169, 1.0, v169
	v_rcp_f32_e32 v202, v169
	v_mul_f32_e32 v169, 0xbfb8aa3b, v185
	v_exp_f32_e32 v169, v169
	s_mul_i32 s22, s22, -6
	s_add_i32 s0, s14, s22
	s_ashr_i32 s22, s0, 1
	v_add_f32_e32 v169, 1.0, v169
	v_rcp_f32_e32 v203, v169
	s_cmp_lt_u32 s0, 2
	s_cselect_b64 vcc, -1, 0
	s_cmp_lt_i32 s22, 2
	v_pk_mul_f32 v[202:203], v[184:185], v[202:203]
	v_pk_mul_f32 v[184:185], v[134:135], v[180:181]
	s_cselect_b64 s[8:9], -1, 0
	v_pk_fma_f32 v[162:163], v[130:131], v[162:163], v[184:185]
	s_cmp_gt_i32 s22, 1
	v_pk_fma_f32 v[162:163], v[138:139], v[198:199], v[162:163]
	v_mov_b32_e32 v168, 1.0
	v_pk_fma_f32 v[162:163], v[142:143], v[166:167], v[162:163]
	v_cndmask_b32_e32 v219, 1.0, v238, vcc
	v_mul_f32_e32 v169, 0xbfb8aa3b, v162
	v_exp_f32_e32 v169, v169
	v_mov_b32_e32 v214, 1.0
	v_add_f32_e32 v169, 1.0, v169
	v_rcp_f32_e32 v184, v169
	v_mul_f32_e32 v169, 0xbfb8aa3b, v163
	v_exp_f32_e32 v169, v169
	s_nop 0
	v_add_f32_e32 v169, 1.0, v169
	v_rcp_f32_e32 v185, v169
	s_nop 0
	v_pk_mul_f32 v[210:211], v[162:163], v[184:185]
	v_pk_mul_f32 v[162:163], v[136:137], v[170:171]
	s_nop 0
	v_pk_fma_f32 v[162:163], v[132:133], v[186:187], v[162:163]
	s_nop 0
	v_pk_fma_f32 v[162:163], v[140:141], v[176:177], v[162:163]
	s_nop 0
	v_pk_fma_f32 v[162:163], v[144:145], v[164:165], v[162:163]
	s_nop 0
	v_mul_f32_e32 v169, 0xbfb8aa3b, v162
	v_exp_f32_e32 v169, v169
	s_nop 0
	v_add_f32_e32 v169, 1.0, v169
	v_rcp_f32_e32 v184, v169
	v_mul_f32_e32 v169, 0xbfb8aa3b, v163
	v_exp_f32_e32 v169, v169
	s_nop 0
	v_add_f32_e32 v169, 1.0, v169
	v_rcp_f32_e32 v185, v169
	s_nop 0
	v_pk_mul_f32 v[212:213], v[162:163], v[184:185]
	s_cbranch_scc1 .LBB0_507
	v_pk_mul_f32 v[162:163], v[172:173], v[172:173]
	v_pk_mul_f32 v[184:185], v[202:203], v[202:203]
	v_add_f32_e32 v162, v162, v163
	v_add_f32_e32 v162, v184, v162
	v_pk_mul_f32 v[186:187], v[210:211], v[210:211]
	v_add_f32_e32 v162, v185, v162
	v_and_b32_e32 v169, 64, v232
	v_add_f32_e32 v162, v186, v162
	v_xor_b32_e32 v163, 1, v232
	v_add_u32_e32 v169, 64, v169
	v_pk_mul_f32 v[214:215], v[212:213], v[212:213]
	v_add_f32_e32 v162, v187, v162
	v_cmp_lt_i32_e64 s[0:1], v163, v169
	v_add_f32_e32 v162, v214, v162
	v_add_f32_e32 v162, v215, v162
	v_cndmask_b32_e64 v163, v232, v163, s[0:1]
	v_lshlrev_b32_e32 v163, 2, v163
	s_nop 1
	v_mov_b32_dpp v163, v162 quad_perm:[1,0,3,2] row_mask:0xf bank_mask:0xf
	s_waitcnt lgkmcnt(0)
	v_add_f32_e32 v162, v162, v163
	v_xor_b32_e32 v163, 2, v232
	v_cmp_lt_i32_e64 s[0:1], v163, v169
	s_nop 1
	v_cndmask_b32_e64 v163, v232, v163, s[0:1]
	v_lshlrev_b32_e32 v163, 2, v163
	s_nop 1
	v_mov_b32_dpp v163, v162 quad_perm:[2,3,0,1] row_mask:0xf bank_mask:0xf
	s_waitcnt lgkmcnt(0)
	v_add_f32_e32 v162, v162, v163
	v_xor_b32_e32 v163, 4, v232
	v_cmp_lt_i32_e64 s[0:1], v163, v169
	s_nop 1
	v_cndmask_b32_e64 v163, v232, v163, s[0:1]
	v_lshlrev_b32_e32 v163, 2, v163
	s_nop 1
	v_mov_b32_dpp v163, v162 row_half_mirror row_mask:0xf bank_mask:0xf
	s_waitcnt lgkmcnt(0)
	v_add_f32_e32 v162, v162, v163
	v_xor_b32_e32 v163, 8, v232
	v_cmp_lt_i32_e64 s[0:1], v163, v169
	s_nop 1
	v_cndmask_b32_e64 v163, v232, v163, s[0:1]
	v_lshlrev_b32_e32 v163, 2, v163
	s_nop 1
	v_mov_b32_dpp v163, v162 row_mirror row_mask:0xf bank_mask:0xf
	s_waitcnt lgkmcnt(0)
	v_add_f32_e32 v162, v162, v163
	v_add_f32_e32 v162, 0x358637bd, v162
	v_rsq_f32_e32 v162, v162
	s_nop 0
	v_mul_f32_e32 v214, v219, v162
.LBB0_507:
	v_pk_mul_f32 v[172:173], v[172:173], v[214:215] op_sel_hi:[1,0]
	v_pk_mul_f32 v[184:185], v[150:151], v[208:209]
	v_cvt_pk_bf16_f32 v220, v172, v173
	v_pk_mul_f32 v[172:173], v[202:203], v[214:215] op_sel_hi:[1,0]
	v_pk_fma_f32 v[184:185], v[146:147], v[206:207], v[184:185]
	v_cvt_pk_bf16_f32 v221, v172, v173
	v_pk_mul_f32 v[172:173], v[210:211], v[214:215] op_sel_hi:[1,0]
	v_lshlrev_b32_e32 v210, 16, v4
	v_and_b32_e32 v211, 0xffff0000, v4
	v_pk_fma_f32 v[184:185], v[154:155], v[196:197], v[184:185]
	v_and_b32_e32 v203, 0xffff0000, v5
	v_pk_fma_f32 v[184:185], v[158:159], v[210:211], v[184:185]
	v_lshlrev_b32_e32 v202, 16, v5
	v_mul_f32_e32 v169, 0xbfb8aa3b, v184
	v_exp_f32_e32 v169, v169
	v_lshrrev_b32_e32 v162, 7, v178
	v_and_b32_e32 v179, 0xffff0000, v6
	v_lshlrev_b32_e32 v178, 16, v6
	v_add_f32_e32 v169, 1.0, v169
	v_rcp_f32_e32 v186, v169
	v_mul_f32_e32 v169, 0xbfb8aa3b, v185
	v_exp_f32_e32 v169, v169
	v_cvt_pk_bf16_f32 v222, v172, v173
	v_pk_mul_f32 v[172:173], v[212:213], v[214:215] op_sel_hi:[1,0]
	s_ashr_i32 s0, s11, 9
	v_add_f32_e32 v169, 1.0, v169
	v_rcp_f32_e32 v187, v169
	v_cvt_pk_bf16_f32 v223, v172, v173
	v_and_b32_e32 v173, 0xffff0000, v7
	v_lshlrev_b32_e32 v172, 16, v7
	v_pk_mul_f32 v[206:207], v[184:185], v[186:187]
	v_pk_mul_f32 v[184:185], v[152:153], v[200:201]
	s_add_i32 s11, s0, s20
	v_pk_fma_f32 v[184:185], v[148:149], v[204:205], v[184:185]
	s_cmp_eq_u32 s22, 1
	v_pk_fma_f32 v[184:185], v[156:157], v[174:175], v[184:185]
	s_mov_b32 s0, 0x1f100000
	v_pk_fma_f32 v[184:185], v[160:161], v[202:203], v[184:185]
	s_cselect_b32 s20, 0x1d100000, s0
	v_mul_f32_e32 v169, 0xbfb8aa3b, v184
	v_exp_f32_e32 v169, v169
	s_and_b64 s[0:1], vcc, exec
	s_cselect_b32 s0, 0x1b100000, s20
	v_readlane_b32 s22, v254, 56
	v_add_f32_e32 v169, 1.0, v169
	v_rcp_f32_e32 v186, v169
	v_mul_f32_e32 v169, 0xbfb8aa3b, v185
	v_exp_f32_e32 v169, v169
	v_readlane_b32 s23, v254, 57
	s_add_u32 s0, s22, s0
	s_addc_u32 s1, s23, 0
	v_add_f32_e32 v169, 1.0, v169
	v_rcp_f32_e32 v187, v169
	s_lshl_b32 s11, s11, 3
	v_and_or_b32 v162, v162, 7, s11
	v_ashrrev_i32_e32 v163, 31, v162
	v_pk_mul_f32 v[204:205], v[184:185], v[186:187]
	v_pk_mul_f32 v[184:185], v[134:135], v[198:199]
	s_ashr_i32 s11, s10, 31
	v_pk_fma_f32 v[180:181], v[130:131], v[180:181], v[184:185]
	v_lshlrev_b64 v[162:163], 21, v[162:163]
	v_pk_fma_f32 v[180:181], v[138:139], v[166:167], v[180:181]
	v_lshl_add_u64 v[162:163], s[0:1], 0, v[162:163]
	v_pk_fma_f32 v[180:181], v[142:143], v[178:179], v[180:181]
	s_lshl_b64 s[0:1], s[10:11], 8
	v_mul_f32_e32 v169, 0xbfb8aa3b, v180
	v_exp_f32_e32 v169, v169
	v_lshl_add_u64 v[162:163], v[162:163], 0, s[0:1]
	v_lshl_add_u64 v[162:163], v[162:163], 0, v[96:97]
	s_andn2_b64 vcc, exec, s[8:9]
	v_add_f32_e32 v169, 1.0, v169
	v_rcp_f32_e32 v184, v169
	v_mul_f32_e32 v169, 0xbfb8aa3b, v181
	v_exp_f32_e32 v169, v169
	s_movk_i32 s23, 0x400
	global_store_dwordx4 v[162:163], v[220:223], off
	v_add_f32_e32 v169, 1.0, v169
	v_rcp_f32_e32 v185, v169
	s_nop 0
	v_pk_mul_f32 v[180:181], v[180:181], v[184:185]
	v_pk_mul_f32 v[184:185], v[136:137], v[176:177]
	s_nop 0
	v_pk_fma_f32 v[170:171], v[132:133], v[170:171], v[184:185]
	s_nop 0
	v_pk_fma_f32 v[170:171], v[140:141], v[164:165], v[170:171]
	s_nop 0
	v_pk_fma_f32 v[170:171], v[144:145], v[172:173], v[170:171]
	s_nop 0
	v_mul_f32_e32 v169, 0xbfb8aa3b, v170
	v_exp_f32_e32 v169, v169
	s_nop 0
	v_add_f32_e32 v169, 1.0, v169
	v_rcp_f32_e32 v184, v169
	v_mul_f32_e32 v169, 0xbfb8aa3b, v171
	v_exp_f32_e32 v169, v169
	s_nop 0
	v_add_f32_e32 v169, 1.0, v169
	v_rcp_f32_e32 v185, v169
	v_cndmask_b32_e64 v169, 0, 1, s[8:9]
	v_cmp_ne_u32_e64 s[38:39], 1, v169
	v_pk_mul_f32 v[170:171], v[170:171], v[184:185]
	s_cbranch_vccnz .LBB0_509
	v_pk_mul_f32 v[168:169], v[206:207], v[206:207]
	v_pk_mul_f32 v[184:185], v[204:205], v[204:205]
	v_add_f32_e32 v168, v168, v169
	v_add_f32_e32 v168, v184, v168
	v_pk_mul_f32 v[186:187], v[180:181], v[180:181]
	v_add_f32_e32 v168, v185, v168
	v_and_b32_e32 v184, 64, v232
	v_add_f32_e32 v168, v186, v168
	v_xor_b32_e32 v169, 1, v232
	v_add_u32_e32 v184, 64, v184
	v_pk_mul_f32 v[212:213], v[170:171], v[170:171]
	v_add_f32_e32 v168, v187, v168
	v_cmp_lt_i32_e32 vcc, v169, v184
	v_add_f32_e32 v168, v212, v168
	v_add_f32_e32 v168, v213, v168
	v_cndmask_b32_e32 v169, v232, v169, vcc
	v_lshlrev_b32_e32 v169, 2, v169
	s_nop 1
	v_mov_b32_dpp v169, v168 quad_perm:[1,0,3,2] row_mask:0xf bank_mask:0xf
	s_waitcnt lgkmcnt(0)
	v_add_f32_e32 v168, v168, v169
	v_xor_b32_e32 v169, 2, v232
	v_cmp_lt_i32_e32 vcc, v169, v184
	s_nop 1
	v_cndmask_b32_e32 v169, v232, v169, vcc
	v_lshlrev_b32_e32 v169, 2, v169
	s_nop 1
	v_mov_b32_dpp v169, v168 quad_perm:[2,3,0,1] row_mask:0xf bank_mask:0xf
	s_waitcnt lgkmcnt(0)
	v_add_f32_e32 v168, v168, v169
	v_xor_b32_e32 v169, 4, v232
	v_cmp_lt_i32_e32 vcc, v169, v184
	s_nop 1
	v_cndmask_b32_e32 v169, v232, v169, vcc
	v_lshlrev_b32_e32 v169, 2, v169
	s_nop 1
	v_mov_b32_dpp v169, v168 row_half_mirror row_mask:0xf bank_mask:0xf
	s_waitcnt lgkmcnt(0)
	v_add_f32_e32 v168, v168, v169
	v_xor_b32_e32 v169, 8, v232
	v_cmp_lt_i32_e32 vcc, v169, v184
	s_nop 1
	v_cndmask_b32_e32 v169, v232, v169, vcc
	v_lshlrev_b32_e32 v169, 2, v169
	s_nop 1
	v_mov_b32_dpp v169, v168 row_mirror row_mask:0xf bank_mask:0xf
	s_waitcnt lgkmcnt(0)
	v_add_f32_e32 v168, v168, v169
	v_add_f32_e32 v168, 0x358637bd, v168
	v_rsq_f32_e32 v168, v168
	s_nop 0
	v_mul_f32_e32 v168, v219, v168
.LBB0_509:
	v_pk_mul_f32 v[184:185], v[206:207], v[168:169] op_sel_hi:[1,0]
	v_pk_mul_f32 v[180:181], v[180:181], v[168:169] op_sel_hi:[1,0]
	v_cvt_pk_bf16_f32 v212, v184, v185
	v_pk_mul_f32 v[184:185], v[204:205], v[168:169] op_sel_hi:[1,0]
	v_pk_mul_f32 v[168:169], v[170:171], v[168:169] op_sel_hi:[1,0]
	v_lshlrev_b32_e32 v206, 16, v8
	v_cvt_pk_bf16_f32 v215, v168, v169
	v_pk_mul_f32 v[168:169], v[146:147], v[208:209]
	v_and_b32_e32 v207, 0xffff0000, v8
	v_pk_fma_f32 v[168:169], v[150:151], v[196:197], v[168:169]
	v_cvt_pk_bf16_f32 v213, v184, v185
	v_pk_fma_f32 v[168:169], v[154:155], v[210:211], v[168:169]
	v_and_b32_e32 v205, 0xffff0000, v9
	v_pk_fma_f32 v[168:169], v[158:159], v[206:207], v[168:169]
	v_lshlrev_b32_e32 v204, 16, v9
	v_mul_f32_e32 v184, 0xbfb8aa3b, v168
	v_mul_f32_e32 v185, 0xbfb8aa3b, v169
	v_exp_f32_e32 v184, v184
	v_exp_f32_e32 v185, v185
	v_cvt_pk_bf16_f32 v214, v180, v181
	v_and_b32_e32 v181, 0xffff0000, v10
	v_add_f32_e32 v184, 1.0, v184
	v_add_f32_e32 v185, 1.0, v185
	v_rcp_f32_e32 v184, v184
	v_rcp_f32_e32 v185, v185
	v_lshlrev_b32_e32 v180, 16, v10
	v_pk_mul_f32 v[176:177], v[132:133], v[176:177]
	v_and_b32_e32 v171, 0xffff0000, v11
	v_pk_mul_f32 v[168:169], v[168:169], v[184:185]
	v_pk_mul_f32 v[184:185], v[148:149], v[200:201]
	v_pk_fma_f32 v[176:177], v[136:137], v[164:165], v[176:177]
	v_pk_fma_f32 v[184:185], v[152:153], v[174:175], v[184:185]
	v_lshlrev_b32_e32 v170, 16, v11
	v_pk_fma_f32 v[184:185], v[156:157], v[202:203], v[184:185]
	v_pk_fma_f32 v[176:177], v[140:141], v[172:173], v[176:177]
	v_pk_fma_f32 v[184:185], v[160:161], v[204:205], v[184:185]
	v_pk_fma_f32 v[176:177], v[144:145], v[170:171], v[176:177]
	v_mul_f32_e32 v186, 0xbfb8aa3b, v184
	v_mul_f32_e32 v187, 0xbfb8aa3b, v185
	v_exp_f32_e32 v186, v186
	v_exp_f32_e32 v187, v187
	global_store_dwordx4 v[162:163], v[212:215], off offset:256
	v_mov_b32_e32 v208, 1.0
	v_add_f32_e32 v186, 1.0, v186
	v_add_f32_e32 v187, 1.0, v187
	v_rcp_f32_e32 v186, v186
	v_rcp_f32_e32 v187, v187
	s_and_b64 vcc, exec, s[38:39]
	v_mov_b32_e32 v212, 1.0
	s_movk_i32 s1, 0x3000
	v_pk_mul_f32 v[200:201], v[184:185], v[186:187]
	v_pk_mul_f32 v[184:185], v[130:131], v[198:199]
	s_nop 0
	v_pk_fma_f32 v[184:185], v[134:135], v[166:167], v[184:185]
	s_nop 0
	v_pk_fma_f32 v[184:185], v[138:139], v[178:179], v[184:185]
	s_nop 0
	v_pk_fma_f32 v[184:185], v[142:143], v[180:181], v[184:185]
	s_nop 0
	v_mul_f32_e32 v186, 0xbfb8aa3b, v184
	v_mul_f32_e32 v187, 0xbfb8aa3b, v185
	v_exp_f32_e32 v186, v186
	v_exp_f32_e32 v187, v187
	v_add_f32_e32 v186, 1.0, v186
	v_add_f32_e32 v187, 1.0, v187
	v_rcp_f32_e32 v186, v186
	v_rcp_f32_e32 v187, v187
	s_nop 0
	v_pk_mul_f32 v[198:199], v[184:185], v[186:187]
	v_mul_f32_e32 v184, 0xbfb8aa3b, v176
	v_mul_f32_e32 v185, 0xbfb8aa3b, v177
	v_exp_f32_e32 v184, v184
	v_exp_f32_e32 v185, v185
	v_add_f32_e32 v184, 1.0, v184
	v_add_f32_e32 v185, 1.0, v185
	v_rcp_f32_e32 v184, v184
	v_rcp_f32_e32 v185, v185
	s_nop 0
	v_pk_mul_f32 v[176:177], v[176:177], v[184:185]
	s_cbranch_vccnz .LBB0_511
	v_pk_mul_f32 v[184:185], v[168:169], v[168:169]
	v_pk_mul_f32 v[186:187], v[200:201], v[200:201]
	v_add_f32_e32 v184, v184, v185
	v_add_f32_e32 v184, v186, v184
	v_pk_mul_f32 v[212:213], v[198:199], v[198:199]
	v_add_f32_e32 v184, v187, v184
	v_and_b32_e32 v186, 64, v232
	v_add_f32_e32 v184, v212, v184
	v_xor_b32_e32 v185, 1, v232
	v_add_u32_e32 v186, 64, v186
	v_pk_mul_f32 v[214:215], v[176:177], v[176:177]
	v_add_f32_e32 v184, v213, v184
	v_cmp_lt_i32_e32 vcc, v185, v186
	v_add_f32_e32 v184, v214, v184
	v_add_f32_e32 v184, v215, v184
	v_cndmask_b32_e32 v185, v232, v185, vcc
	v_lshlrev_b32_e32 v185, 2, v185
	s_nop 1
	v_mov_b32_dpp v185, v184 quad_perm:[1,0,3,2] row_mask:0xf bank_mask:0xf
	s_waitcnt lgkmcnt(0)
	v_add_f32_e32 v184, v184, v185
	v_xor_b32_e32 v185, 2, v232
	v_cmp_lt_i32_e32 vcc, v185, v186
	s_nop 1
	v_cndmask_b32_e32 v185, v232, v185, vcc
	v_lshlrev_b32_e32 v185, 2, v185
	s_nop 1
	v_mov_b32_dpp v185, v184 quad_perm:[2,3,0,1] row_mask:0xf bank_mask:0xf
	s_waitcnt lgkmcnt(0)
	v_add_f32_e32 v184, v184, v185
	v_xor_b32_e32 v185, 4, v232
	v_cmp_lt_i32_e32 vcc, v185, v186
	s_nop 1
	v_cndmask_b32_e32 v185, v232, v185, vcc
	v_lshlrev_b32_e32 v185, 2, v185
	s_nop 1
	v_mov_b32_dpp v185, v184 row_half_mirror row_mask:0xf bank_mask:0xf
	s_waitcnt lgkmcnt(0)
	v_add_f32_e32 v184, v184, v185
	v_xor_b32_e32 v185, 8, v232
	v_cmp_lt_i32_e32 vcc, v185, v186
	s_nop 1
	v_cndmask_b32_e32 v185, v232, v185, vcc
	v_lshlrev_b32_e32 v185, 2, v185
	s_nop 1
	v_mov_b32_dpp v185, v184 row_mirror row_mask:0xf bank_mask:0xf
	s_waitcnt lgkmcnt(0)
	v_add_f32_e32 v184, v184, v185
	v_add_f32_e32 v184, 0x358637bd, v184
	v_rsq_f32_e32 v184, v184
	s_nop 0
	v_mul_f32_e32 v212, v219, v184
.LBB0_511:
	v_pk_mul_f32 v[168:169], v[168:169], v[212:213] op_sel_hi:[1,0]
	v_pk_mul_f32 v[184:185], v[150:151], v[210:211]
	v_cvt_pk_bf16_f32 v214, v168, v169
	v_pk_mul_f32 v[168:169], v[200:201], v[212:213] op_sel_hi:[1,0]
	v_pk_fma_f32 v[184:185], v[146:147], v[196:197], v[184:185]
	v_cvt_pk_bf16_f32 v215, v168, v169
	v_pk_mul_f32 v[168:169], v[198:199], v[212:213] op_sel_hi:[1,0]
	v_pk_fma_f32 v[184:185], v[154:155], v[206:207], v[184:185]
	v_cvt_pk_bf16_f32 v216, v168, v169
	v_pk_mul_f32 v[168:169], v[176:177], v[212:213] op_sel_hi:[1,0]
	v_and_b32_e32 v201, 0xffff0000, v13
	v_cvt_pk_bf16_f32 v217, v168, v169
	global_store_dwordx4 v[162:163], v[214:217], off offset:512
	v_lshlrev_b32_e32 v200, 16, v13
	v_and_b32_e32 v177, 0xffff0000, v14
	v_lshlrev_b32_e32 v214, 16, v12
	v_and_b32_e32 v215, 0xffff0000, v12
	v_pk_fma_f32 v[184:185], v[158:159], v[214:215], v[184:185]
	v_lshlrev_b32_e32 v176, 16, v14
	v_mul_f32_e32 v186, 0xbfb8aa3b, v184
	v_mul_f32_e32 v187, 0xbfb8aa3b, v185
	v_exp_f32_e32 v186, v186
	v_exp_f32_e32 v187, v187
	v_and_b32_e32 v169, 0xffff0000, v15
	v_lshlrev_b32_e32 v168, 16, v15
	v_add_f32_e32 v186, 1.0, v186
	v_add_f32_e32 v187, 1.0, v187
	v_rcp_f32_e32 v186, v186
	v_rcp_f32_e32 v187, v187
	s_and_b64 vcc, exec, s[38:39]
	v_pk_mul_f32 v[196:197], v[184:185], v[186:187]
	v_pk_mul_f32 v[184:185], v[152:153], v[202:203]
	s_nop 0
	v_pk_fma_f32 v[174:175], v[148:149], v[174:175], v[184:185]
	s_nop 0
	v_pk_fma_f32 v[174:175], v[156:157], v[204:205], v[174:175]
	s_nop 0
	v_pk_fma_f32 v[174:175], v[160:161], v[200:201], v[174:175]
	s_nop 0
	v_mul_f32_e32 v184, 0xbfb8aa3b, v174
	v_mul_f32_e32 v185, 0xbfb8aa3b, v175
	v_exp_f32_e32 v184, v184
	v_exp_f32_e32 v185, v185
	v_add_f32_e32 v184, 1.0, v184
	v_add_f32_e32 v185, 1.0, v185
	v_rcp_f32_e32 v184, v184
	v_rcp_f32_e32 v185, v185
	s_nop 0
	v_pk_mul_f32 v[174:175], v[174:175], v[184:185]
	v_pk_mul_f32 v[184:185], v[134:135], v[178:179]
	s_nop 0
	v_pk_fma_f32 v[166:167], v[130:131], v[166:167], v[184:185]
	s_nop 0
	v_pk_fma_f32 v[166:167], v[138:139], v[180:181], v[166:167]
	s_nop 0
	v_pk_fma_f32 v[166:167], v[142:143], v[176:177], v[166:167]
	s_nop 0
	v_mul_f32_e32 v184, 0xbfb8aa3b, v166
	v_mul_f32_e32 v185, 0xbfb8aa3b, v167
	v_exp_f32_e32 v184, v184
	v_exp_f32_e32 v185, v185
	v_add_f32_e32 v184, 1.0, v184
	v_add_f32_e32 v185, 1.0, v185
	v_rcp_f32_e32 v184, v184
	v_rcp_f32_e32 v185, v185
	s_nop 0
	v_pk_mul_f32 v[166:167], v[166:167], v[184:185]
	v_pk_mul_f32 v[184:185], v[136:137], v[172:173]
	s_nop 0
	v_pk_fma_f32 v[164:165], v[132:133], v[164:165], v[184:185]
	s_nop 0
	v_pk_fma_f32 v[164:165], v[140:141], v[170:171], v[164:165]
	s_nop 0
	v_pk_fma_f32 v[164:165], v[144:145], v[168:169], v[164:165]
	s_nop 0
	v_mul_f32_e32 v184, 0xbfb8aa3b, v164
	v_mul_f32_e32 v185, 0xbfb8aa3b, v165
	v_exp_f32_e32 v184, v184
	v_exp_f32_e32 v185, v185
	v_add_f32_e32 v184, 1.0, v184
	v_add_f32_e32 v185, 1.0, v185
	v_rcp_f32_e32 v184, v184
	v_rcp_f32_e32 v185, v185
	s_nop 0
	v_pk_mul_f32 v[164:165], v[164:165], v[184:185]
	s_cbranch_vccnz .LBB0_513
	v_pk_mul_f32 v[184:185], v[196:197], v[196:197]
	v_pk_mul_f32 v[186:187], v[174:175], v[174:175]
	v_add_f32_e32 v184, v184, v185
	v_add_f32_e32 v184, v186, v184
	v_pk_mul_f32 v[198:199], v[166:167], v[166:167]
	v_add_f32_e32 v184, v187, v184
	v_and_b32_e32 v186, 64, v232
	v_add_f32_e32 v184, v198, v184
	v_xor_b32_e32 v185, 1, v232
	v_add_u32_e32 v186, 64, v186
	v_pk_mul_f32 v[208:209], v[164:165], v[164:165]
	v_add_f32_e32 v184, v199, v184
	v_cmp_lt_i32_e32 vcc, v185, v186
	v_add_f32_e32 v184, v208, v184
	v_add_f32_e32 v184, v209, v184
	v_cndmask_b32_e32 v185, v232, v185, vcc
	v_lshlrev_b32_e32 v185, 2, v185
	s_nop 1
	v_mov_b32_dpp v185, v184 quad_perm:[1,0,3,2] row_mask:0xf bank_mask:0xf
	s_waitcnt lgkmcnt(0)
	v_add_f32_e32 v184, v184, v185
	v_xor_b32_e32 v185, 2, v232
	v_cmp_lt_i32_e32 vcc, v185, v186
	s_nop 1
	v_cndmask_b32_e32 v185, v232, v185, vcc
	v_lshlrev_b32_e32 v185, 2, v185
	s_nop 1
	v_mov_b32_dpp v185, v184 quad_perm:[2,3,0,1] row_mask:0xf bank_mask:0xf
	s_waitcnt lgkmcnt(0)
	v_add_f32_e32 v184, v184, v185
	v_xor_b32_e32 v185, 4, v232
	v_cmp_lt_i32_e32 vcc, v185, v186
	s_nop 1
	v_cndmask_b32_e32 v185, v232, v185, vcc
	v_lshlrev_b32_e32 v185, 2, v185
	s_nop 1
	v_mov_b32_dpp v185, v184 row_half_mirror row_mask:0xf bank_mask:0xf
	s_waitcnt lgkmcnt(0)
	v_add_f32_e32 v184, v184, v185
	v_xor_b32_e32 v185, 8, v232
	v_cmp_lt_i32_e32 vcc, v185, v186
	s_nop 1
	v_cndmask_b32_e32 v185, v232, v185, vcc
	v_lshlrev_b32_e32 v185, 2, v185
	s_nop 1
	v_mov_b32_dpp v185, v184 row_mirror row_mask:0xf bank_mask:0xf
	s_waitcnt lgkmcnt(0)
	v_add_f32_e32 v184, v184, v185
	v_add_f32_e32 v184, 0x358637bd, v184
	v_rsq_f32_e32 v184, v184
	s_nop 0
	v_mul_f32_e32 v208, v219, v184
.LBB0_513:
	v_pk_mul_f32 v[164:165], v[164:165], v[208:209] op_sel_hi:[1,0]
	v_pk_mul_f32 v[166:167], v[166:167], v[208:209] op_sel_hi:[1,0]
	v_cvt_pk_bf16_f32 v199, v164, v165
	v_pk_mul_f32 v[164:165], v[150:151], v[206:207]
	v_lshlrev_b32_e32 v212, 16, v16
	v_pk_fma_f32 v[164:165], v[146:147], v[210:211], v[164:165]
	v_and_b32_e32 v213, 0xffff0000, v16
	v_pk_fma_f32 v[164:165], v[154:155], v[214:215], v[164:165]
	v_cvt_pk_bf16_f32 v198, v166, v167
	v_pk_fma_f32 v[166:167], v[158:159], v[212:213], v[164:165]
	v_pk_mul_f32 v[184:185], v[196:197], v[208:209] op_sel_hi:[1,0]
	v_mul_f32_e32 v164, 0xbfb8aa3b, v166
	v_exp_f32_e32 v165, v164
	v_cvt_pk_bf16_f32 v196, v184, v185
	v_pk_mul_f32 v[174:175], v[174:175], v[208:209] op_sel_hi:[1,0]
	v_and_b32_e32 v209, 0xffff0000, v17
	v_add_f32_e32 v165, 1.0, v165
	v_rcp_f32_e32 v184, v165
	v_mul_f32_e32 v165, 0xbfb8aa3b, v167
	v_exp_f32_e32 v165, v165
	v_lshlrev_b32_e32 v208, 16, v17
	v_cvt_pk_bf16_f32 v197, v174, v175
	global_store_dwordx4 v[162:163], v[196:199], off offset:768
	v_add_f32_e32 v165, 1.0, v165
	v_rcp_f32_e32 v185, v165
	v_and_b32_e32 v199, 0xffff0000, v18
	v_lshlrev_b32_e32 v198, 16, v18
	v_and_b32_e32 v175, 0xffff0000, v19
	v_pk_mul_f32 v[166:167], v[166:167], v[184:185]
	v_pk_mul_f32 v[184:185], v[152:153], v[204:205]
	v_lshlrev_b32_e32 v174, 16, v19
	v_pk_fma_f32 v[184:185], v[148:149], v[202:203], v[184:185]
	v_mov_b32_e32 v164, 1.0
	v_pk_fma_f32 v[184:185], v[156:157], v[200:201], v[184:185]
	s_and_b64 vcc, exec, s[38:39]
	v_pk_fma_f32 v[184:185], v[160:161], v[208:209], v[184:185]
	v_mov_b32_e32 v202, 1.0
	v_mul_f32_e32 v165, 0xbfb8aa3b, v184
	v_exp_f32_e32 v165, v165
	s_nop 0
	v_add_f32_e32 v165, 1.0, v165
	v_rcp_f32_e32 v186, v165
	v_mul_f32_e32 v165, 0xbfb8aa3b, v185
	v_exp_f32_e32 v165, v165
	s_nop 0
	v_add_f32_e32 v165, 1.0, v165
	v_rcp_f32_e32 v187, v165
	s_nop 0
	v_pk_mul_f32 v[196:197], v[184:185], v[186:187]
	v_pk_mul_f32 v[184:185], v[134:135], v[180:181]
	s_nop 0
	v_pk_fma_f32 v[178:179], v[130:131], v[178:179], v[184:185]
	s_nop 0
	v_pk_fma_f32 v[178:179], v[138:139], v[176:177], v[178:179]
	s_nop 0
	v_pk_fma_f32 v[178:179], v[142:143], v[198:199], v[178:179]
	s_nop 0
	v_mul_f32_e32 v165, 0xbfb8aa3b, v178
	v_exp_f32_e32 v165, v165
	s_nop 0
	v_add_f32_e32 v165, 1.0, v165
	v_rcp_f32_e32 v184, v165
	v_mul_f32_e32 v165, 0xbfb8aa3b, v179
	v_exp_f32_e32 v165, v165
	s_nop 0
	v_add_f32_e32 v165, 1.0, v165
	v_rcp_f32_e32 v185, v165
	s_nop 0
	v_pk_mul_f32 v[178:179], v[178:179], v[184:185]
	v_pk_mul_f32 v[184:185], v[136:137], v[170:171]
	s_nop 0
	v_pk_fma_f32 v[172:173], v[132:133], v[172:173], v[184:185]
	s_nop 0
	v_pk_fma_f32 v[172:173], v[140:141], v[168:169], v[172:173]
	s_nop 0
	v_pk_fma_f32 v[172:173], v[144:145], v[174:175], v[172:173]
	s_nop 0
	v_mul_f32_e32 v165, 0xbfb8aa3b, v172
	v_exp_f32_e32 v165, v165
	s_nop 0
	v_add_f32_e32 v165, 1.0, v165
	v_rcp_f32_e32 v184, v165
	v_mul_f32_e32 v165, 0xbfb8aa3b, v173
	v_exp_f32_e32 v165, v165
	s_nop 0
	v_add_f32_e32 v165, 1.0, v165
	v_rcp_f32_e32 v185, v165
	s_nop 0
	v_pk_mul_f32 v[172:173], v[172:173], v[184:185]
	s_cbranch_vccnz .LBB0_515
	v_pk_mul_f32 v[184:185], v[166:167], v[166:167]
	v_pk_mul_f32 v[186:187], v[196:197], v[196:197]
	v_add_f32_e32 v165, v184, v185
	v_add_f32_e32 v165, v186, v165
	v_pk_mul_f32 v[202:203], v[178:179], v[178:179]
	v_add_f32_e32 v165, v187, v165
	v_and_b32_e32 v185, 64, v232
	v_add_f32_e32 v165, v202, v165
	v_xor_b32_e32 v184, 1, v232
	v_add_u32_e32 v185, 64, v185
	v_pk_mul_f32 v[210:211], v[172:173], v[172:173]
	v_add_f32_e32 v165, v203, v165
	v_cmp_lt_i32_e32 vcc, v184, v185
	v_add_f32_e32 v165, v210, v165
	v_add_f32_e32 v165, v211, v165
	v_cndmask_b32_e32 v184, v232, v184, vcc
	v_lshlrev_b32_e32 v184, 2, v184
	s_nop 1
	v_mov_b32_dpp v184, v165 quad_perm:[1,0,3,2] row_mask:0xf bank_mask:0xf
	s_waitcnt lgkmcnt(0)
	v_add_f32_e32 v165, v165, v184
	v_xor_b32_e32 v184, 2, v232
	v_cmp_lt_i32_e32 vcc, v184, v185
	s_nop 1
	v_cndmask_b32_e32 v184, v232, v184, vcc
	v_lshlrev_b32_e32 v184, 2, v184
	s_nop 1
	v_mov_b32_dpp v184, v165 quad_perm:[2,3,0,1] row_mask:0xf bank_mask:0xf
	s_waitcnt lgkmcnt(0)
	v_add_f32_e32 v165, v165, v184
	v_xor_b32_e32 v184, 4, v232
	v_cmp_lt_i32_e32 vcc, v184, v185
	s_nop 1
	v_cndmask_b32_e32 v184, v232, v184, vcc
	v_lshlrev_b32_e32 v184, 2, v184
	s_nop 1
	v_mov_b32_dpp v184, v165 row_half_mirror row_mask:0xf bank_mask:0xf
	s_waitcnt lgkmcnt(0)
	v_add_f32_e32 v165, v165, v184
	v_xor_b32_e32 v184, 8, v232
	v_cmp_lt_i32_e32 vcc, v184, v185
	s_nop 1
	v_cndmask_b32_e32 v184, v232, v184, vcc
	v_lshlrev_b32_e32 v184, 2, v184
	s_nop 1
	v_mov_b32_dpp v184, v165 row_mirror row_mask:0xf bank_mask:0xf
	s_waitcnt lgkmcnt(0)
	v_add_f32_e32 v165, v165, v184
	v_add_f32_e32 v165, 0x358637bd, v165
	v_rsq_f32_e32 v165, v165
	s_nop 0
	v_mul_f32_e32 v202, v219, v165
.LBB0_515:
	v_pk_mul_f32 v[166:167], v[166:167], v[202:203] op_sel_hi:[1,0]
	v_lshlrev_b32_e32 v216, 16, v20
	v_cvt_pk_bf16_f32 v220, v166, v167
	v_pk_mul_f32 v[166:167], v[196:197], v[202:203] op_sel_hi:[1,0]
	v_and_b32_e32 v217, 0xffff0000, v20
	v_cvt_pk_bf16_f32 v221, v166, v167
	v_pk_mul_f32 v[166:167], v[178:179], v[202:203] op_sel_hi:[1,0]
	v_and_b32_e32 v179, 0xffff0000, v22
	v_cvt_pk_bf16_f32 v222, v166, v167
	v_pk_mul_f32 v[166:167], v[172:173], v[202:203] op_sel_hi:[1,0]
	v_pk_mul_f32 v[172:173], v[150:151], v[214:215]
	v_and_b32_e32 v203, 0xffff0000, v21
	v_pk_fma_f32 v[172:173], v[146:147], v[206:207], v[172:173]
	v_lshlrev_b32_e32 v202, 16, v21
	v_pk_fma_f32 v[172:173], v[154:155], v[212:213], v[172:173]
	v_lshlrev_b32_e32 v178, 16, v22
	v_pk_fma_f32 v[172:173], v[158:159], v[216:217], v[172:173]
	v_cvt_pk_bf16_f32 v223, v166, v167
	v_mul_f32_e32 v165, 0xbfb8aa3b, v172
	v_exp_f32_e32 v165, v165
	v_and_b32_e32 v167, 0xffff0000, v23
	v_lshlrev_b32_e32 v166, 16, v23
	s_and_b64 vcc, exec, s[38:39]
	v_add_f32_e32 v165, 1.0, v165
	v_rcp_f32_e32 v184, v165
	v_mul_f32_e32 v165, 0xbfb8aa3b, v173
	v_exp_f32_e32 v165, v165
	global_store_dwordx4 v[162:163], v[220:223], off offset:1024
	v_add_f32_e32 v165, 1.0, v165
	v_rcp_f32_e32 v185, v165
	s_nop 0
	v_pk_mul_f32 v[172:173], v[172:173], v[184:185]
	v_pk_mul_f32 v[184:185], v[152:153], v[200:201]
	s_nop 0
	v_pk_fma_f32 v[184:185], v[148:149], v[204:205], v[184:185]
	s_nop 0
	v_pk_fma_f32 v[184:185], v[156:157], v[208:209], v[184:185]
	s_nop 0
	v_pk_fma_f32 v[184:185], v[160:161], v[202:203], v[184:185]
	s_nop 0
	v_mul_f32_e32 v165, 0xbfb8aa3b, v184
	v_exp_f32_e32 v165, v165
	s_nop 0
	v_add_f32_e32 v165, 1.0, v165
	v_rcp_f32_e32 v186, v165
	v_mul_f32_e32 v165, 0xbfb8aa3b, v185
	v_exp_f32_e32 v165, v165
	s_nop 0
	v_add_f32_e32 v165, 1.0, v165
	v_rcp_f32_e32 v187, v165
	s_nop 0
	v_pk_mul_f32 v[196:197], v[184:185], v[186:187]
	v_pk_mul_f32 v[184:185], v[134:135], v[176:177]
	s_nop 0
	v_pk_fma_f32 v[180:181], v[130:131], v[180:181], v[184:185]
	s_nop 0
	v_pk_fma_f32 v[180:181], v[138:139], v[198:199], v[180:181]
	s_nop 0
	v_pk_fma_f32 v[180:181], v[142:143], v[178:179], v[180:181]
	s_nop 0
	v_mul_f32_e32 v165, 0xbfb8aa3b, v180
	v_exp_f32_e32 v165, v165
	s_nop 0
	v_add_f32_e32 v165, 1.0, v165
	v_rcp_f32_e32 v184, v165
	v_mul_f32_e32 v165, 0xbfb8aa3b, v181
	v_exp_f32_e32 v165, v165
	s_nop 0
	v_add_f32_e32 v165, 1.0, v165
	v_rcp_f32_e32 v185, v165
	s_nop 0
	v_pk_mul_f32 v[180:181], v[180:181], v[184:185]
	v_pk_mul_f32 v[184:185], v[136:137], v[168:169]
	s_nop 0
	v_pk_fma_f32 v[170:171], v[132:133], v[170:171], v[184:185]
	s_nop 0
	v_pk_fma_f32 v[170:171], v[140:141], v[174:175], v[170:171]
	s_nop 0
	v_pk_fma_f32 v[170:171], v[144:145], v[166:167], v[170:171]
	s_nop 0
	v_mul_f32_e32 v165, 0xbfb8aa3b, v170
	v_exp_f32_e32 v165, v165
	s_nop 0
	v_add_f32_e32 v165, 1.0, v165
	v_rcp_f32_e32 v184, v165
	v_mul_f32_e32 v165, 0xbfb8aa3b, v171
	v_exp_f32_e32 v165, v165
	s_nop 0
	v_add_f32_e32 v165, 1.0, v165
	v_rcp_f32_e32 v185, v165
	s_nop 0
	v_pk_mul_f32 v[170:171], v[170:171], v[184:185]
	s_cbranch_vccnz .LBB0_517
	v_pk_mul_f32 v[164:165], v[172:173], v[172:173]
	v_pk_mul_f32 v[184:185], v[196:197], v[196:197]
	v_add_f32_e32 v164, v164, v165
	v_add_f32_e32 v164, v184, v164
	v_pk_mul_f32 v[186:187], v[180:181], v[180:181]
	v_add_f32_e32 v164, v185, v164
	v_and_b32_e32 v184, 64, v232
	v_add_f32_e32 v164, v186, v164
	v_xor_b32_e32 v165, 1, v232
	v_add_u32_e32 v184, 64, v184
	v_pk_mul_f32 v[204:205], v[170:171], v[170:171]
	v_add_f32_e32 v164, v187, v164
	v_cmp_lt_i32_e32 vcc, v165, v184
	v_add_f32_e32 v164, v204, v164
	v_add_f32_e32 v164, v205, v164
	v_cndmask_b32_e32 v165, v232, v165, vcc
	v_lshlrev_b32_e32 v165, 2, v165
	s_nop 1
	v_mov_b32_dpp v165, v164 quad_perm:[1,0,3,2] row_mask:0xf bank_mask:0xf
	s_waitcnt lgkmcnt(0)
	v_add_f32_e32 v164, v164, v165
	v_xor_b32_e32 v165, 2, v232
	v_cmp_lt_i32_e32 vcc, v165, v184
	s_nop 1
	v_cndmask_b32_e32 v165, v232, v165, vcc
	v_lshlrev_b32_e32 v165, 2, v165
	s_nop 1
	v_mov_b32_dpp v165, v164 quad_perm:[2,3,0,1] row_mask:0xf bank_mask:0xf
	s_waitcnt lgkmcnt(0)
	v_add_f32_e32 v164, v164, v165
	v_xor_b32_e32 v165, 4, v232
	v_cmp_lt_i32_e32 vcc, v165, v184
	s_nop 1
	v_cndmask_b32_e32 v165, v232, v165, vcc
	v_lshlrev_b32_e32 v165, 2, v165
	s_nop 1
	v_mov_b32_dpp v165, v164 row_half_mirror row_mask:0xf bank_mask:0xf
	s_waitcnt lgkmcnt(0)
	v_add_f32_e32 v164, v164, v165
	v_xor_b32_e32 v165, 8, v232
	v_cmp_lt_i32_e32 vcc, v165, v184
	s_nop 1
	v_cndmask_b32_e32 v165, v232, v165, vcc
	v_lshlrev_b32_e32 v165, 2, v165
	s_nop 1
	v_mov_b32_dpp v165, v164 row_mirror row_mask:0xf bank_mask:0xf
	s_waitcnt lgkmcnt(0)
	v_add_f32_e32 v164, v164, v165
	v_add_f32_e32 v164, 0x358637bd, v164
	v_rsq_f32_e32 v164, v164
	s_nop 0
	v_mul_f32_e32 v164, v219, v164
.LBB0_517:
	v_pk_mul_f32 v[172:173], v[172:173], v[164:165] op_sel_hi:[1,0]
	v_lshlrev_b32_e32 v210, 16, v24
	v_cvt_pk_bf16_f32 v204, v172, v173
	v_pk_mul_f32 v[172:173], v[196:197], v[164:165] op_sel_hi:[1,0]
	v_and_b32_e32 v211, 0xffff0000, v24
	v_cvt_pk_bf16_f32 v205, v172, v173
	v_pk_mul_f32 v[172:173], v[180:181], v[164:165] op_sel_hi:[1,0]
	v_pk_mul_f32 v[164:165], v[170:171], v[164:165] op_sel_hi:[1,0]
	v_cvt_pk_bf16_f32 v206, v172, v173
	v_cvt_pk_bf16_f32 v207, v164, v165
	v_pk_mul_f32 v[164:165], v[150:151], v[212:213]
	global_store_dwordx4 v[162:163], v[204:207], off offset:1280
	v_pk_fma_f32 v[164:165], v[146:147], v[214:215], v[164:165]
	v_and_b32_e32 v197, 0xffff0000, v26
	v_pk_fma_f32 v[164:165], v[154:155], v[216:217], v[164:165]
	v_and_b32_e32 v207, 0xffff0000, v25
	v_pk_fma_f32 v[164:165], v[158:159], v[210:211], v[164:165]
	v_lshlrev_b32_e32 v206, 16, v25
	v_mul_f32_e32 v170, 0xbfb8aa3b, v164
	v_exp_f32_e32 v171, v170
	v_lshlrev_b32_e32 v196, 16, v26
	v_and_b32_e32 v173, 0xffff0000, v27
	v_lshlrev_b32_e32 v172, 16, v27
	v_add_f32_e32 v171, 1.0, v171
	v_rcp_f32_e32 v180, v171
	v_mul_f32_e32 v171, 0xbfb8aa3b, v165
	v_exp_f32_e32 v171, v171
	v_mov_b32_e32 v170, 1.0
	s_and_b64 vcc, exec, s[38:39]
	v_add_f32_e32 v171, 1.0, v171
	v_rcp_f32_e32 v181, v171
	s_nop 0
	v_pk_mul_f32 v[164:165], v[164:165], v[180:181]
	v_pk_mul_f32 v[180:181], v[152:153], v[208:209]
	s_nop 0
	v_pk_fma_f32 v[180:181], v[148:149], v[200:201], v[180:181]
	v_mov_b32_e32 v200, 1.0
	v_pk_fma_f32 v[180:181], v[156:157], v[202:203], v[180:181]
	s_nop 0
	v_pk_fma_f32 v[180:181], v[160:161], v[206:207], v[180:181]
	s_nop 0
	v_mul_f32_e32 v171, 0xbfb8aa3b, v180
	v_exp_f32_e32 v171, v171
	s_nop 0
	v_add_f32_e32 v171, 1.0, v171
	v_rcp_f32_e32 v184, v171
	v_mul_f32_e32 v171, 0xbfb8aa3b, v181
	v_exp_f32_e32 v171, v171
	s_nop 0
	v_add_f32_e32 v171, 1.0, v171
	v_rcp_f32_e32 v185, v171
	s_nop 0
	v_pk_mul_f32 v[180:181], v[180:181], v[184:185]
	v_pk_mul_f32 v[184:185], v[134:135], v[198:199]
	s_nop 0
	v_pk_fma_f32 v[176:177], v[130:131], v[176:177], v[184:185]
	s_nop 0
	v_pk_fma_f32 v[176:177], v[138:139], v[178:179], v[176:177]
	s_nop 0
	v_pk_fma_f32 v[176:177], v[142:143], v[196:197], v[176:177]
	s_nop 0
	v_mul_f32_e32 v171, 0xbfb8aa3b, v176
	v_exp_f32_e32 v171, v171
	s_nop 0
	v_add_f32_e32 v171, 1.0, v171
	v_rcp_f32_e32 v184, v171
	v_mul_f32_e32 v171, 0xbfb8aa3b, v177
	v_exp_f32_e32 v171, v171
	s_nop 0
	v_add_f32_e32 v171, 1.0, v171
	v_rcp_f32_e32 v185, v171
	s_nop 0
	v_pk_mul_f32 v[176:177], v[176:177], v[184:185]
	v_pk_mul_f32 v[184:185], v[136:137], v[174:175]
	s_nop 0
	v_pk_fma_f32 v[168:169], v[132:133], v[168:169], v[184:185]
	s_nop 0
	v_pk_fma_f32 v[168:169], v[140:141], v[166:167], v[168:169]
	s_nop 0
	v_pk_fma_f32 v[168:169], v[144:145], v[172:173], v[168:169]
	s_nop 0
	v_mul_f32_e32 v171, 0xbfb8aa3b, v168
	v_exp_f32_e32 v171, v171
	s_nop 0
	v_add_f32_e32 v171, 1.0, v171
	v_rcp_f32_e32 v184, v171
	v_mul_f32_e32 v171, 0xbfb8aa3b, v169
	v_exp_f32_e32 v171, v171
	s_nop 0
	v_add_f32_e32 v171, 1.0, v171
	v_rcp_f32_e32 v185, v171
	s_nop 0
	v_pk_mul_f32 v[168:169], v[168:169], v[184:185]
	s_cbranch_vccnz .LBB0_519
	v_pk_mul_f32 v[184:185], v[164:165], v[164:165]
	v_pk_mul_f32 v[186:187], v[180:181], v[180:181]
	v_add_f32_e32 v171, v184, v185
	v_add_f32_e32 v171, v186, v171
	v_pk_mul_f32 v[200:201], v[176:177], v[176:177]
	v_add_f32_e32 v171, v187, v171
	v_and_b32_e32 v185, 64, v232
	v_add_f32_e32 v171, v200, v171
	v_xor_b32_e32 v184, 1, v232
	v_add_u32_e32 v185, 64, v185
	v_pk_mul_f32 v[204:205], v[168:169], v[168:169]
	v_add_f32_e32 v171, v201, v171
	v_cmp_lt_i32_e32 vcc, v184, v185
	v_add_f32_e32 v171, v204, v171
	v_add_f32_e32 v171, v205, v171
	v_cndmask_b32_e32 v184, v232, v184, vcc
	v_lshlrev_b32_e32 v184, 2, v184
	s_nop 1
	v_mov_b32_dpp v184, v171 quad_perm:[1,0,3,2] row_mask:0xf bank_mask:0xf
	s_waitcnt lgkmcnt(0)
	v_add_f32_e32 v171, v171, v184
	v_xor_b32_e32 v184, 2, v232
	v_cmp_lt_i32_e32 vcc, v184, v185
	s_nop 1
	v_cndmask_b32_e32 v184, v232, v184, vcc
	v_lshlrev_b32_e32 v184, 2, v184
	s_nop 1
	v_mov_b32_dpp v184, v171 quad_perm:[2,3,0,1] row_mask:0xf bank_mask:0xf
	s_waitcnt lgkmcnt(0)
	v_add_f32_e32 v171, v171, v184
	v_xor_b32_e32 v184, 4, v232
	v_cmp_lt_i32_e32 vcc, v184, v185
	s_nop 1
	v_cndmask_b32_e32 v184, v232, v184, vcc
	v_lshlrev_b32_e32 v184, 2, v184
	s_nop 1
	v_mov_b32_dpp v184, v171 row_half_mirror row_mask:0xf bank_mask:0xf
	s_waitcnt lgkmcnt(0)
	v_add_f32_e32 v171, v171, v184
	v_xor_b32_e32 v184, 8, v232
	v_cmp_lt_i32_e32 vcc, v184, v185
	s_nop 1
	v_cndmask_b32_e32 v184, v232, v184, vcc
	v_lshlrev_b32_e32 v184, 2, v184
	s_nop 1
	v_mov_b32_dpp v184, v171 row_mirror row_mask:0xf bank_mask:0xf
	s_waitcnt lgkmcnt(0)
	v_add_f32_e32 v171, v171, v184
	v_add_f32_e32 v171, 0x358637bd, v171
	v_rsq_f32_e32 v171, v171
	s_nop 0
	v_mul_f32_e32 v200, v219, v171
.LBB0_519:
	v_pk_mul_f32 v[164:165], v[164:165], v[200:201] op_sel_hi:[1,0]
	v_lshlrev_b32_e32 v214, 16, v28
	v_cvt_pk_bf16_f32 v220, v164, v165
	v_pk_mul_f32 v[164:165], v[180:181], v[200:201] op_sel_hi:[1,0]
	v_and_b32_e32 v215, 0xffff0000, v28
	v_cvt_pk_bf16_f32 v221, v164, v165
	v_pk_mul_f32 v[164:165], v[176:177], v[200:201] op_sel_hi:[1,0]
	v_and_b32_e32 v177, 0xffff0000, v30
	v_cvt_pk_bf16_f32 v222, v164, v165
	v_pk_mul_f32 v[164:165], v[168:169], v[200:201] op_sel_hi:[1,0]
	v_pk_mul_f32 v[168:169], v[150:151], v[216:217]
	v_and_b32_e32 v201, 0xffff0000, v29
	v_pk_fma_f32 v[168:169], v[146:147], v[212:213], v[168:169]
	v_lshlrev_b32_e32 v200, 16, v29
	v_pk_fma_f32 v[168:169], v[154:155], v[210:211], v[168:169]
	v_lshlrev_b32_e32 v176, 16, v30
	v_pk_fma_f32 v[168:169], v[158:159], v[214:215], v[168:169]
	v_cvt_pk_bf16_f32 v223, v164, v165
	v_mul_f32_e32 v171, 0xbfb8aa3b, v168
	v_exp_f32_e32 v171, v171
	v_and_b32_e32 v165, 0xffff0000, v31
	v_lshlrev_b32_e32 v164, 16, v31
	s_and_b64 vcc, exec, s[38:39]
	v_add_f32_e32 v171, 1.0, v171
	v_rcp_f32_e32 v180, v171
	v_mul_f32_e32 v171, 0xbfb8aa3b, v169
	v_exp_f32_e32 v171, v171
	global_store_dwordx4 v[162:163], v[220:223], off offset:1536
	v_add_f32_e32 v171, 1.0, v171
	v_rcp_f32_e32 v181, v171
	s_nop 0
	v_pk_mul_f32 v[168:169], v[168:169], v[180:181]
	v_pk_mul_f32 v[180:181], v[152:153], v[202:203]
	s_nop 0
	v_pk_fma_f32 v[180:181], v[148:149], v[208:209], v[180:181]
	s_nop 0
	v_pk_fma_f32 v[180:181], v[156:157], v[206:207], v[180:181]
	s_nop 0
	v_pk_fma_f32 v[180:181], v[160:161], v[200:201], v[180:181]
	s_nop 0
	v_mul_f32_e32 v171, 0xbfb8aa3b, v180
	v_exp_f32_e32 v171, v171
	s_nop 0
	v_add_f32_e32 v171, 1.0, v171
	v_rcp_f32_e32 v184, v171
	v_mul_f32_e32 v171, 0xbfb8aa3b, v181
	v_exp_f32_e32 v171, v171
	s_nop 0
	v_add_f32_e32 v171, 1.0, v171
	v_rcp_f32_e32 v185, v171
	s_nop 0
	v_pk_mul_f32 v[180:181], v[180:181], v[184:185]
	v_pk_mul_f32 v[184:185], v[134:135], v[178:179]
	s_nop 0
	v_pk_fma_f32 v[184:185], v[130:131], v[198:199], v[184:185]
	s_nop 0
	v_pk_fma_f32 v[184:185], v[138:139], v[196:197], v[184:185]
	s_nop 0
	v_pk_fma_f32 v[184:185], v[142:143], v[176:177], v[184:185]
	s_nop 0
	v_mul_f32_e32 v171, 0xbfb8aa3b, v184
	v_exp_f32_e32 v171, v171
	s_nop 0
	v_add_f32_e32 v171, 1.0, v171
	v_rcp_f32_e32 v186, v171
	v_mul_f32_e32 v171, 0xbfb8aa3b, v185
	v_exp_f32_e32 v171, v171
	s_nop 0
	v_add_f32_e32 v171, 1.0, v171
	v_rcp_f32_e32 v187, v171
	s_nop 0
	v_pk_mul_f32 v[198:199], v[184:185], v[186:187]
	v_pk_mul_f32 v[184:185], v[136:137], v[166:167]
	s_nop 0
	v_pk_fma_f32 v[174:175], v[132:133], v[174:175], v[184:185]
	s_nop 0
	v_pk_fma_f32 v[174:175], v[140:141], v[172:173], v[174:175]
	s_nop 0
	v_pk_fma_f32 v[174:175], v[144:145], v[164:165], v[174:175]
	s_nop 0
	v_mul_f32_e32 v171, 0xbfb8aa3b, v174
	v_exp_f32_e32 v171, v171
	s_nop 0
	v_add_f32_e32 v171, 1.0, v171
	v_rcp_f32_e32 v184, v171
	v_mul_f32_e32 v171, 0xbfb8aa3b, v175
	v_exp_f32_e32 v171, v171
	s_nop 0
	v_add_f32_e32 v171, 1.0, v171
	v_rcp_f32_e32 v185, v171
	s_nop 0
	v_pk_mul_f32 v[174:175], v[174:175], v[184:185]
	s_cbranch_vccnz .LBB0_521
	v_pk_mul_f32 v[170:171], v[168:169], v[168:169]
	v_pk_mul_f32 v[184:185], v[180:181], v[180:181]
	v_add_f32_e32 v170, v170, v171
	v_add_f32_e32 v170, v184, v170
	v_pk_mul_f32 v[186:187], v[198:199], v[198:199]
	v_add_f32_e32 v170, v185, v170
	v_and_b32_e32 v184, 64, v232
	v_add_f32_e32 v170, v186, v170
	v_xor_b32_e32 v171, 1, v232
	v_add_u32_e32 v184, 64, v184
	v_pk_mul_f32 v[204:205], v[174:175], v[174:175]
	v_add_f32_e32 v170, v187, v170
	v_cmp_lt_i32_e32 vcc, v171, v184
	v_add_f32_e32 v170, v204, v170
	v_add_f32_e32 v170, v205, v170
	v_cndmask_b32_e32 v171, v232, v171, vcc
	v_lshlrev_b32_e32 v171, 2, v171
	s_nop 1
	v_mov_b32_dpp v171, v170 quad_perm:[1,0,3,2] row_mask:0xf bank_mask:0xf
	s_waitcnt lgkmcnt(0)
	v_add_f32_e32 v170, v170, v171
	v_xor_b32_e32 v171, 2, v232
	v_cmp_lt_i32_e32 vcc, v171, v184
	s_nop 1
	v_cndmask_b32_e32 v171, v232, v171, vcc
	v_lshlrev_b32_e32 v171, 2, v171
	s_nop 1
	v_mov_b32_dpp v171, v170 quad_perm:[2,3,0,1] row_mask:0xf bank_mask:0xf
	s_waitcnt lgkmcnt(0)
	v_add_f32_e32 v170, v170, v171
	v_xor_b32_e32 v171, 4, v232
	v_cmp_lt_i32_e32 vcc, v171, v184
	s_nop 1
	v_cndmask_b32_e32 v171, v232, v171, vcc
	v_lshlrev_b32_e32 v171, 2, v171
	s_nop 1
	v_mov_b32_dpp v171, v170 row_half_mirror row_mask:0xf bank_mask:0xf
	s_waitcnt lgkmcnt(0)
	v_add_f32_e32 v170, v170, v171
	v_xor_b32_e32 v171, 8, v232
	v_cmp_lt_i32_e32 vcc, v171, v184
	s_nop 1
	v_cndmask_b32_e32 v171, v232, v171, vcc
	v_lshlrev_b32_e32 v171, 2, v171
	s_nop 1
	v_mov_b32_dpp v171, v170 row_mirror row_mask:0xf bank_mask:0xf
	s_waitcnt lgkmcnt(0)
	v_add_f32_e32 v170, v170, v171
	v_add_f32_e32 v170, 0x358637bd, v170
	v_rsq_f32_e32 v170, v170
	s_nop 0
	v_mul_f32_e32 v170, v219, v170
.LBB0_521:
	v_pk_mul_f32 v[168:169], v[168:169], v[170:171] op_sel_hi:[1,0]
	v_lshlrev_b32_e32 v208, 16, v32
	v_cvt_pk_bf16_f32 v220, v168, v169
	v_pk_mul_f32 v[168:169], v[180:181], v[170:171] op_sel_hi:[1,0]
	v_and_b32_e32 v209, 0xffff0000, v32
	v_cvt_pk_bf16_f32 v221, v168, v169
	v_pk_mul_f32 v[168:169], v[198:199], v[170:171] op_sel_hi:[1,0]
	v_and_b32_e32 v205, 0xffff0000, v33
	v_cvt_pk_bf16_f32 v222, v168, v169
	v_pk_mul_f32 v[168:169], v[174:175], v[170:171] op_sel_hi:[1,0]
	v_lshlrev_b32_e32 v204, 16, v33
	v_cvt_pk_bf16_f32 v223, v168, v169
	v_pk_mul_f32 v[168:169], v[150:151], v[210:211]
	v_and_b32_e32 v181, 0xffff0000, v34
	v_pk_fma_f32 v[168:169], v[146:147], v[216:217], v[168:169]
	v_lshlrev_b32_e32 v180, 16, v34
	v_pk_fma_f32 v[168:169], v[154:155], v[214:215], v[168:169]
	v_and_b32_e32 v171, 0xffff0000, v35
	v_pk_fma_f32 v[174:175], v[158:159], v[208:209], v[168:169]
	v_lshlrev_b32_e32 v170, 16, v35
	v_mul_f32_e32 v168, 0xbfb8aa3b, v174
	v_exp_f32_e32 v169, v168
	v_mov_b32_e32 v168, 1.0
	s_and_b64 vcc, exec, s[38:39]
	global_store_dwordx4 v[162:163], v[220:223], off offset:1792
	v_add_f32_e32 v169, 1.0, v169
	v_rcp_f32_e32 v184, v169
	v_mul_f32_e32 v169, 0xbfb8aa3b, v175
	v_exp_f32_e32 v169, v169
	s_nop 0
	v_add_f32_e32 v169, 1.0, v169
	v_rcp_f32_e32 v185, v169
	s_nop 0
	v_pk_mul_f32 v[174:175], v[174:175], v[184:185]
	v_pk_mul_f32 v[184:185], v[152:153], v[206:207]
	s_nop 0
	v_pk_fma_f32 v[184:185], v[148:149], v[202:203], v[184:185]
	v_mov_b32_e32 v202, 1.0
	v_pk_fma_f32 v[184:185], v[156:157], v[200:201], v[184:185]
	s_nop 0
	v_pk_fma_f32 v[184:185], v[160:161], v[204:205], v[184:185]
	s_nop 0
	v_mul_f32_e32 v169, 0xbfb8aa3b, v184
	v_exp_f32_e32 v169, v169
	s_nop 0
	v_add_f32_e32 v169, 1.0, v169
	v_rcp_f32_e32 v186, v169
	v_mul_f32_e32 v169, 0xbfb8aa3b, v185
	v_exp_f32_e32 v169, v169
	s_nop 0
	v_add_f32_e32 v169, 1.0, v169
	v_rcp_f32_e32 v187, v169
	s_nop 0
	v_pk_mul_f32 v[198:199], v[184:185], v[186:187]
	v_pk_mul_f32 v[184:185], v[134:135], v[196:197]
	s_nop 0
	v_pk_fma_f32 v[178:179], v[130:131], v[178:179], v[184:185]
	s_nop 0
	v_pk_fma_f32 v[178:179], v[138:139], v[176:177], v[178:179]
	s_nop 0
	v_pk_fma_f32 v[178:179], v[142:143], v[180:181], v[178:179]
	s_nop 0
	v_mul_f32_e32 v169, 0xbfb8aa3b, v178
	v_exp_f32_e32 v169, v169
	s_nop 0
	v_add_f32_e32 v169, 1.0, v169
	v_rcp_f32_e32 v184, v169
	v_mul_f32_e32 v169, 0xbfb8aa3b, v179
	v_exp_f32_e32 v169, v169
	s_nop 0
	v_add_f32_e32 v169, 1.0, v169
	v_rcp_f32_e32 v185, v169
	s_nop 0
	v_pk_mul_f32 v[178:179], v[178:179], v[184:185]
	v_pk_mul_f32 v[184:185], v[136:137], v[172:173]
	s_nop 0
	v_pk_fma_f32 v[166:167], v[132:133], v[166:167], v[184:185]
	s_nop 0
	v_pk_fma_f32 v[166:167], v[140:141], v[164:165], v[166:167]
	s_nop 0
	v_pk_fma_f32 v[166:167], v[144:145], v[170:171], v[166:167]
	s_nop 0
	v_mul_f32_e32 v169, 0xbfb8aa3b, v166
	v_exp_f32_e32 v169, v169
	s_nop 0
	v_add_f32_e32 v169, 1.0, v169
	v_rcp_f32_e32 v184, v169
	v_mul_f32_e32 v169, 0xbfb8aa3b, v167
	v_exp_f32_e32 v169, v169
	s_nop 0
	v_add_f32_e32 v169, 1.0, v169
	v_rcp_f32_e32 v185, v169
	s_nop 0
	v_pk_mul_f32 v[166:167], v[166:167], v[184:185]
	s_cbranch_vccnz .LBB0_523
	v_pk_mul_f32 v[184:185], v[174:175], v[174:175]
	v_pk_mul_f32 v[186:187], v[198:199], v[198:199]
	v_add_f32_e32 v169, v184, v185
	v_add_f32_e32 v169, v186, v169
	v_pk_mul_f32 v[202:203], v[178:179], v[178:179]
	v_add_f32_e32 v169, v187, v169
	v_and_b32_e32 v185, 64, v232
	v_add_f32_e32 v169, v202, v169
	v_xor_b32_e32 v184, 1, v232
	v_add_u32_e32 v185, 64, v185
	v_pk_mul_f32 v[212:213], v[166:167], v[166:167]
	v_add_f32_e32 v169, v203, v169
	v_cmp_lt_i32_e32 vcc, v184, v185
	v_add_f32_e32 v169, v212, v169
	v_add_f32_e32 v169, v213, v169
	v_cndmask_b32_e32 v184, v232, v184, vcc
	v_lshlrev_b32_e32 v184, 2, v184
	s_nop 1
	v_mov_b32_dpp v184, v169 quad_perm:[1,0,3,2] row_mask:0xf bank_mask:0xf
	s_waitcnt lgkmcnt(0)
	v_add_f32_e32 v169, v169, v184
	v_xor_b32_e32 v184, 2, v232
	v_cmp_lt_i32_e32 vcc, v184, v185
	s_nop 1
	v_cndmask_b32_e32 v184, v232, v184, vcc
	v_lshlrev_b32_e32 v184, 2, v184
	s_nop 1
	v_mov_b32_dpp v184, v169 quad_perm:[2,3,0,1] row_mask:0xf bank_mask:0xf
	s_waitcnt lgkmcnt(0)
	v_add_f32_e32 v169, v169, v184
	v_xor_b32_e32 v184, 4, v232
	v_cmp_lt_i32_e32 vcc, v184, v185
	s_nop 1
	v_cndmask_b32_e32 v184, v232, v184, vcc
	v_lshlrev_b32_e32 v184, 2, v184
	s_nop 1
	v_mov_b32_dpp v184, v169 row_half_mirror row_mask:0xf bank_mask:0xf
	s_waitcnt lgkmcnt(0)
	v_add_f32_e32 v169, v169, v184
	v_xor_b32_e32 v184, 8, v232
	v_cmp_lt_i32_e32 vcc, v184, v185
	s_nop 1
	v_cndmask_b32_e32 v184, v232, v184, vcc
	v_lshlrev_b32_e32 v184, 2, v184
	s_nop 1
	v_mov_b32_dpp v184, v169 row_mirror row_mask:0xf bank_mask:0xf
	s_waitcnt lgkmcnt(0)
	v_add_f32_e32 v169, v169, v184
	v_add_f32_e32 v169, 0x358637bd, v169
	v_rsq_f32_e32 v169, v169
	s_nop 0
	v_mul_f32_e32 v202, v219, v169
.LBB0_523:
	v_pk_mul_f32 v[174:175], v[174:175], v[202:203] op_sel_hi:[1,0]
	v_lshlrev_b32_e32 v212, 16, v36
	v_cvt_pk_bf16_f32 v220, v174, v175
	v_pk_mul_f32 v[174:175], v[198:199], v[202:203] op_sel_hi:[1,0]
	v_and_b32_e32 v213, 0xffff0000, v36
	v_cvt_pk_bf16_f32 v221, v174, v175
	v_pk_mul_f32 v[174:175], v[178:179], v[202:203] op_sel_hi:[1,0]
	v_pk_mul_f32 v[178:179], v[150:151], v[214:215]
	v_and_b32_e32 v199, 0xffff0000, v37
	v_pk_fma_f32 v[178:179], v[146:147], v[210:211], v[178:179]
	v_lshlrev_b32_e32 v198, 16, v37
	v_pk_fma_f32 v[178:179], v[154:155], v[208:209], v[178:179]
	v_pk_mul_f32 v[166:167], v[166:167], v[202:203] op_sel_hi:[1,0]
	v_pk_fma_f32 v[178:179], v[158:159], v[212:213], v[178:179]
	v_cvt_pk_bf16_f32 v222, v174, v175
	v_mul_f32_e32 v169, 0xbfb8aa3b, v178
	v_exp_f32_e32 v169, v169
	v_and_b32_e32 v175, 0xffff0000, v38
	v_lshlrev_b32_e32 v174, 16, v38
	v_cvt_pk_bf16_f32 v223, v166, v167
	v_add_f32_e32 v169, 1.0, v169
	v_rcp_f32_e32 v184, v169
	v_mul_f32_e32 v169, 0xbfb8aa3b, v179
	v_exp_f32_e32 v169, v169
	v_and_b32_e32 v167, 0xffff0000, v39
	v_lshlrev_b32_e32 v166, 16, v39
	s_and_b64 vcc, exec, s[38:39]
	v_add_f32_e32 v169, 1.0, v169
	v_rcp_f32_e32 v185, v169
	global_store_dwordx4 v[162:163], v[220:223], off offset:2048
	v_pk_mul_f32 v[178:179], v[178:179], v[184:185]
	v_pk_mul_f32 v[184:185], v[152:153], v[200:201]
	s_nop 0
	v_pk_fma_f32 v[184:185], v[148:149], v[206:207], v[184:185]
	s_nop 0
	v_pk_fma_f32 v[184:185], v[156:157], v[204:205], v[184:185]
	s_nop 0
	v_pk_fma_f32 v[184:185], v[160:161], v[198:199], v[184:185]
	s_nop 0
	v_mul_f32_e32 v169, 0xbfb8aa3b, v184
	v_exp_f32_e32 v169, v169
	s_nop 0
	v_add_f32_e32 v169, 1.0, v169
	v_rcp_f32_e32 v186, v169
	v_mul_f32_e32 v169, 0xbfb8aa3b, v185
	v_exp_f32_e32 v169, v169
	s_nop 0
	v_add_f32_e32 v169, 1.0, v169
	v_rcp_f32_e32 v187, v169
	s_nop 0
	v_pk_mul_f32 v[202:203], v[184:185], v[186:187]
	v_pk_mul_f32 v[184:185], v[134:135], v[176:177]
	s_nop 0
	v_pk_fma_f32 v[184:185], v[130:131], v[196:197], v[184:185]
	s_nop 0
	v_pk_fma_f32 v[184:185], v[138:139], v[180:181], v[184:185]
	s_nop 0
	v_pk_fma_f32 v[184:185], v[142:143], v[174:175], v[184:185]
	s_nop 0
	v_mul_f32_e32 v169, 0xbfb8aa3b, v184
	v_exp_f32_e32 v169, v169
	s_nop 0
	v_add_f32_e32 v169, 1.0, v169
	v_rcp_f32_e32 v186, v169
	v_mul_f32_e32 v169, 0xbfb8aa3b, v185
	v_exp_f32_e32 v169, v169
	s_nop 0
	v_add_f32_e32 v169, 1.0, v169
	v_rcp_f32_e32 v187, v169
	s_nop 0
	v_pk_mul_f32 v[196:197], v[184:185], v[186:187]
	v_pk_mul_f32 v[184:185], v[136:137], v[164:165]
	s_nop 0
	v_pk_fma_f32 v[172:173], v[132:133], v[172:173], v[184:185]
	s_nop 0
	v_pk_fma_f32 v[172:173], v[140:141], v[170:171], v[172:173]
	s_nop 0
	v_pk_fma_f32 v[172:173], v[144:145], v[166:167], v[172:173]
	s_nop 0
	v_mul_f32_e32 v169, 0xbfb8aa3b, v172
	v_exp_f32_e32 v169, v169
	s_nop 0
	v_add_f32_e32 v169, 1.0, v169
	v_rcp_f32_e32 v184, v169
	v_mul_f32_e32 v169, 0xbfb8aa3b, v173
	v_exp_f32_e32 v169, v169
	s_nop 0
	v_add_f32_e32 v169, 1.0, v169
	v_rcp_f32_e32 v185, v169
	s_nop 0
	v_pk_mul_f32 v[172:173], v[172:173], v[184:185]
	s_cbranch_vccnz .LBB0_525
	v_pk_mul_f32 v[168:169], v[178:179], v[178:179]
	v_pk_mul_f32 v[184:185], v[202:203], v[202:203]
	v_add_f32_e32 v168, v168, v169
	v_add_f32_e32 v168, v184, v168
	v_pk_mul_f32 v[186:187], v[196:197], v[196:197]
	v_add_f32_e32 v168, v185, v168
	v_and_b32_e32 v184, 64, v232
	v_add_f32_e32 v168, v186, v168
	v_xor_b32_e32 v169, 1, v232
	v_add_u32_e32 v184, 64, v184
	v_pk_mul_f32 v[206:207], v[172:173], v[172:173]
	v_add_f32_e32 v168, v187, v168
	v_cmp_lt_i32_e32 vcc, v169, v184
	v_add_f32_e32 v168, v206, v168
	v_add_f32_e32 v168, v207, v168
	v_cndmask_b32_e32 v169, v232, v169, vcc
	v_lshlrev_b32_e32 v169, 2, v169
	s_nop 1
	v_mov_b32_dpp v169, v168 quad_perm:[1,0,3,2] row_mask:0xf bank_mask:0xf
	s_waitcnt lgkmcnt(0)
	v_add_f32_e32 v168, v168, v169
	v_xor_b32_e32 v169, 2, v232
	v_cmp_lt_i32_e32 vcc, v169, v184
	s_nop 1
	v_cndmask_b32_e32 v169, v232, v169, vcc
	v_lshlrev_b32_e32 v169, 2, v169
	s_nop 1
	v_mov_b32_dpp v169, v168 quad_perm:[2,3,0,1] row_mask:0xf bank_mask:0xf
	s_waitcnt lgkmcnt(0)
	v_add_f32_e32 v168, v168, v169
	v_xor_b32_e32 v169, 4, v232
	v_cmp_lt_i32_e32 vcc, v169, v184
	s_nop 1
	v_cndmask_b32_e32 v169, v232, v169, vcc
	v_lshlrev_b32_e32 v169, 2, v169
	s_nop 1
	v_mov_b32_dpp v169, v168 row_half_mirror row_mask:0xf bank_mask:0xf
	s_waitcnt lgkmcnt(0)
	v_add_f32_e32 v168, v168, v169
	v_xor_b32_e32 v169, 8, v232
	v_cmp_lt_i32_e32 vcc, v169, v184
	s_nop 1
	v_cndmask_b32_e32 v169, v232, v169, vcc
	v_lshlrev_b32_e32 v169, 2, v169
	s_nop 1
	v_mov_b32_dpp v169, v168 row_mirror row_mask:0xf bank_mask:0xf
	s_waitcnt lgkmcnt(0)
	v_add_f32_e32 v168, v168, v169
	v_add_f32_e32 v168, 0x358637bd, v168
	v_rsq_f32_e32 v168, v168
	s_nop 0
	v_mul_f32_e32 v168, v219, v168
.LBB0_525:
	v_pk_mul_f32 v[178:179], v[178:179], v[168:169] op_sel_hi:[1,0]
	v_mov_b32_e32 v210, 1.0
	v_cvt_pk_bf16_f32 v220, v178, v179
	v_pk_mul_f32 v[178:179], v[202:203], v[168:169] op_sel_hi:[1,0]
	v_lshlrev_b32_e32 v202, 16, v40
	v_cvt_pk_bf16_f32 v221, v178, v179
	v_pk_mul_f32 v[178:179], v[196:197], v[168:169] op_sel_hi:[1,0]
	v_pk_mul_f32 v[168:169], v[172:173], v[168:169] op_sel_hi:[1,0]
	v_pk_mul_f32 v[172:173], v[150:151], v[208:209]
	v_and_b32_e32 v203, 0xffff0000, v40
	v_pk_fma_f32 v[172:173], v[146:147], v[214:215], v[172:173]
	v_and_b32_e32 v197, 0xffff0000, v41
	v_pk_fma_f32 v[172:173], v[154:155], v[212:213], v[172:173]
	v_lshlrev_b32_e32 v196, 16, v41
	v_pk_fma_f32 v[172:173], v[158:159], v[202:203], v[172:173]
	v_cvt_pk_bf16_f32 v222, v178, v179
	v_mul_f32_e32 v184, 0xbfb8aa3b, v172
	v_mul_f32_e32 v185, 0xbfb8aa3b, v173
	v_exp_f32_e32 v184, v184
	v_exp_f32_e32 v185, v185
	v_and_b32_e32 v179, 0xffff0000, v42
	v_lshlrev_b32_e32 v178, 16, v42
	v_add_f32_e32 v184, 1.0, v184
	v_add_f32_e32 v185, 1.0, v185
	v_rcp_f32_e32 v184, v184
	v_rcp_f32_e32 v185, v185
	v_cvt_pk_bf16_f32 v223, v168, v169
	v_and_b32_e32 v169, 0xffff0000, v43
	v_lshlrev_b32_e32 v168, 16, v43
	v_pk_mul_f32 v[172:173], v[172:173], v[184:185]
	v_pk_mul_f32 v[184:185], v[152:153], v[204:205]
	s_and_b64 vcc, exec, s[38:39]
	v_pk_fma_f32 v[184:185], v[148:149], v[200:201], v[184:185]
	v_mov_b32_e32 v206, 1.0
	v_pk_fma_f32 v[184:185], v[156:157], v[198:199], v[184:185]
	global_store_dwordx4 v[162:163], v[220:223], off offset:2304
	v_pk_fma_f32 v[184:185], v[160:161], v[196:197], v[184:185]
	s_nop 0
	v_mul_f32_e32 v186, 0xbfb8aa3b, v184
	v_mul_f32_e32 v187, 0xbfb8aa3b, v185
	v_exp_f32_e32 v186, v186
	v_exp_f32_e32 v187, v187
	v_add_f32_e32 v186, 1.0, v186
	v_add_f32_e32 v187, 1.0, v187
	v_rcp_f32_e32 v186, v186
	v_rcp_f32_e32 v187, v187
	s_nop 0
	v_pk_mul_f32 v[200:201], v[184:185], v[186:187]
	v_pk_mul_f32 v[184:185], v[134:135], v[180:181]
	s_nop 0
	v_pk_fma_f32 v[176:177], v[130:131], v[176:177], v[184:185]
	s_nop 0
	v_pk_fma_f32 v[176:177], v[138:139], v[174:175], v[176:177]
	s_nop 0
	v_pk_fma_f32 v[176:177], v[142:143], v[178:179], v[176:177]
	s_nop 0
	v_mul_f32_e32 v184, 0xbfb8aa3b, v176
	v_mul_f32_e32 v185, 0xbfb8aa3b, v177
	v_exp_f32_e32 v184, v184
	v_exp_f32_e32 v185, v185
	v_add_f32_e32 v184, 1.0, v184
	v_add_f32_e32 v185, 1.0, v185
	v_rcp_f32_e32 v184, v184
	v_rcp_f32_e32 v185, v185
	s_nop 0
	v_pk_mul_f32 v[176:177], v[176:177], v[184:185]
	v_pk_mul_f32 v[184:185], v[136:137], v[170:171]
	s_nop 0
	v_pk_fma_f32 v[164:165], v[132:133], v[164:165], v[184:185]
	s_nop 0
	v_pk_fma_f32 v[164:165], v[140:141], v[166:167], v[164:165]
	s_nop 0
	v_pk_fma_f32 v[164:165], v[144:145], v[168:169], v[164:165]
	s_nop 0
	v_mul_f32_e32 v184, 0xbfb8aa3b, v164
	v_mul_f32_e32 v185, 0xbfb8aa3b, v165
	v_exp_f32_e32 v184, v184
	v_exp_f32_e32 v185, v185
	v_add_f32_e32 v184, 1.0, v184
	v_add_f32_e32 v185, 1.0, v185
	v_rcp_f32_e32 v184, v184
	v_rcp_f32_e32 v185, v185
	s_nop 0
	v_pk_mul_f32 v[164:165], v[164:165], v[184:185]
	s_cbranch_vccnz .LBB0_527
	v_pk_mul_f32 v[184:185], v[172:173], v[172:173]
	v_pk_mul_f32 v[186:187], v[200:201], v[200:201]
	v_add_f32_e32 v184, v184, v185
	v_add_f32_e32 v184, v186, v184
	v_pk_mul_f32 v[206:207], v[176:177], v[176:177]
	v_add_f32_e32 v184, v187, v184
	v_and_b32_e32 v186, 64, v232
	v_add_f32_e32 v184, v206, v184
	v_xor_b32_e32 v185, 1, v232
	v_add_u32_e32 v186, 64, v186
	v_pk_mul_f32 v[214:215], v[164:165], v[164:165]
	v_add_f32_e32 v184, v207, v184
	v_cmp_lt_i32_e32 vcc, v185, v186
	v_add_f32_e32 v184, v214, v184
	v_add_f32_e32 v184, v215, v184
	v_cndmask_b32_e32 v185, v232, v185, vcc
	v_lshlrev_b32_e32 v185, 2, v185
	s_nop 1
	v_mov_b32_dpp v185, v184 quad_perm:[1,0,3,2] row_mask:0xf bank_mask:0xf
	s_waitcnt lgkmcnt(0)
	v_add_f32_e32 v184, v184, v185
	v_xor_b32_e32 v185, 2, v232
	v_cmp_lt_i32_e32 vcc, v185, v186
	s_nop 1
	v_cndmask_b32_e32 v185, v232, v185, vcc
	v_lshlrev_b32_e32 v185, 2, v185
	s_nop 1
	v_mov_b32_dpp v185, v184 quad_perm:[2,3,0,1] row_mask:0xf bank_mask:0xf
	s_waitcnt lgkmcnt(0)
	v_add_f32_e32 v184, v184, v185
	v_xor_b32_e32 v185, 4, v232
	v_cmp_lt_i32_e32 vcc, v185, v186
	s_nop 1
	v_cndmask_b32_e32 v185, v232, v185, vcc
	v_lshlrev_b32_e32 v185, 2, v185
	s_nop 1
	v_mov_b32_dpp v185, v184 row_half_mirror row_mask:0xf bank_mask:0xf
	s_waitcnt lgkmcnt(0)
	v_add_f32_e32 v184, v184, v185
	v_xor_b32_e32 v185, 8, v232
	v_cmp_lt_i32_e32 vcc, v185, v186
	s_nop 1
	v_cndmask_b32_e32 v185, v232, v185, vcc
	v_lshlrev_b32_e32 v185, 2, v185
	s_nop 1
	v_mov_b32_dpp v185, v184 row_mirror row_mask:0xf bank_mask:0xf
	s_waitcnt lgkmcnt(0)
	v_add_f32_e32 v184, v184, v185
	v_add_f32_e32 v184, 0x358637bd, v184
	v_rsq_f32_e32 v184, v184
	s_nop 0
	v_mul_f32_e32 v206, v219, v184
.LBB0_527:
	v_pk_mul_f32 v[172:173], v[172:173], v[206:207] op_sel_hi:[1,0]
	v_pk_mul_f32 v[184:185], v[150:151], v[212:213]
	v_cvt_pk_bf16_f32 v214, v172, v173
	v_pk_mul_f32 v[172:173], v[200:201], v[206:207] op_sel_hi:[1,0]
	v_pk_fma_f32 v[184:185], v[146:147], v[208:209], v[184:185]
	v_cvt_pk_bf16_f32 v215, v172, v173
	v_pk_mul_f32 v[172:173], v[176:177], v[206:207] op_sel_hi:[1,0]
	v_pk_mul_f32 v[164:165], v[164:165], v[206:207] op_sel_hi:[1,0]
	v_lshlrev_b32_e32 v206, 16, v44
	v_and_b32_e32 v207, 0xffff0000, v44
	v_pk_fma_f32 v[184:185], v[154:155], v[202:203], v[184:185]
	v_and_b32_e32 v177, 0xffff0000, v45
	v_pk_fma_f32 v[184:185], v[158:159], v[206:207], v[184:185]
	v_lshlrev_b32_e32 v176, 16, v45
	v_mul_f32_e32 v186, 0xbfb8aa3b, v184
	v_mul_f32_e32 v187, 0xbfb8aa3b, v185
	v_exp_f32_e32 v186, v186
	v_exp_f32_e32 v187, v187
	v_cvt_pk_bf16_f32 v216, v172, v173
	v_and_b32_e32 v173, 0xffff0000, v46
	v_add_f32_e32 v186, 1.0, v186
	v_add_f32_e32 v187, 1.0, v187
	v_rcp_f32_e32 v186, v186
	v_rcp_f32_e32 v187, v187
	v_lshlrev_b32_e32 v172, 16, v46
	v_cvt_pk_bf16_f32 v217, v164, v165
	v_and_b32_e32 v165, 0xffff0000, v47
	v_pk_mul_f32 v[200:201], v[184:185], v[186:187]
	v_pk_mul_f32 v[184:185], v[152:153], v[198:199]
	v_lshlrev_b32_e32 v164, 16, v47
	v_pk_fma_f32 v[184:185], v[148:149], v[204:205], v[184:185]
	s_and_b64 vcc, exec, s[38:39]
	v_pk_fma_f32 v[184:185], v[156:157], v[196:197], v[184:185]
	global_store_dwordx4 v[162:163], v[214:217], off offset:2560
	v_pk_fma_f32 v[184:185], v[160:161], v[176:177], v[184:185]
	s_nop 0
	v_mul_f32_e32 v186, 0xbfb8aa3b, v184
	v_mul_f32_e32 v187, 0xbfb8aa3b, v185
	v_exp_f32_e32 v186, v186
	v_exp_f32_e32 v187, v187
	v_add_f32_e32 v186, 1.0, v186
	v_add_f32_e32 v187, 1.0, v187
	v_rcp_f32_e32 v186, v186
	v_rcp_f32_e32 v187, v187
	s_nop 0
	v_pk_mul_f32 v[204:205], v[184:185], v[186:187]
	v_pk_mul_f32 v[184:185], v[134:135], v[174:175]
	s_nop 0
	v_pk_fma_f32 v[180:181], v[130:131], v[180:181], v[184:185]
	s_nop 0
	v_pk_fma_f32 v[180:181], v[138:139], v[178:179], v[180:181]
	s_nop 0
	v_pk_fma_f32 v[180:181], v[142:143], v[172:173], v[180:181]
	s_nop 0
	v_mul_f32_e32 v184, 0xbfb8aa3b, v180
	v_mul_f32_e32 v185, 0xbfb8aa3b, v181
	v_exp_f32_e32 v184, v184
	v_exp_f32_e32 v185, v185
	v_add_f32_e32 v184, 1.0, v184
	v_add_f32_e32 v185, 1.0, v185
	v_rcp_f32_e32 v184, v184
	v_rcp_f32_e32 v185, v185
	s_nop 0
	v_pk_mul_f32 v[180:181], v[180:181], v[184:185]
	v_pk_mul_f32 v[184:185], v[136:137], v[166:167]
	s_nop 0
	v_pk_fma_f32 v[170:171], v[132:133], v[170:171], v[184:185]
	s_nop 0
	v_pk_fma_f32 v[170:171], v[140:141], v[168:169], v[170:171]
	s_nop 0
	v_pk_fma_f32 v[170:171], v[144:145], v[164:165], v[170:171]
	s_nop 0
	v_mul_f32_e32 v184, 0xbfb8aa3b, v170
	v_mul_f32_e32 v185, 0xbfb8aa3b, v171
	v_exp_f32_e32 v184, v184
	v_exp_f32_e32 v185, v185
	v_add_f32_e32 v184, 1.0, v184
	v_add_f32_e32 v185, 1.0, v185
	v_rcp_f32_e32 v184, v184
	v_rcp_f32_e32 v185, v185
	s_nop 0
	v_pk_mul_f32 v[170:171], v[170:171], v[184:185]
	s_cbranch_vccnz .LBB0_529
	v_pk_mul_f32 v[184:185], v[200:201], v[200:201]
	v_pk_mul_f32 v[186:187], v[204:205], v[204:205]
	v_add_f32_e32 v184, v184, v185
	v_add_f32_e32 v184, v186, v184
	v_pk_mul_f32 v[208:209], v[180:181], v[180:181]
	v_add_f32_e32 v184, v187, v184
	v_and_b32_e32 v186, 64, v232
	v_add_f32_e32 v184, v208, v184
	v_xor_b32_e32 v185, 1, v232
	v_add_u32_e32 v186, 64, v186
	v_pk_mul_f32 v[210:211], v[170:171], v[170:171]
	v_add_f32_e32 v184, v209, v184
	v_cmp_lt_i32_e32 vcc, v185, v186
	v_add_f32_e32 v184, v210, v184
	v_add_f32_e32 v184, v211, v184
	v_cndmask_b32_e32 v185, v232, v185, vcc
	v_lshlrev_b32_e32 v185, 2, v185
	s_nop 1
	v_mov_b32_dpp v185, v184 quad_perm:[1,0,3,2] row_mask:0xf bank_mask:0xf
	s_waitcnt lgkmcnt(0)
	v_add_f32_e32 v184, v184, v185
	v_xor_b32_e32 v185, 2, v232
	v_cmp_lt_i32_e32 vcc, v185, v186
	s_nop 1
	v_cndmask_b32_e32 v185, v232, v185, vcc
	v_lshlrev_b32_e32 v185, 2, v185
	s_nop 1
	v_mov_b32_dpp v185, v184 quad_perm:[2,3,0,1] row_mask:0xf bank_mask:0xf
	s_waitcnt lgkmcnt(0)
	v_add_f32_e32 v184, v184, v185
	v_xor_b32_e32 v185, 4, v232
	v_cmp_lt_i32_e32 vcc, v185, v186
	s_nop 1
	v_cndmask_b32_e32 v185, v232, v185, vcc
	v_lshlrev_b32_e32 v185, 2, v185
	s_nop 1
	v_mov_b32_dpp v185, v184 row_half_mirror row_mask:0xf bank_mask:0xf
	s_waitcnt lgkmcnt(0)
	v_add_f32_e32 v184, v184, v185
	v_xor_b32_e32 v185, 8, v232
	v_cmp_lt_i32_e32 vcc, v185, v186
	s_nop 1
	v_cndmask_b32_e32 v185, v232, v185, vcc
	v_lshlrev_b32_e32 v185, 2, v185
	s_nop 1
	v_mov_b32_dpp v185, v184 row_mirror row_mask:0xf bank_mask:0xf
	s_waitcnt lgkmcnt(0)
	v_add_f32_e32 v184, v184, v185
	v_add_f32_e32 v184, 0x358637bd, v184
	v_rsq_f32_e32 v184, v184
	s_nop 0
	v_mul_f32_e32 v210, v219, v184
.LBB0_529:
	v_pk_mul_f32 v[184:185], v[200:201], v[210:211] op_sel_hi:[1,0]
	v_and_b32_e32 v201, 0xffff0000, v49
	v_cvt_pk_bf16_f32 v214, v184, v185
	v_pk_mul_f32 v[184:185], v[204:205], v[210:211] op_sel_hi:[1,0]
	v_lshlrev_b32_e32 v204, 16, v48
	v_cvt_pk_bf16_f32 v215, v184, v185
	v_pk_mul_f32 v[184:185], v[150:151], v[202:203]
	v_and_b32_e32 v205, 0xffff0000, v48
	v_pk_fma_f32 v[184:185], v[146:147], v[212:213], v[184:185]
	v_lshlrev_b32_e32 v200, 16, v49
	v_pk_fma_f32 v[184:185], v[154:155], v[206:207], v[184:185]
	v_pk_mul_f32 v[180:181], v[180:181], v[210:211] op_sel_hi:[1,0]
	v_pk_fma_f32 v[184:185], v[158:159], v[204:205], v[184:185]
	v_cvt_pk_bf16_f32 v216, v180, v181
	v_mul_f32_e32 v186, 0xbfb8aa3b, v184
	v_mul_f32_e32 v187, 0xbfb8aa3b, v185
	v_exp_f32_e32 v186, v186
	v_exp_f32_e32 v187, v187
	v_and_b32_e32 v181, 0xffff0000, v50
	v_lshlrev_b32_e32 v180, 16, v50
	v_add_f32_e32 v186, 1.0, v186
	v_add_f32_e32 v187, 1.0, v187
	v_rcp_f32_e32 v186, v186
	v_rcp_f32_e32 v187, v187
	v_pk_mul_f32 v[170:171], v[170:171], v[210:211] op_sel_hi:[1,0]
	v_mov_b32_e32 v210, 1.0
	v_cvt_pk_bf16_f32 v217, v170, v171
	v_pk_mul_f32 v[208:209], v[184:185], v[186:187]
	v_pk_mul_f32 v[184:185], v[152:153], v[196:197]
	v_and_b32_e32 v171, 0xffff0000, v51
	v_pk_fma_f32 v[184:185], v[148:149], v[198:199], v[184:185]
	v_lshlrev_b32_e32 v170, 16, v51
	v_pk_fma_f32 v[184:185], v[156:157], v[176:177], v[184:185]
	s_and_b64 vcc, exec, s[38:39]
	v_pk_fma_f32 v[184:185], v[160:161], v[200:201], v[184:185]
	v_mov_b32_e32 v212, 1.0
	v_mul_f32_e32 v186, 0xbfb8aa3b, v184
	v_mul_f32_e32 v187, 0xbfb8aa3b, v185
	v_exp_f32_e32 v186, v186
	v_exp_f32_e32 v187, v187
	global_store_dwordx4 v[162:163], v[214:217], off offset:2816
	v_add_f32_e32 v186, 1.0, v186
	v_add_f32_e32 v187, 1.0, v187
	v_rcp_f32_e32 v186, v186
	v_rcp_f32_e32 v187, v187
	s_nop 0
	v_pk_mul_f32 v[198:199], v[184:185], v[186:187]
	v_pk_mul_f32 v[184:185], v[134:135], v[178:179]
	s_nop 0
	v_pk_fma_f32 v[174:175], v[130:131], v[174:175], v[184:185]
	s_nop 0
	v_pk_fma_f32 v[174:175], v[138:139], v[172:173], v[174:175]
	s_nop 0
	v_pk_fma_f32 v[174:175], v[142:143], v[180:181], v[174:175]
	s_nop 0
	v_mul_f32_e32 v184, 0xbfb8aa3b, v174
	v_mul_f32_e32 v185, 0xbfb8aa3b, v175
	v_exp_f32_e32 v184, v184
	v_exp_f32_e32 v185, v185
	v_add_f32_e32 v184, 1.0, v184
	v_add_f32_e32 v185, 1.0, v185
	v_rcp_f32_e32 v184, v184
	v_rcp_f32_e32 v185, v185
	s_nop 0
	v_pk_mul_f32 v[174:175], v[174:175], v[184:185]
	v_pk_mul_f32 v[184:185], v[136:137], v[168:169]
	s_nop 0
	v_pk_fma_f32 v[166:167], v[132:133], v[166:167], v[184:185]
	s_nop 0
	v_pk_fma_f32 v[166:167], v[140:141], v[164:165], v[166:167]
	s_nop 0
	v_pk_fma_f32 v[166:167], v[144:145], v[170:171], v[166:167]
	s_nop 0
	v_mul_f32_e32 v184, 0xbfb8aa3b, v166
	v_mul_f32_e32 v185, 0xbfb8aa3b, v167
	v_exp_f32_e32 v184, v184
	v_exp_f32_e32 v185, v185
	v_add_f32_e32 v184, 1.0, v184
	v_add_f32_e32 v185, 1.0, v185
	v_rcp_f32_e32 v184, v184
	v_rcp_f32_e32 v185, v185
	s_nop 0
	v_pk_mul_f32 v[166:167], v[166:167], v[184:185]
	s_cbranch_vccnz .LBB0_531
	v_pk_mul_f32 v[184:185], v[208:209], v[208:209]
	v_pk_mul_f32 v[186:187], v[198:199], v[198:199]
	v_add_f32_e32 v184, v184, v185
	v_add_f32_e32 v184, v186, v184
	v_pk_mul_f32 v[212:213], v[174:175], v[174:175]
	v_add_f32_e32 v184, v187, v184
	v_and_b32_e32 v186, 64, v232
	v_add_f32_e32 v184, v212, v184
	v_xor_b32_e32 v185, 1, v232
	v_add_u32_e32 v186, 64, v186
	v_pk_mul_f32 v[214:215], v[166:167], v[166:167]
	v_add_f32_e32 v184, v213, v184
	v_cmp_lt_i32_e32 vcc, v185, v186
	v_add_f32_e32 v184, v214, v184
	v_add_f32_e32 v184, v215, v184
	v_cndmask_b32_e32 v185, v232, v185, vcc
	v_lshlrev_b32_e32 v185, 2, v185
	s_nop 1
	v_mov_b32_dpp v185, v184 quad_perm:[1,0,3,2] row_mask:0xf bank_mask:0xf
	s_waitcnt lgkmcnt(0)
	v_add_f32_e32 v184, v184, v185
	v_xor_b32_e32 v185, 2, v232
	v_cmp_lt_i32_e32 vcc, v185, v186
	s_nop 1
	v_cndmask_b32_e32 v185, v232, v185, vcc
	v_lshlrev_b32_e32 v185, 2, v185
	s_nop 1
	v_mov_b32_dpp v185, v184 quad_perm:[2,3,0,1] row_mask:0xf bank_mask:0xf
	s_waitcnt lgkmcnt(0)
	v_add_f32_e32 v184, v184, v185
	v_xor_b32_e32 v185, 4, v232
	v_cmp_lt_i32_e32 vcc, v185, v186
	s_nop 1
	v_cndmask_b32_e32 v185, v232, v185, vcc
	v_lshlrev_b32_e32 v185, 2, v185
	s_nop 1
	v_mov_b32_dpp v185, v184 row_half_mirror row_mask:0xf bank_mask:0xf
	s_waitcnt lgkmcnt(0)
	v_add_f32_e32 v184, v184, v185
	v_xor_b32_e32 v185, 8, v232
	v_cmp_lt_i32_e32 vcc, v185, v186
	s_nop 1
	v_cndmask_b32_e32 v185, v232, v185, vcc
	v_lshlrev_b32_e32 v185, 2, v185
	s_nop 1
	v_mov_b32_dpp v185, v184 row_mirror row_mask:0xf bank_mask:0xf
	s_waitcnt lgkmcnt(0)
	v_add_f32_e32 v184, v184, v185
	v_add_f32_e32 v184, 0x358637bd, v184
	v_rsq_f32_e32 v184, v184
	s_nop 0
	v_mul_f32_e32 v212, v219, v184
.LBB0_531:
	v_pk_mul_f32 v[184:185], v[208:209], v[212:213] op_sel_hi:[1,0]
	v_lshlrev_b32_e32 v208, 16, v52
	v_cvt_pk_bf16_f32 v214, v184, v185
	v_pk_mul_f32 v[184:185], v[198:199], v[212:213] op_sel_hi:[1,0]
	v_and_b32_e32 v209, 0xffff0000, v52
	v_cvt_pk_bf16_f32 v215, v184, v185
	v_pk_mul_f32 v[184:185], v[150:151], v[206:207]
	v_and_b32_e32 v199, 0xffff0000, v53
	v_pk_fma_f32 v[184:185], v[146:147], v[202:203], v[184:185]
	v_lshlrev_b32_e32 v198, 16, v53
	v_pk_fma_f32 v[184:185], v[154:155], v[204:205], v[184:185]
	v_pk_mul_f32 v[174:175], v[174:175], v[212:213] op_sel_hi:[1,0]
	v_pk_fma_f32 v[184:185], v[158:159], v[208:209], v[184:185]
	v_cvt_pk_bf16_f32 v216, v174, v175
	v_mul_f32_e32 v186, 0xbfb8aa3b, v184
	v_mul_f32_e32 v187, 0xbfb8aa3b, v185
	v_exp_f32_e32 v186, v186
	v_exp_f32_e32 v187, v187
	v_and_b32_e32 v175, 0xffff0000, v54
	v_lshlrev_b32_e32 v174, 16, v54
	v_add_f32_e32 v186, 1.0, v186
	v_add_f32_e32 v187, 1.0, v187
	v_rcp_f32_e32 v186, v186
	v_rcp_f32_e32 v187, v187
	v_pk_mul_f32 v[166:167], v[166:167], v[212:213] op_sel_hi:[1,0]
	s_and_b64 vcc, exec, s[38:39]
	v_cvt_pk_bf16_f32 v217, v166, v167
	v_pk_mul_f32 v[202:203], v[184:185], v[186:187]
	v_pk_mul_f32 v[184:185], v[152:153], v[176:177]
	v_and_b32_e32 v167, 0xffff0000, v55
	v_pk_fma_f32 v[184:185], v[148:149], v[196:197], v[184:185]
	v_lshlrev_b32_e32 v166, 16, v55
	v_pk_fma_f32 v[184:185], v[156:157], v[200:201], v[184:185]
	global_store_dwordx4 v[162:163], v[214:217], off offset:3072
	v_pk_fma_f32 v[184:185], v[160:161], v[198:199], v[184:185]
	s_nop 0
	v_mul_f32_e32 v186, 0xbfb8aa3b, v184
	v_mul_f32_e32 v187, 0xbfb8aa3b, v185
	v_exp_f32_e32 v186, v186
	v_exp_f32_e32 v187, v187
	v_add_f32_e32 v186, 1.0, v186
	v_add_f32_e32 v187, 1.0, v187
	v_rcp_f32_e32 v186, v186
	v_rcp_f32_e32 v187, v187
	s_nop 0
	v_pk_mul_f32 v[196:197], v[184:185], v[186:187]
	v_pk_mul_f32 v[184:185], v[134:135], v[172:173]
	s_nop 0
	v_pk_fma_f32 v[178:179], v[130:131], v[178:179], v[184:185]
	s_nop 0
	v_pk_fma_f32 v[178:179], v[138:139], v[180:181], v[178:179]
	s_nop 0
	v_pk_fma_f32 v[178:179], v[142:143], v[174:175], v[178:179]
	s_nop 0
	v_mul_f32_e32 v184, 0xbfb8aa3b, v178
	v_mul_f32_e32 v185, 0xbfb8aa3b, v179
	v_exp_f32_e32 v184, v184
	v_exp_f32_e32 v185, v185
	v_add_f32_e32 v184, 1.0, v184
	v_add_f32_e32 v185, 1.0, v185
	v_rcp_f32_e32 v184, v184
	v_rcp_f32_e32 v185, v185
	s_nop 0
	v_pk_mul_f32 v[178:179], v[178:179], v[184:185]
	v_pk_mul_f32 v[184:185], v[136:137], v[164:165]
	s_nop 0
	v_pk_fma_f32 v[168:169], v[132:133], v[168:169], v[184:185]
	s_nop 0
	v_pk_fma_f32 v[168:169], v[140:141], v[170:171], v[168:169]
	s_nop 0
	v_pk_fma_f32 v[168:169], v[144:145], v[166:167], v[168:169]
	s_nop 0
	v_mul_f32_e32 v184, 0xbfb8aa3b, v168
	v_mul_f32_e32 v185, 0xbfb8aa3b, v169
	v_exp_f32_e32 v184, v184
	v_exp_f32_e32 v185, v185
	v_add_f32_e32 v184, 1.0, v184
	v_add_f32_e32 v185, 1.0, v185
	v_rcp_f32_e32 v184, v184
	v_rcp_f32_e32 v185, v185
	s_nop 0
	v_pk_mul_f32 v[168:169], v[168:169], v[184:185]
	s_cbranch_vccnz .LBB0_533
	v_pk_mul_f32 v[184:185], v[202:203], v[202:203]
	v_pk_mul_f32 v[186:187], v[196:197], v[196:197]
	v_add_f32_e32 v184, v184, v185
	v_add_f32_e32 v184, v186, v184
	v_pk_mul_f32 v[210:211], v[178:179], v[178:179]
	v_add_f32_e32 v184, v187, v184
	v_and_b32_e32 v186, 64, v232
	v_add_f32_e32 v184, v210, v184
	v_xor_b32_e32 v185, 1, v232
	v_add_u32_e32 v186, 64, v186
	v_pk_mul_f32 v[212:213], v[168:169], v[168:169]
	v_add_f32_e32 v184, v211, v184
	v_cmp_lt_i32_e32 vcc, v185, v186
	v_add_f32_e32 v184, v212, v184
	v_add_f32_e32 v184, v213, v184
	v_cndmask_b32_e32 v185, v232, v185, vcc
	v_lshlrev_b32_e32 v185, 2, v185
	s_nop 1
	v_mov_b32_dpp v185, v184 quad_perm:[1,0,3,2] row_mask:0xf bank_mask:0xf
	s_waitcnt lgkmcnt(0)
	v_add_f32_e32 v184, v184, v185
	v_xor_b32_e32 v185, 2, v232
	v_cmp_lt_i32_e32 vcc, v185, v186
	s_nop 1
	v_cndmask_b32_e32 v185, v232, v185, vcc
	v_lshlrev_b32_e32 v185, 2, v185
	s_nop 1
	v_mov_b32_dpp v185, v184 quad_perm:[2,3,0,1] row_mask:0xf bank_mask:0xf
	s_waitcnt lgkmcnt(0)
	v_add_f32_e32 v184, v184, v185
	v_xor_b32_e32 v185, 4, v232
	v_cmp_lt_i32_e32 vcc, v185, v186
	s_nop 1
	v_cndmask_b32_e32 v185, v232, v185, vcc
	v_lshlrev_b32_e32 v185, 2, v185
	s_nop 1
	v_mov_b32_dpp v185, v184 row_half_mirror row_mask:0xf bank_mask:0xf
	s_waitcnt lgkmcnt(0)
	v_add_f32_e32 v184, v184, v185
	v_xor_b32_e32 v185, 8, v232
	v_cmp_lt_i32_e32 vcc, v185, v186
	s_nop 1
	v_cndmask_b32_e32 v185, v232, v185, vcc
	v_lshlrev_b32_e32 v185, 2, v185
	s_nop 1
	v_mov_b32_dpp v185, v184 row_mirror row_mask:0xf bank_mask:0xf
	s_waitcnt lgkmcnt(0)
	v_add_f32_e32 v184, v184, v185
	v_add_f32_e32 v184, 0x358637bd, v184
	v_rsq_f32_e32 v184, v184
	s_nop 0
	v_mul_f32_e32 v210, v219, v184
.LBB0_533:
	v_pk_mul_f32 v[168:169], v[168:169], v[210:211] op_sel_hi:[1,0]
	v_pk_mul_f32 v[184:185], v[202:203], v[210:211] op_sel_hi:[1,0]
	v_cvt_pk_bf16_f32 v215, v168, v169
	v_pk_mul_f32 v[168:169], v[150:151], v[204:205]
	v_cvt_pk_bf16_f32 v212, v184, v185
	v_pk_fma_f32 v[168:169], v[146:147], v[206:207], v[168:169]
	v_pk_mul_f32 v[184:185], v[196:197], v[210:211] op_sel_hi:[1,0]
	v_pk_mul_f32 v[178:179], v[178:179], v[210:211] op_sel_hi:[1,0]
	v_lshlrev_b32_e32 v210, 16, v56
	v_and_b32_e32 v211, 0xffff0000, v56
	v_pk_fma_f32 v[168:169], v[154:155], v[208:209], v[168:169]
	v_cvt_pk_bf16_f32 v213, v184, v185
	v_pk_fma_f32 v[184:185], v[158:159], v[210:211], v[168:169]
	v_and_b32_e32 v203, 0xffff0000, v57
	v_mul_f32_e32 v168, 0xbfb8aa3b, v184
	v_exp_f32_e32 v169, v168
	v_lshlrev_b32_e32 v202, 16, v57
	v_and_b32_e32 v197, 0xffff0000, v58
	v_lshlrev_b32_e32 v196, 16, v58
	v_add_f32_e32 v169, 1.0, v169
	v_rcp_f32_e32 v186, v169
	v_mul_f32_e32 v169, 0xbfb8aa3b, v185
	v_exp_f32_e32 v169, v169
	v_cvt_pk_bf16_f32 v214, v178, v179
	v_and_b32_e32 v179, 0xffff0000, v59
	v_lshlrev_b32_e32 v178, 16, v59
	v_add_f32_e32 v169, 1.0, v169
	v_rcp_f32_e32 v187, v169
	global_store_dwordx4 v[162:163], v[212:215], off offset:3328
	v_mov_b32_e32 v168, 1.0
	s_and_b64 vcc, exec, s[38:39]
	v_pk_mul_f32 v[206:207], v[184:185], v[186:187]
	v_pk_mul_f32 v[184:185], v[152:153], v[200:201]
	v_mov_b32_e32 v212, 1.0
	v_pk_fma_f32 v[176:177], v[148:149], v[176:177], v[184:185]
	s_nop 0
	v_pk_fma_f32 v[176:177], v[156:157], v[198:199], v[176:177]
	s_nop 0
	v_pk_fma_f32 v[176:177], v[160:161], v[202:203], v[176:177]
	s_nop 0
	v_mul_f32_e32 v169, 0xbfb8aa3b, v176
	v_exp_f32_e32 v169, v169
	s_nop 0
	v_add_f32_e32 v169, 1.0, v169
	v_rcp_f32_e32 v184, v169
	v_mul_f32_e32 v169, 0xbfb8aa3b, v177
	v_exp_f32_e32 v169, v169
	s_nop 0
	v_add_f32_e32 v169, 1.0, v169
	v_rcp_f32_e32 v185, v169
	s_nop 0
	v_pk_mul_f32 v[176:177], v[176:177], v[184:185]
	v_pk_mul_f32 v[184:185], v[134:135], v[180:181]
	s_nop 0
	v_pk_fma_f32 v[172:173], v[130:131], v[172:173], v[184:185]
	s_nop 0
	v_pk_fma_f32 v[172:173], v[138:139], v[174:175], v[172:173]
	s_nop 0
	v_pk_fma_f32 v[172:173], v[142:143], v[196:197], v[172:173]
	s_nop 0
	v_mul_f32_e32 v169, 0xbfb8aa3b, v172
	v_exp_f32_e32 v169, v169
	s_nop 0
	v_add_f32_e32 v169, 1.0, v169
	v_rcp_f32_e32 v184, v169
	v_mul_f32_e32 v169, 0xbfb8aa3b, v173
	v_exp_f32_e32 v169, v169
	s_nop 0
	v_add_f32_e32 v169, 1.0, v169
	v_rcp_f32_e32 v185, v169
	s_nop 0
	v_pk_mul_f32 v[172:173], v[172:173], v[184:185]
	v_pk_mul_f32 v[184:185], v[136:137], v[170:171]
	s_nop 0
	v_pk_fma_f32 v[164:165], v[132:133], v[164:165], v[184:185]
	s_nop 0
	v_pk_fma_f32 v[164:165], v[140:141], v[166:167], v[164:165]
	s_nop 0
	v_pk_fma_f32 v[164:165], v[144:145], v[178:179], v[164:165]
	s_nop 0
	v_mul_f32_e32 v169, 0xbfb8aa3b, v164
	v_exp_f32_e32 v169, v169
	s_nop 0
	v_add_f32_e32 v169, 1.0, v169
	v_rcp_f32_e32 v184, v169
	v_mul_f32_e32 v169, 0xbfb8aa3b, v165
	v_exp_f32_e32 v169, v169
	s_nop 0
	v_add_f32_e32 v169, 1.0, v169
	v_rcp_f32_e32 v185, v169
	s_nop 0
	v_pk_mul_f32 v[164:165], v[164:165], v[184:185]
	s_cbranch_vccnz .LBB0_535
	v_pk_mul_f32 v[184:185], v[206:207], v[206:207]
	v_pk_mul_f32 v[186:187], v[176:177], v[176:177]
	v_add_f32_e32 v169, v184, v185
	v_add_f32_e32 v169, v186, v169
	v_pk_mul_f32 v[212:213], v[172:173], v[172:173]
	v_add_f32_e32 v169, v187, v169
	v_and_b32_e32 v185, 64, v232
	v_add_f32_e32 v169, v212, v169
	v_xor_b32_e32 v184, 1, v232
	v_add_u32_e32 v185, 64, v185
	v_pk_mul_f32 v[214:215], v[164:165], v[164:165]
	v_add_f32_e32 v169, v213, v169
	v_cmp_lt_i32_e32 vcc, v184, v185
	v_add_f32_e32 v169, v214, v169
	v_add_f32_e32 v169, v215, v169
	v_cndmask_b32_e32 v184, v232, v184, vcc
	v_lshlrev_b32_e32 v184, 2, v184
	s_nop 1
	v_mov_b32_dpp v184, v169 quad_perm:[1,0,3,2] row_mask:0xf bank_mask:0xf
	s_waitcnt lgkmcnt(0)
	v_add_f32_e32 v169, v169, v184
	v_xor_b32_e32 v184, 2, v232
	v_cmp_lt_i32_e32 vcc, v184, v185
	s_nop 1
	v_cndmask_b32_e32 v184, v232, v184, vcc
	v_lshlrev_b32_e32 v184, 2, v184
	s_nop 1
	v_mov_b32_dpp v184, v169 quad_perm:[2,3,0,1] row_mask:0xf bank_mask:0xf
	s_waitcnt lgkmcnt(0)
	v_add_f32_e32 v169, v169, v184
	v_xor_b32_e32 v184, 4, v232
	v_cmp_lt_i32_e32 vcc, v184, v185
	s_nop 1
	v_cndmask_b32_e32 v184, v232, v184, vcc
	v_lshlrev_b32_e32 v184, 2, v184
	s_nop 1
	v_mov_b32_dpp v184, v169 row_half_mirror row_mask:0xf bank_mask:0xf
	s_waitcnt lgkmcnt(0)
	v_add_f32_e32 v169, v169, v184
	v_xor_b32_e32 v184, 8, v232
	v_cmp_lt_i32_e32 vcc, v184, v185
	s_nop 1
	v_cndmask_b32_e32 v184, v232, v184, vcc
	v_lshlrev_b32_e32 v184, 2, v184
	s_nop 1
	v_mov_b32_dpp v184, v169 row_mirror row_mask:0xf bank_mask:0xf
	s_waitcnt lgkmcnt(0)
	v_add_f32_e32 v169, v169, v184
	v_add_f32_e32 v169, 0x358637bd, v169
	v_rsq_f32_e32 v169, v169
	s_nop 0
	v_mul_f32_e32 v212, v219, v169
.LBB0_535:
	v_pk_mul_f32 v[150:151], v[150:151], v[208:209]
	v_pk_mul_f32 v[164:165], v[164:165], v[212:213] op_sel_hi:[1,0]
	v_pk_fma_f32 v[146:147], v[146:147], v[204:205], v[150:151]
	v_cvt_pk_bf16_f32 v217, v164, v165
	v_lshlrev_b32_e32 v164, 16, v60
	v_and_b32_e32 v165, 0xffff0000, v60
	v_pk_fma_f32 v[146:147], v[154:155], v[210:211], v[146:147]
	v_pk_mul_f32 v[152:153], v[152:153], v[198:199]
	v_pk_fma_f32 v[146:147], v[158:159], v[164:165], v[146:147]
	v_pk_fma_f32 v[148:149], v[148:149], v[200:201], v[152:153]
	v_mul_f32_e32 v150, 0xbfb8aa3b, v146
	v_mul_f32_e32 v151, 0xbfb8aa3b, v147
	v_exp_f32_e32 v150, v150
	v_exp_f32_e32 v151, v151
	v_and_b32_e32 v155, 0xffff0000, v61
	v_lshlrev_b32_e32 v154, 16, v61
	v_pk_fma_f32 v[148:149], v[156:157], v[202:203], v[148:149]
	v_add_f32_e32 v150, 1.0, v150
	v_pk_fma_f32 v[148:149], v[160:161], v[154:155], v[148:149]
	v_add_f32_e32 v151, 1.0, v151
	v_mul_f32_e32 v152, 0xbfb8aa3b, v148
	v_mul_f32_e32 v153, 0xbfb8aa3b, v149
	v_rcp_f32_e32 v150, v150
	v_rcp_f32_e32 v151, v151
	v_exp_f32_e32 v152, v152
	v_exp_f32_e32 v153, v153
	v_pk_mul_f32 v[134:135], v[134:135], v[174:175]
	v_pk_mul_f32 v[136:137], v[136:137], v[166:167]
	v_pk_fma_f32 v[130:131], v[130:131], v[180:181], v[134:135]
	v_pk_fma_f32 v[132:133], v[132:133], v[170:171], v[136:137]
	v_pk_fma_f32 v[130:131], v[138:139], v[196:197], v[130:131]
	v_and_b32_e32 v139, 0xffff0000, v63
	v_lshlrev_b32_e32 v138, 16, v63
	v_pk_fma_f32 v[132:133], v[140:141], v[178:179], v[132:133]
	v_pk_mul_f32 v[146:147], v[146:147], v[150:151]
	v_add_f32_e32 v150, 1.0, v152
	v_add_f32_e32 v151, 1.0, v153
	v_and_b32_e32 v153, 0xffff0000, v62
	v_lshlrev_b32_e32 v152, 16, v62
	v_pk_fma_f32 v[136:137], v[144:145], v[138:139], v[132:133]
	v_pk_fma_f32 v[130:131], v[142:143], v[152:153], v[130:131]
	v_mul_f32_e32 v132, 0xbfb8aa3b, v136
	v_mul_f32_e32 v134, 0xbfb8aa3b, v130
	v_mul_f32_e32 v135, 0xbfb8aa3b, v131
	v_exp_f32_e32 v132, v132
	v_mul_f32_e32 v133, 0xbfb8aa3b, v137
	v_exp_f32_e32 v134, v134
	v_exp_f32_e32 v135, v135
	v_exp_f32_e32 v133, v133
	v_add_f32_e32 v132, 1.0, v132
	v_add_f32_e32 v134, 1.0, v134
	v_add_f32_e32 v135, 1.0, v135
	v_rcp_f32_e32 v138, v132
	v_add_f32_e32 v132, 1.0, v133
	v_rcp_f32_e32 v150, v150
	v_rcp_f32_e32 v151, v151
	v_rcp_f32_e32 v134, v134
	v_rcp_f32_e32 v135, v135
	v_rcp_f32_e32 v139, v132
	v_pk_mul_f32 v[184:185], v[206:207], v[212:213] op_sel_hi:[1,0]
	v_pk_mul_f32 v[176:177], v[176:177], v[212:213] op_sel_hi:[1,0]
	v_pk_mul_f32 v[172:173], v[172:173], v[212:213] op_sel_hi:[1,0]
	v_cvt_pk_bf16_f32 v214, v184, v185
	v_cvt_pk_bf16_f32 v215, v176, v177
	v_cvt_pk_bf16_f32 v216, v172, v173
	v_pk_mul_f32 v[132:133], v[148:149], v[150:151]
	v_pk_mul_f32 v[130:131], v[130:131], v[134:135]
	s_and_b64 vcc, exec, s[38:39]
	v_pk_mul_f32 v[134:135], v[136:137], v[138:139]
	global_store_dwordx4 v[162:163], v[214:217], off offset:3584
	s_cbranch_vccnz .LBB0_537
	v_pk_mul_f32 v[136:137], v[146:147], v[146:147]
	v_pk_mul_f32 v[138:139], v[132:133], v[132:133]
	v_add_f32_e32 v136, v136, v137
	v_add_f32_e32 v136, v138, v136
	v_pk_mul_f32 v[140:141], v[130:131], v[130:131]
	v_add_f32_e32 v136, v139, v136
	v_and_b32_e32 v138, 64, v232
	v_add_f32_e32 v136, v140, v136
	v_xor_b32_e32 v137, 1, v232
	v_add_u32_e32 v138, 64, v138
	v_pk_mul_f32 v[142:143], v[134:135], v[134:135]
	v_add_f32_e32 v136, v141, v136
	v_cmp_lt_i32_e32 vcc, v137, v138
	v_add_f32_e32 v136, v142, v136
	v_add_f32_e32 v136, v143, v136
	v_cndmask_b32_e32 v137, v232, v137, vcc
	v_lshlrev_b32_e32 v137, 2, v137
	s_nop 1
	v_mov_b32_dpp v137, v136 quad_perm:[1,0,3,2] row_mask:0xf bank_mask:0xf
	s_waitcnt lgkmcnt(0)
	v_add_f32_e32 v136, v136, v137
	v_xor_b32_e32 v137, 2, v232
	v_cmp_lt_i32_e32 vcc, v137, v138
	s_nop 1
	v_cndmask_b32_e32 v137, v232, v137, vcc
	v_lshlrev_b32_e32 v137, 2, v137
	s_nop 1
	v_mov_b32_dpp v137, v136 quad_perm:[2,3,0,1] row_mask:0xf bank_mask:0xf
	s_waitcnt lgkmcnt(0)
	v_add_f32_e32 v136, v136, v137
	v_xor_b32_e32 v137, 4, v232
	v_cmp_lt_i32_e32 vcc, v137, v138
	s_nop 1
	v_cndmask_b32_e32 v137, v232, v137, vcc
	v_lshlrev_b32_e32 v137, 2, v137
	s_nop 1
	v_mov_b32_dpp v137, v136 row_half_mirror row_mask:0xf bank_mask:0xf
	s_waitcnt lgkmcnt(0)
	v_add_f32_e32 v136, v136, v137
	v_xor_b32_e32 v137, 8, v232
	v_cmp_lt_i32_e32 vcc, v137, v138
	s_nop 1
	v_cndmask_b32_e32 v137, v232, v137, vcc
	v_lshlrev_b32_e32 v137, 2, v137
	s_nop 1
	v_mov_b32_dpp v137, v136 row_mirror row_mask:0xf bank_mask:0xf
	s_waitcnt lgkmcnt(0)
	v_add_f32_e32 v136, v136, v137
	v_add_f32_e32 v136, 0x358637bd, v136
	v_rsq_f32_e32 v136, v136
	s_nop 0
	v_mul_f32_e32 v168, v219, v136

.LBB0_547:
	s_waitcnt vmcnt(0)
	v_lshlrev_b32_e32 v206, 16, v170
	v_and_b32_e32 v207, 0xffff0000, v170
	v_and_b32_e32 v205, 0xffff0000, v171
	v_lshlrev_b32_e32 v204, 16, v171
	v_and_b32_e32 v181, 0xffff0000, v172
	v_lshlrev_b32_e32 v180, 16, v172
	v_and_b32_e32 v171, 0xffff0000, v173
	v_lshlrev_b32_e32 v170, 16, v173
	v_lshlrev_b32_e32 v172, 16, v162
	v_and_b32_e32 v173, 0xffff0000, v162
	v_pk_mul_f32 v[202:203], v[150:151], v[206:207]
	v_lshlrev_b32_e32 v208, 16, v166
	v_and_b32_e32 v209, 0xffff0000, v166
	v_pk_fma_f32 v[172:173], v[146:147], v[172:173], v[202:203]
	v_lshlrev_b32_e32 v196, 16, v64
	v_and_b32_e32 v197, 0xffff0000, v64
	v_pk_fma_f32 v[172:173], v[154:155], v[208:209], v[172:173]
	v_and_b32_e32 v177, 0xffff0000, v169
	v_pk_fma_f32 v[172:173], v[158:159], v[196:197], v[172:173]
	v_lshlrev_b32_e32 v176, 16, v169
	v_mul_f32_e32 v169, 0xbfb8aa3b, v172
	v_exp_f32_e32 v169, v169
	v_and_b32_e32 v185, 0xffff0000, v163
	v_lshlrev_b32_e32 v184, 16, v163
	v_and_b32_e32 v201, 0xffff0000, v167
	v_add_f32_e32 v169, 1.0, v169
	v_rcp_f32_e32 v202, v169
	v_mul_f32_e32 v169, 0xbfb8aa3b, v173
	v_exp_f32_e32 v169, v169
	v_lshlrev_b32_e32 v200, 16, v167
	v_and_b32_e32 v175, 0xffff0000, v65
	v_lshlrev_b32_e32 v174, 16, v65
	v_add_f32_e32 v169, 1.0, v169
	v_rcp_f32_e32 v203, v169
	v_and_b32_e32 v163, 0xffff0000, v164
	v_lshlrev_b32_e32 v162, 16, v164
	v_and_b32_e32 v199, 0xffff0000, v168
	v_pk_mul_f32 v[172:173], v[172:173], v[202:203]
	v_pk_mul_f32 v[202:203], v[152:153], v[204:205]
	v_lshlrev_b32_e32 v198, 16, v168
	v_pk_fma_f32 v[184:185], v[148:149], v[184:185], v[202:203]
	v_and_b32_e32 v167, 0xffff0000, v66
	v_pk_fma_f32 v[184:185], v[156:157], v[200:201], v[184:185]
	v_lshlrev_b32_e32 v166, 16, v66
	v_pk_fma_f32 v[184:185], v[160:161], v[174:175], v[184:185]
	v_and_b32_e32 v187, 0xffff0000, v165
	v_mul_f32_e32 v169, 0xbfb8aa3b, v184
	v_exp_f32_e32 v169, v169
	v_lshlrev_b32_e32 v186, 16, v165
	v_and_b32_e32 v165, 0xffff0000, v67
	v_lshlrev_b32_e32 v164, 16, v67
	v_add_f32_e32 v169, 1.0, v169
	v_rcp_f32_e32 v202, v169
	v_mul_f32_e32 v169, 0xbfb8aa3b, v185
	v_exp_f32_e32 v169, v169
	s_ashr_i32 s19, s20, 1
	s_cmp_lt_u32 s20, 2
	s_cselect_b64 vcc, -1, 0
	v_add_f32_e32 v169, 1.0, v169
	v_rcp_f32_e32 v203, v169
	s_cmp_lt_i32 s19, 2
	s_cselect_b64 s[8:9], -1, 0
	s_cmp_gt_i32 s19, 1
	v_pk_mul_f32 v[202:203], v[184:185], v[202:203]
	v_pk_mul_f32 v[184:185], v[134:135], v[180:181]
	v_mov_b32_e32 v168, 1.0
	v_pk_fma_f32 v[162:163], v[130:131], v[162:163], v[184:185]
	v_cndmask_b32_e32 v219, 1.0, v238, vcc
	v_pk_fma_f32 v[162:163], v[138:139], v[198:199], v[162:163]
	v_mov_b32_e32 v214, 1.0
	v_pk_fma_f32 v[162:163], v[142:143], v[166:167], v[162:163]
	s_nop 0
	v_mul_f32_e32 v169, 0xbfb8aa3b, v162
	v_exp_f32_e32 v169, v169
	s_nop 0
	v_add_f32_e32 v169, 1.0, v169
	v_rcp_f32_e32 v184, v169
	v_mul_f32_e32 v169, 0xbfb8aa3b, v163
	v_exp_f32_e32 v169, v169
	s_nop 0
	v_add_f32_e32 v169, 1.0, v169
	v_rcp_f32_e32 v185, v169
	s_nop 0
	v_pk_mul_f32 v[210:211], v[162:163], v[184:185]
	v_pk_mul_f32 v[162:163], v[136:137], v[170:171]
	s_nop 0
	v_pk_fma_f32 v[162:163], v[132:133], v[186:187], v[162:163]
	s_nop 0
	v_pk_fma_f32 v[162:163], v[140:141], v[176:177], v[162:163]
	s_nop 0
	v_pk_fma_f32 v[162:163], v[144:145], v[164:165], v[162:163]
	s_nop 0
	v_mul_f32_e32 v169, 0xbfb8aa3b, v162
	v_exp_f32_e32 v169, v169
	s_nop 0
	v_add_f32_e32 v169, 1.0, v169
	v_rcp_f32_e32 v184, v169
	v_mul_f32_e32 v169, 0xbfb8aa3b, v163
	v_exp_f32_e32 v169, v169
	s_nop 0
	v_add_f32_e32 v169, 1.0, v169
	v_rcp_f32_e32 v185, v169
	s_nop 0
	v_pk_mul_f32 v[212:213], v[162:163], v[184:185]
	s_cbranch_scc1 .LBB0_549
	v_pk_mul_f32 v[162:163], v[172:173], v[172:173]
	v_pk_mul_f32 v[184:185], v[202:203], v[202:203]
	v_add_f32_e32 v162, v162, v163
	v_add_f32_e32 v162, v184, v162
	v_pk_mul_f32 v[186:187], v[210:211], v[210:211]
	v_add_f32_e32 v162, v185, v162
	v_and_b32_e32 v169, 64, v232
	v_add_f32_e32 v162, v186, v162
	v_xor_b32_e32 v163, 1, v232
	v_add_u32_e32 v169, 64, v169
	v_pk_mul_f32 v[214:215], v[212:213], v[212:213]
	v_add_f32_e32 v162, v187, v162
	v_cmp_lt_i32_e64 s[0:1], v163, v169
	v_add_f32_e32 v162, v214, v162
	v_add_f32_e32 v162, v215, v162
	v_cndmask_b32_e64 v163, v232, v163, s[0:1]
	v_lshlrev_b32_e32 v163, 2, v163
	s_nop 1
	v_mov_b32_dpp v163, v162 quad_perm:[1,0,3,2] row_mask:0xf bank_mask:0xf
	s_waitcnt lgkmcnt(0)
	v_add_f32_e32 v162, v162, v163
	v_xor_b32_e32 v163, 2, v232
	v_cmp_lt_i32_e64 s[0:1], v163, v169
	s_nop 1
	v_cndmask_b32_e64 v163, v232, v163, s[0:1]
	v_lshlrev_b32_e32 v163, 2, v163
	s_nop 1
	v_mov_b32_dpp v163, v162 quad_perm:[2,3,0,1] row_mask:0xf bank_mask:0xf
	s_waitcnt lgkmcnt(0)
	v_add_f32_e32 v162, v162, v163
	v_xor_b32_e32 v163, 4, v232
	v_cmp_lt_i32_e64 s[0:1], v163, v169
	s_nop 1
	v_cndmask_b32_e64 v163, v232, v163, s[0:1]
	v_lshlrev_b32_e32 v163, 2, v163
	s_nop 1
	v_mov_b32_dpp v163, v162 row_half_mirror row_mask:0xf bank_mask:0xf
	s_waitcnt lgkmcnt(0)
	v_add_f32_e32 v162, v162, v163
	v_xor_b32_e32 v163, 8, v232
	v_cmp_lt_i32_e64 s[0:1], v163, v169
	s_nop 1
	v_cndmask_b32_e64 v163, v232, v163, s[0:1]
	v_lshlrev_b32_e32 v163, 2, v163
	s_nop 1
	v_mov_b32_dpp v163, v162 row_mirror row_mask:0xf bank_mask:0xf
	s_waitcnt lgkmcnt(0)
	v_add_f32_e32 v162, v162, v163
	v_add_f32_e32 v162, 0x358637bd, v162
	v_rsq_f32_e32 v162, v162
	s_nop 0
	v_mul_f32_e32 v214, v219, v162
.LBB0_549:
	v_pk_mul_f32 v[172:173], v[172:173], v[214:215] op_sel_hi:[1,0]
	v_pk_mul_f32 v[184:185], v[150:151], v[208:209]
	v_cvt_pk_bf16_f32 v220, v172, v173
	v_pk_mul_f32 v[172:173], v[202:203], v[214:215] op_sel_hi:[1,0]
	v_pk_fma_f32 v[184:185], v[146:147], v[206:207], v[184:185]
	v_cvt_pk_bf16_f32 v221, v172, v173
	v_pk_mul_f32 v[172:173], v[210:211], v[214:215] op_sel_hi:[1,0]
	v_lshlrev_b32_e32 v210, 16, v68
	v_and_b32_e32 v211, 0xffff0000, v68
	v_pk_fma_f32 v[184:185], v[154:155], v[196:197], v[184:185]
	v_and_b32_e32 v203, 0xffff0000, v69
	v_pk_fma_f32 v[184:185], v[158:159], v[210:211], v[184:185]
	v_lshlrev_b32_e32 v202, 16, v69
	v_mul_f32_e32 v169, 0xbfb8aa3b, v184
	v_exp_f32_e32 v169, v169
	v_lshrrev_b32_e32 v162, 7, v178
	v_and_b32_e32 v179, 0xffff0000, v70
	v_lshlrev_b32_e32 v178, 16, v70
	v_add_f32_e32 v169, 1.0, v169
	v_rcp_f32_e32 v186, v169
	v_mul_f32_e32 v169, 0xbfb8aa3b, v185
	v_exp_f32_e32 v169, v169
	v_cvt_pk_bf16_f32 v222, v172, v173
	v_pk_mul_f32 v[172:173], v[212:213], v[214:215] op_sel_hi:[1,0]
	s_ashr_i32 s0, s15, 9
	v_add_f32_e32 v169, 1.0, v169
	v_rcp_f32_e32 v187, v169
	v_cvt_pk_bf16_f32 v223, v172, v173
	v_and_b32_e32 v173, 0xffff0000, v71
	v_lshlrev_b32_e32 v172, 16, v71
	v_pk_mul_f32 v[206:207], v[184:185], v[186:187]
	v_pk_mul_f32 v[184:185], v[152:153], v[200:201]
	s_add_i32 s11, s0, s11
	v_pk_fma_f32 v[184:185], v[148:149], v[204:205], v[184:185]
	s_cmp_eq_u32 s19, 1
	v_pk_fma_f32 v[184:185], v[156:157], v[174:175], v[184:185]
	s_mov_b32 s0, 0x1f100000
	v_pk_fma_f32 v[184:185], v[160:161], v[202:203], v[184:185]
	s_cselect_b32 s15, 0x1d100000, s0
	v_mul_f32_e32 v169, 0xbfb8aa3b, v184
	v_exp_f32_e32 v169, v169
	s_and_b64 s[0:1], vcc, exec
	s_cselect_b32 s0, 0x1b100000, s15
	v_readlane_b32 s36, v254, 56
	v_add_f32_e32 v169, 1.0, v169
	v_rcp_f32_e32 v186, v169
	v_mul_f32_e32 v169, 0xbfb8aa3b, v185
	v_exp_f32_e32 v169, v169
	v_readlane_b32 s37, v254, 57
	s_add_u32 s0, s36, s0
	s_addc_u32 s1, s37, 0
	v_add_f32_e32 v169, 1.0, v169
	v_rcp_f32_e32 v187, v169
	s_lshl_b32 s11, s11, 3
	v_and_or_b32 v162, v162, 7, s11
	v_ashrrev_i32_e32 v163, 31, v162
	v_pk_mul_f32 v[204:205], v[184:185], v[186:187]
	v_pk_mul_f32 v[184:185], v[134:135], v[198:199]
	s_ashr_i32 s11, s10, 31
	v_pk_fma_f32 v[180:181], v[130:131], v[180:181], v[184:185]
	v_lshlrev_b64 v[162:163], 21, v[162:163]
	v_pk_fma_f32 v[180:181], v[138:139], v[166:167], v[180:181]
	v_lshl_add_u64 v[162:163], s[0:1], 0, v[162:163]
	v_pk_fma_f32 v[180:181], v[142:143], v[178:179], v[180:181]
	s_lshl_b64 s[0:1], s[10:11], 8
	v_mul_f32_e32 v169, 0xbfb8aa3b, v180
	v_exp_f32_e32 v169, v169
	v_lshl_add_u64 v[162:163], v[162:163], 0, s[0:1]
	v_lshl_add_u64 v[162:163], v[162:163], 0, v[96:97]
	s_andn2_b64 vcc, exec, s[8:9]
	v_add_f32_e32 v169, 1.0, v169
	v_rcp_f32_e32 v184, v169
	v_mul_f32_e32 v169, 0xbfb8aa3b, v181
	v_exp_f32_e32 v169, v169
	global_store_dwordx4 v[162:163], v[220:223], off
	v_add_f32_e32 v169, 1.0, v169
	v_rcp_f32_e32 v185, v169
	s_nop 0
	v_pk_mul_f32 v[180:181], v[180:181], v[184:185]
	v_pk_mul_f32 v[184:185], v[136:137], v[176:177]
	s_nop 0
	v_pk_fma_f32 v[170:171], v[132:133], v[170:171], v[184:185]
	s_nop 0
	v_pk_fma_f32 v[170:171], v[140:141], v[164:165], v[170:171]
	s_nop 0
	v_pk_fma_f32 v[170:171], v[144:145], v[172:173], v[170:171]
	s_nop 0
	v_mul_f32_e32 v169, 0xbfb8aa3b, v170
	v_exp_f32_e32 v169, v169
	s_nop 0
	v_add_f32_e32 v169, 1.0, v169
	v_rcp_f32_e32 v184, v169
	v_mul_f32_e32 v169, 0xbfb8aa3b, v171
	v_exp_f32_e32 v169, v169
	s_nop 0
	v_add_f32_e32 v169, 1.0, v169
	v_rcp_f32_e32 v185, v169
	v_cndmask_b32_e64 v169, 0, 1, s[8:9]
	v_cmp_ne_u32_e64 s[38:39], 1, v169
	v_pk_mul_f32 v[170:171], v[170:171], v[184:185]
	s_cbranch_vccnz .LBB0_551
	v_pk_mul_f32 v[168:169], v[206:207], v[206:207]
	v_pk_mul_f32 v[184:185], v[204:205], v[204:205]
	v_add_f32_e32 v168, v168, v169
	v_add_f32_e32 v168, v184, v168
	v_pk_mul_f32 v[186:187], v[180:181], v[180:181]
	v_add_f32_e32 v168, v185, v168
	v_and_b32_e32 v184, 64, v232
	v_add_f32_e32 v168, v186, v168
	v_xor_b32_e32 v169, 1, v232
	v_add_u32_e32 v184, 64, v184
	v_pk_mul_f32 v[212:213], v[170:171], v[170:171]
	v_add_f32_e32 v168, v187, v168
	v_cmp_lt_i32_e32 vcc, v169, v184
	v_add_f32_e32 v168, v212, v168
	v_add_f32_e32 v168, v213, v168
	v_cndmask_b32_e32 v169, v232, v169, vcc
	v_lshlrev_b32_e32 v169, 2, v169
	s_nop 1
	v_mov_b32_dpp v169, v168 quad_perm:[1,0,3,2] row_mask:0xf bank_mask:0xf
	s_waitcnt lgkmcnt(0)
	v_add_f32_e32 v168, v168, v169
	v_xor_b32_e32 v169, 2, v232
	v_cmp_lt_i32_e32 vcc, v169, v184
	s_nop 1
	v_cndmask_b32_e32 v169, v232, v169, vcc
	v_lshlrev_b32_e32 v169, 2, v169
	s_nop 1
	v_mov_b32_dpp v169, v168 quad_perm:[2,3,0,1] row_mask:0xf bank_mask:0xf
	s_waitcnt lgkmcnt(0)
	v_add_f32_e32 v168, v168, v169
	v_xor_b32_e32 v169, 4, v232
	v_cmp_lt_i32_e32 vcc, v169, v184
	s_nop 1
	v_cndmask_b32_e32 v169, v232, v169, vcc
	v_lshlrev_b32_e32 v169, 2, v169
	s_nop 1
	v_mov_b32_dpp v169, v168 row_half_mirror row_mask:0xf bank_mask:0xf
	s_waitcnt lgkmcnt(0)
	v_add_f32_e32 v168, v168, v169
	v_xor_b32_e32 v169, 8, v232
	v_cmp_lt_i32_e32 vcc, v169, v184
	s_nop 1
	v_cndmask_b32_e32 v169, v232, v169, vcc
	v_lshlrev_b32_e32 v169, 2, v169
	s_nop 1
	v_mov_b32_dpp v169, v168 row_mirror row_mask:0xf bank_mask:0xf
	s_waitcnt lgkmcnt(0)
	v_add_f32_e32 v168, v168, v169
	v_add_f32_e32 v168, 0x358637bd, v168
	v_rsq_f32_e32 v168, v168
	s_nop 0
	v_mul_f32_e32 v168, v219, v168
.LBB0_551:
	v_pk_mul_f32 v[184:185], v[206:207], v[168:169] op_sel_hi:[1,0]
	v_pk_mul_f32 v[180:181], v[180:181], v[168:169] op_sel_hi:[1,0]
	v_cvt_pk_bf16_f32 v212, v184, v185
	v_pk_mul_f32 v[184:185], v[204:205], v[168:169] op_sel_hi:[1,0]
	v_pk_mul_f32 v[168:169], v[170:171], v[168:169] op_sel_hi:[1,0]
	v_lshlrev_b32_e32 v206, 16, v72
	v_cvt_pk_bf16_f32 v215, v168, v169
	v_pk_mul_f32 v[168:169], v[146:147], v[208:209]
	v_and_b32_e32 v207, 0xffff0000, v72
	v_pk_fma_f32 v[168:169], v[150:151], v[196:197], v[168:169]
	v_cvt_pk_bf16_f32 v213, v184, v185
	v_pk_fma_f32 v[168:169], v[154:155], v[210:211], v[168:169]
	v_and_b32_e32 v205, 0xffff0000, v73
	v_pk_fma_f32 v[168:169], v[158:159], v[206:207], v[168:169]
	v_lshlrev_b32_e32 v204, 16, v73
	v_mul_f32_e32 v184, 0xbfb8aa3b, v168
	v_mul_f32_e32 v185, 0xbfb8aa3b, v169
	v_exp_f32_e32 v184, v184
	v_exp_f32_e32 v185, v185
	v_cvt_pk_bf16_f32 v214, v180, v181
	v_and_b32_e32 v181, 0xffff0000, v74
	v_add_f32_e32 v184, 1.0, v184
	v_add_f32_e32 v185, 1.0, v185
	v_rcp_f32_e32 v184, v184
	v_rcp_f32_e32 v185, v185
	v_lshlrev_b32_e32 v180, 16, v74
	v_pk_mul_f32 v[176:177], v[132:133], v[176:177]
	v_and_b32_e32 v171, 0xffff0000, v75
	v_pk_mul_f32 v[168:169], v[168:169], v[184:185]
	v_pk_mul_f32 v[184:185], v[148:149], v[200:201]
	v_pk_fma_f32 v[176:177], v[136:137], v[164:165], v[176:177]
	v_pk_fma_f32 v[184:185], v[152:153], v[174:175], v[184:185]
	v_lshlrev_b32_e32 v170, 16, v75
	v_pk_fma_f32 v[184:185], v[156:157], v[202:203], v[184:185]
	v_pk_fma_f32 v[176:177], v[140:141], v[172:173], v[176:177]
	v_pk_fma_f32 v[184:185], v[160:161], v[204:205], v[184:185]
	v_pk_fma_f32 v[176:177], v[144:145], v[170:171], v[176:177]
	v_mul_f32_e32 v186, 0xbfb8aa3b, v184
	v_mul_f32_e32 v187, 0xbfb8aa3b, v185
	v_exp_f32_e32 v186, v186
	v_exp_f32_e32 v187, v187
	global_store_dwordx4 v[162:163], v[212:215], off offset:256
	v_mov_b32_e32 v208, 1.0
	v_add_f32_e32 v186, 1.0, v186
	v_add_f32_e32 v187, 1.0, v187
	v_rcp_f32_e32 v186, v186
	v_rcp_f32_e32 v187, v187
	s_and_b64 vcc, exec, s[38:39]
	v_mov_b32_e32 v212, 1.0
	s_movk_i32 s1, 0x3000
	v_pk_mul_f32 v[200:201], v[184:185], v[186:187]
	v_pk_mul_f32 v[184:185], v[130:131], v[198:199]
	s_nop 0
	v_pk_fma_f32 v[184:185], v[134:135], v[166:167], v[184:185]
	s_nop 0
	v_pk_fma_f32 v[184:185], v[138:139], v[178:179], v[184:185]
	s_nop 0
	v_pk_fma_f32 v[184:185], v[142:143], v[180:181], v[184:185]
	s_nop 0
	v_mul_f32_e32 v186, 0xbfb8aa3b, v184
	v_mul_f32_e32 v187, 0xbfb8aa3b, v185
	v_exp_f32_e32 v186, v186
	v_exp_f32_e32 v187, v187
	v_add_f32_e32 v186, 1.0, v186
	v_add_f32_e32 v187, 1.0, v187
	v_rcp_f32_e32 v186, v186
	v_rcp_f32_e32 v187, v187
	s_nop 0
	v_pk_mul_f32 v[198:199], v[184:185], v[186:187]
	v_mul_f32_e32 v184, 0xbfb8aa3b, v176
	v_mul_f32_e32 v185, 0xbfb8aa3b, v177
	v_exp_f32_e32 v184, v184
	v_exp_f32_e32 v185, v185
	v_add_f32_e32 v184, 1.0, v184
	v_add_f32_e32 v185, 1.0, v185
	v_rcp_f32_e32 v184, v184
	v_rcp_f32_e32 v185, v185
	s_nop 0
	v_pk_mul_f32 v[176:177], v[176:177], v[184:185]
	s_cbranch_vccnz .LBB0_553
	v_pk_mul_f32 v[184:185], v[168:169], v[168:169]
	v_pk_mul_f32 v[186:187], v[200:201], v[200:201]
	v_add_f32_e32 v184, v184, v185
	v_add_f32_e32 v184, v186, v184
	v_pk_mul_f32 v[212:213], v[198:199], v[198:199]
	v_add_f32_e32 v184, v187, v184
	v_and_b32_e32 v186, 64, v232
	v_add_f32_e32 v184, v212, v184
	v_xor_b32_e32 v185, 1, v232
	v_add_u32_e32 v186, 64, v186
	v_pk_mul_f32 v[214:215], v[176:177], v[176:177]
	v_add_f32_e32 v184, v213, v184
	v_cmp_lt_i32_e32 vcc, v185, v186
	v_add_f32_e32 v184, v214, v184
	v_add_f32_e32 v184, v215, v184
	v_cndmask_b32_e32 v185, v232, v185, vcc
	v_lshlrev_b32_e32 v185, 2, v185
	s_nop 1
	v_mov_b32_dpp v185, v184 quad_perm:[1,0,3,2] row_mask:0xf bank_mask:0xf
	s_waitcnt lgkmcnt(0)
	v_add_f32_e32 v184, v184, v185
	v_xor_b32_e32 v185, 2, v232
	v_cmp_lt_i32_e32 vcc, v185, v186
	s_nop 1
	v_cndmask_b32_e32 v185, v232, v185, vcc
	v_lshlrev_b32_e32 v185, 2, v185
	s_nop 1
	v_mov_b32_dpp v185, v184 quad_perm:[2,3,0,1] row_mask:0xf bank_mask:0xf
	s_waitcnt lgkmcnt(0)
	v_add_f32_e32 v184, v184, v185
	v_xor_b32_e32 v185, 4, v232
	v_cmp_lt_i32_e32 vcc, v185, v186
	s_nop 1
	v_cndmask_b32_e32 v185, v232, v185, vcc
	v_lshlrev_b32_e32 v185, 2, v185
	s_nop 1
	v_mov_b32_dpp v185, v184 row_half_mirror row_mask:0xf bank_mask:0xf
	s_waitcnt lgkmcnt(0)
	v_add_f32_e32 v184, v184, v185
	v_xor_b32_e32 v185, 8, v232
	v_cmp_lt_i32_e32 vcc, v185, v186
	s_nop 1
	v_cndmask_b32_e32 v185, v232, v185, vcc
	v_lshlrev_b32_e32 v185, 2, v185
	s_nop 1
	v_mov_b32_dpp v185, v184 row_mirror row_mask:0xf bank_mask:0xf
	s_waitcnt lgkmcnt(0)
	v_add_f32_e32 v184, v184, v185
	v_add_f32_e32 v184, 0x358637bd, v184
	v_rsq_f32_e32 v184, v184
	s_nop 0
	v_mul_f32_e32 v212, v219, v184
.LBB0_553:
	v_pk_mul_f32 v[168:169], v[168:169], v[212:213] op_sel_hi:[1,0]
	v_pk_mul_f32 v[184:185], v[150:151], v[210:211]
	v_cvt_pk_bf16_f32 v214, v168, v169
	v_pk_mul_f32 v[168:169], v[200:201], v[212:213] op_sel_hi:[1,0]
	v_pk_fma_f32 v[184:185], v[146:147], v[196:197], v[184:185]
	v_cvt_pk_bf16_f32 v215, v168, v169
	v_pk_mul_f32 v[168:169], v[198:199], v[212:213] op_sel_hi:[1,0]
	v_pk_fma_f32 v[184:185], v[154:155], v[206:207], v[184:185]
	v_cvt_pk_bf16_f32 v216, v168, v169
	v_pk_mul_f32 v[168:169], v[176:177], v[212:213] op_sel_hi:[1,0]
	v_and_b32_e32 v201, 0xffff0000, v77
	v_cvt_pk_bf16_f32 v217, v168, v169
	global_store_dwordx4 v[162:163], v[214:217], off offset:512
	v_lshlrev_b32_e32 v200, 16, v77
	v_and_b32_e32 v177, 0xffff0000, v78
	v_lshlrev_b32_e32 v214, 16, v76
	v_and_b32_e32 v215, 0xffff0000, v76
	v_pk_fma_f32 v[184:185], v[158:159], v[214:215], v[184:185]
	v_lshlrev_b32_e32 v176, 16, v78
	v_mul_f32_e32 v186, 0xbfb8aa3b, v184
	v_mul_f32_e32 v187, 0xbfb8aa3b, v185
	v_exp_f32_e32 v186, v186
	v_exp_f32_e32 v187, v187
	v_and_b32_e32 v169, 0xffff0000, v79
	v_lshlrev_b32_e32 v168, 16, v79
	v_add_f32_e32 v186, 1.0, v186
	v_add_f32_e32 v187, 1.0, v187
	v_rcp_f32_e32 v186, v186
	v_rcp_f32_e32 v187, v187
	s_and_b64 vcc, exec, s[38:39]
	v_pk_mul_f32 v[196:197], v[184:185], v[186:187]
	v_pk_mul_f32 v[184:185], v[152:153], v[202:203]
	s_nop 0
	v_pk_fma_f32 v[174:175], v[148:149], v[174:175], v[184:185]
	s_nop 0
	v_pk_fma_f32 v[174:175], v[156:157], v[204:205], v[174:175]
	s_nop 0
	v_pk_fma_f32 v[174:175], v[160:161], v[200:201], v[174:175]
	s_nop 0
	v_mul_f32_e32 v184, 0xbfb8aa3b, v174
	v_mul_f32_e32 v185, 0xbfb8aa3b, v175
	v_exp_f32_e32 v184, v184
	v_exp_f32_e32 v185, v185
	v_add_f32_e32 v184, 1.0, v184
	v_add_f32_e32 v185, 1.0, v185
	v_rcp_f32_e32 v184, v184
	v_rcp_f32_e32 v185, v185
	s_nop 0
	v_pk_mul_f32 v[174:175], v[174:175], v[184:185]
	v_pk_mul_f32 v[184:185], v[134:135], v[178:179]
	s_nop 0
	v_pk_fma_f32 v[166:167], v[130:131], v[166:167], v[184:185]
	s_nop 0
	v_pk_fma_f32 v[166:167], v[138:139], v[180:181], v[166:167]
	s_nop 0
	v_pk_fma_f32 v[166:167], v[142:143], v[176:177], v[166:167]
	s_nop 0
	v_mul_f32_e32 v184, 0xbfb8aa3b, v166
	v_mul_f32_e32 v185, 0xbfb8aa3b, v167
	v_exp_f32_e32 v184, v184
	v_exp_f32_e32 v185, v185
	v_add_f32_e32 v184, 1.0, v184
	v_add_f32_e32 v185, 1.0, v185
	v_rcp_f32_e32 v184, v184
	v_rcp_f32_e32 v185, v185
	s_nop 0
	v_pk_mul_f32 v[166:167], v[166:167], v[184:185]
	v_pk_mul_f32 v[184:185], v[136:137], v[172:173]
	s_nop 0
	v_pk_fma_f32 v[164:165], v[132:133], v[164:165], v[184:185]
	s_nop 0
	v_pk_fma_f32 v[164:165], v[140:141], v[170:171], v[164:165]
	s_nop 0
	v_pk_fma_f32 v[164:165], v[144:145], v[168:169], v[164:165]
	s_nop 0
	v_mul_f32_e32 v184, 0xbfb8aa3b, v164
	v_mul_f32_e32 v185, 0xbfb8aa3b, v165
	v_exp_f32_e32 v184, v184
	v_exp_f32_e32 v185, v185
	v_add_f32_e32 v184, 1.0, v184
	v_add_f32_e32 v185, 1.0, v185
	v_rcp_f32_e32 v184, v184
	v_rcp_f32_e32 v185, v185
	s_nop 0
	v_pk_mul_f32 v[164:165], v[164:165], v[184:185]
	s_cbranch_vccnz .LBB0_555
	v_pk_mul_f32 v[184:185], v[196:197], v[196:197]
	v_pk_mul_f32 v[186:187], v[174:175], v[174:175]
	v_add_f32_e32 v184, v184, v185
	v_add_f32_e32 v184, v186, v184
	v_pk_mul_f32 v[198:199], v[166:167], v[166:167]
	v_add_f32_e32 v184, v187, v184
	v_and_b32_e32 v186, 64, v232
	v_add_f32_e32 v184, v198, v184
	v_xor_b32_e32 v185, 1, v232
	v_add_u32_e32 v186, 64, v186
	v_pk_mul_f32 v[208:209], v[164:165], v[164:165]
	v_add_f32_e32 v184, v199, v184
	v_cmp_lt_i32_e32 vcc, v185, v186
	v_add_f32_e32 v184, v208, v184
	v_add_f32_e32 v184, v209, v184
	v_cndmask_b32_e32 v185, v232, v185, vcc
	v_lshlrev_b32_e32 v185, 2, v185
	s_nop 1
	v_mov_b32_dpp v185, v184 quad_perm:[1,0,3,2] row_mask:0xf bank_mask:0xf
	s_waitcnt lgkmcnt(0)
	v_add_f32_e32 v184, v184, v185
	v_xor_b32_e32 v185, 2, v232
	v_cmp_lt_i32_e32 vcc, v185, v186
	s_nop 1
	v_cndmask_b32_e32 v185, v232, v185, vcc
	v_lshlrev_b32_e32 v185, 2, v185
	s_nop 1
	v_mov_b32_dpp v185, v184 quad_perm:[2,3,0,1] row_mask:0xf bank_mask:0xf
	s_waitcnt lgkmcnt(0)
	v_add_f32_e32 v184, v184, v185
	v_xor_b32_e32 v185, 4, v232
	v_cmp_lt_i32_e32 vcc, v185, v186
	s_nop 1
	v_cndmask_b32_e32 v185, v232, v185, vcc
	v_lshlrev_b32_e32 v185, 2, v185
	s_nop 1
	v_mov_b32_dpp v185, v184 row_half_mirror row_mask:0xf bank_mask:0xf
	s_waitcnt lgkmcnt(0)
	v_add_f32_e32 v184, v184, v185
	v_xor_b32_e32 v185, 8, v232
	v_cmp_lt_i32_e32 vcc, v185, v186
	s_nop 1
	v_cndmask_b32_e32 v185, v232, v185, vcc
	v_lshlrev_b32_e32 v185, 2, v185
	s_nop 1
	v_mov_b32_dpp v185, v184 row_mirror row_mask:0xf bank_mask:0xf
	s_waitcnt lgkmcnt(0)
	v_add_f32_e32 v184, v184, v185
	v_add_f32_e32 v184, 0x358637bd, v184
	v_rsq_f32_e32 v184, v184
	s_nop 0
	v_mul_f32_e32 v208, v219, v184
.LBB0_555:
	v_pk_mul_f32 v[164:165], v[164:165], v[208:209] op_sel_hi:[1,0]
	v_pk_mul_f32 v[166:167], v[166:167], v[208:209] op_sel_hi:[1,0]
	v_cvt_pk_bf16_f32 v199, v164, v165
	v_pk_mul_f32 v[164:165], v[150:151], v[206:207]
	v_lshlrev_b32_e32 v212, 16, v80
	v_pk_fma_f32 v[164:165], v[146:147], v[210:211], v[164:165]
	v_and_b32_e32 v213, 0xffff0000, v80
	v_pk_fma_f32 v[164:165], v[154:155], v[214:215], v[164:165]
	v_cvt_pk_bf16_f32 v198, v166, v167
	v_pk_fma_f32 v[166:167], v[158:159], v[212:213], v[164:165]
	v_pk_mul_f32 v[184:185], v[196:197], v[208:209] op_sel_hi:[1,0]
	v_mul_f32_e32 v164, 0xbfb8aa3b, v166
	v_exp_f32_e32 v165, v164
	v_cvt_pk_bf16_f32 v196, v184, v185
	v_pk_mul_f32 v[174:175], v[174:175], v[208:209] op_sel_hi:[1,0]
	v_and_b32_e32 v209, 0xffff0000, v81
	v_add_f32_e32 v165, 1.0, v165
	v_rcp_f32_e32 v184, v165
	v_mul_f32_e32 v165, 0xbfb8aa3b, v167
	v_exp_f32_e32 v165, v165
	v_lshlrev_b32_e32 v208, 16, v81
	v_cvt_pk_bf16_f32 v197, v174, v175
	global_store_dwordx4 v[162:163], v[196:199], off offset:768
	v_add_f32_e32 v165, 1.0, v165
	v_rcp_f32_e32 v185, v165
	v_and_b32_e32 v199, 0xffff0000, v82
	v_lshlrev_b32_e32 v198, 16, v82
	v_and_b32_e32 v175, 0xffff0000, v83
	v_pk_mul_f32 v[166:167], v[166:167], v[184:185]
	v_pk_mul_f32 v[184:185], v[152:153], v[204:205]
	v_lshlrev_b32_e32 v174, 16, v83
	v_pk_fma_f32 v[184:185], v[148:149], v[202:203], v[184:185]
	v_mov_b32_e32 v164, 1.0
	v_pk_fma_f32 v[184:185], v[156:157], v[200:201], v[184:185]
	s_and_b64 vcc, exec, s[38:39]
	v_pk_fma_f32 v[184:185], v[160:161], v[208:209], v[184:185]
	v_mov_b32_e32 v202, 1.0
	v_mul_f32_e32 v165, 0xbfb8aa3b, v184
	v_exp_f32_e32 v165, v165
	s_nop 0
	v_add_f32_e32 v165, 1.0, v165
	v_rcp_f32_e32 v186, v165
	v_mul_f32_e32 v165, 0xbfb8aa3b, v185
	v_exp_f32_e32 v165, v165
	s_nop 0
	v_add_f32_e32 v165, 1.0, v165
	v_rcp_f32_e32 v187, v165
	s_nop 0
	v_pk_mul_f32 v[196:197], v[184:185], v[186:187]
	v_pk_mul_f32 v[184:185], v[134:135], v[180:181]
	s_nop 0
	v_pk_fma_f32 v[178:179], v[130:131], v[178:179], v[184:185]
	s_nop 0
	v_pk_fma_f32 v[178:179], v[138:139], v[176:177], v[178:179]
	s_nop 0
	v_pk_fma_f32 v[178:179], v[142:143], v[198:199], v[178:179]
	s_nop 0
	v_mul_f32_e32 v165, 0xbfb8aa3b, v178
	v_exp_f32_e32 v165, v165
	s_nop 0
	v_add_f32_e32 v165, 1.0, v165
	v_rcp_f32_e32 v184, v165
	v_mul_f32_e32 v165, 0xbfb8aa3b, v179
	v_exp_f32_e32 v165, v165
	s_nop 0
	v_add_f32_e32 v165, 1.0, v165
	v_rcp_f32_e32 v185, v165
	s_nop 0
	v_pk_mul_f32 v[178:179], v[178:179], v[184:185]
	v_pk_mul_f32 v[184:185], v[136:137], v[170:171]
	s_nop 0
	v_pk_fma_f32 v[172:173], v[132:133], v[172:173], v[184:185]
	s_nop 0
	v_pk_fma_f32 v[172:173], v[140:141], v[168:169], v[172:173]
	s_nop 0
	v_pk_fma_f32 v[172:173], v[144:145], v[174:175], v[172:173]
	s_nop 0
	v_mul_f32_e32 v165, 0xbfb8aa3b, v172
	v_exp_f32_e32 v165, v165
	s_nop 0
	v_add_f32_e32 v165, 1.0, v165
	v_rcp_f32_e32 v184, v165
	v_mul_f32_e32 v165, 0xbfb8aa3b, v173
	v_exp_f32_e32 v165, v165
	s_nop 0
	v_add_f32_e32 v165, 1.0, v165
	v_rcp_f32_e32 v185, v165
	s_nop 0
	v_pk_mul_f32 v[172:173], v[172:173], v[184:185]
	s_cbranch_vccnz .LBB0_557
	v_pk_mul_f32 v[184:185], v[166:167], v[166:167]
	v_pk_mul_f32 v[186:187], v[196:197], v[196:197]
	v_add_f32_e32 v165, v184, v185
	v_add_f32_e32 v165, v186, v165
	v_pk_mul_f32 v[202:203], v[178:179], v[178:179]
	v_add_f32_e32 v165, v187, v165
	v_and_b32_e32 v185, 64, v232
	v_add_f32_e32 v165, v202, v165
	v_xor_b32_e32 v184, 1, v232
	v_add_u32_e32 v185, 64, v185
	v_pk_mul_f32 v[210:211], v[172:173], v[172:173]
	v_add_f32_e32 v165, v203, v165
	v_cmp_lt_i32_e32 vcc, v184, v185
	v_add_f32_e32 v165, v210, v165
	v_add_f32_e32 v165, v211, v165
	v_cndmask_b32_e32 v184, v232, v184, vcc
	v_lshlrev_b32_e32 v184, 2, v184
	s_nop 1
	v_mov_b32_dpp v184, v165 quad_perm:[1,0,3,2] row_mask:0xf bank_mask:0xf
	s_waitcnt lgkmcnt(0)
	v_add_f32_e32 v165, v165, v184
	v_xor_b32_e32 v184, 2, v232
	v_cmp_lt_i32_e32 vcc, v184, v185
	s_nop 1
	v_cndmask_b32_e32 v184, v232, v184, vcc
	v_lshlrev_b32_e32 v184, 2, v184
	s_nop 1
	v_mov_b32_dpp v184, v165 quad_perm:[2,3,0,1] row_mask:0xf bank_mask:0xf
	s_waitcnt lgkmcnt(0)
	v_add_f32_e32 v165, v165, v184
	v_xor_b32_e32 v184, 4, v232
	v_cmp_lt_i32_e32 vcc, v184, v185
	s_nop 1
	v_cndmask_b32_e32 v184, v232, v184, vcc
	v_lshlrev_b32_e32 v184, 2, v184
	s_nop 1
	v_mov_b32_dpp v184, v165 row_half_mirror row_mask:0xf bank_mask:0xf
	s_waitcnt lgkmcnt(0)
	v_add_f32_e32 v165, v165, v184
	v_xor_b32_e32 v184, 8, v232
	v_cmp_lt_i32_e32 vcc, v184, v185
	s_nop 1
	v_cndmask_b32_e32 v184, v232, v184, vcc
	v_lshlrev_b32_e32 v184, 2, v184
	s_nop 1
	v_mov_b32_dpp v184, v165 row_mirror row_mask:0xf bank_mask:0xf
	s_waitcnt lgkmcnt(0)
	v_add_f32_e32 v165, v165, v184
	v_add_f32_e32 v165, 0x358637bd, v165
	v_rsq_f32_e32 v165, v165
	s_nop 0
	v_mul_f32_e32 v202, v219, v165
.LBB0_557:
	v_pk_mul_f32 v[166:167], v[166:167], v[202:203] op_sel_hi:[1,0]
	v_lshlrev_b32_e32 v216, 16, v84
	v_cvt_pk_bf16_f32 v220, v166, v167
	v_pk_mul_f32 v[166:167], v[196:197], v[202:203] op_sel_hi:[1,0]
	v_and_b32_e32 v217, 0xffff0000, v84
	v_cvt_pk_bf16_f32 v221, v166, v167
	v_pk_mul_f32 v[166:167], v[178:179], v[202:203] op_sel_hi:[1,0]
	v_and_b32_e32 v179, 0xffff0000, v86
	v_cvt_pk_bf16_f32 v222, v166, v167
	v_pk_mul_f32 v[166:167], v[172:173], v[202:203] op_sel_hi:[1,0]
	v_pk_mul_f32 v[172:173], v[150:151], v[214:215]
	v_and_b32_e32 v203, 0xffff0000, v85
	v_pk_fma_f32 v[172:173], v[146:147], v[206:207], v[172:173]
	v_lshlrev_b32_e32 v202, 16, v85
	v_pk_fma_f32 v[172:173], v[154:155], v[212:213], v[172:173]
	v_lshlrev_b32_e32 v178, 16, v86
	v_pk_fma_f32 v[172:173], v[158:159], v[216:217], v[172:173]
	v_cvt_pk_bf16_f32 v223, v166, v167
	v_mul_f32_e32 v165, 0xbfb8aa3b, v172
	v_exp_f32_e32 v165, v165
	v_and_b32_e32 v167, 0xffff0000, v87
	v_lshlrev_b32_e32 v166, 16, v87
	s_and_b64 vcc, exec, s[38:39]
	v_add_f32_e32 v165, 1.0, v165
	v_rcp_f32_e32 v184, v165
	v_mul_f32_e32 v165, 0xbfb8aa3b, v173
	v_exp_f32_e32 v165, v165
	global_store_dwordx4 v[162:163], v[220:223], off offset:1024
	v_add_f32_e32 v165, 1.0, v165
	v_rcp_f32_e32 v185, v165
	s_nop 0
	v_pk_mul_f32 v[172:173], v[172:173], v[184:185]
	v_pk_mul_f32 v[184:185], v[152:153], v[200:201]
	s_nop 0
	v_pk_fma_f32 v[184:185], v[148:149], v[204:205], v[184:185]
	s_nop 0
	v_pk_fma_f32 v[184:185], v[156:157], v[208:209], v[184:185]
	s_nop 0
	v_pk_fma_f32 v[184:185], v[160:161], v[202:203], v[184:185]
	s_nop 0
	v_mul_f32_e32 v165, 0xbfb8aa3b, v184
	v_exp_f32_e32 v165, v165
	s_nop 0
	v_add_f32_e32 v165, 1.0, v165
	v_rcp_f32_e32 v186, v165
	v_mul_f32_e32 v165, 0xbfb8aa3b, v185
	v_exp_f32_e32 v165, v165
	s_nop 0
	v_add_f32_e32 v165, 1.0, v165
	v_rcp_f32_e32 v187, v165
	s_nop 0
	v_pk_mul_f32 v[196:197], v[184:185], v[186:187]
	v_pk_mul_f32 v[184:185], v[134:135], v[176:177]
	s_nop 0
	v_pk_fma_f32 v[180:181], v[130:131], v[180:181], v[184:185]
	s_nop 0
	v_pk_fma_f32 v[180:181], v[138:139], v[198:199], v[180:181]
	s_nop 0
	v_pk_fma_f32 v[180:181], v[142:143], v[178:179], v[180:181]
	s_nop 0
	v_mul_f32_e32 v165, 0xbfb8aa3b, v180
	v_exp_f32_e32 v165, v165
	s_nop 0
	v_add_f32_e32 v165, 1.0, v165
	v_rcp_f32_e32 v184, v165
	v_mul_f32_e32 v165, 0xbfb8aa3b, v181
	v_exp_f32_e32 v165, v165
	s_nop 0
	v_add_f32_e32 v165, 1.0, v165
	v_rcp_f32_e32 v185, v165
	s_nop 0
	v_pk_mul_f32 v[180:181], v[180:181], v[184:185]
	v_pk_mul_f32 v[184:185], v[136:137], v[168:169]
	s_nop 0
	v_pk_fma_f32 v[170:171], v[132:133], v[170:171], v[184:185]
	s_nop 0
	v_pk_fma_f32 v[170:171], v[140:141], v[174:175], v[170:171]
	s_nop 0
	v_pk_fma_f32 v[170:171], v[144:145], v[166:167], v[170:171]
	s_nop 0
	v_mul_f32_e32 v165, 0xbfb8aa3b, v170
	v_exp_f32_e32 v165, v165
	s_nop 0
	v_add_f32_e32 v165, 1.0, v165
	v_rcp_f32_e32 v184, v165
	v_mul_f32_e32 v165, 0xbfb8aa3b, v171
	v_exp_f32_e32 v165, v165
	s_nop 0
	v_add_f32_e32 v165, 1.0, v165
	v_rcp_f32_e32 v185, v165
	s_nop 0
	v_pk_mul_f32 v[170:171], v[170:171], v[184:185]
	s_cbranch_vccnz .LBB0_559
	v_pk_mul_f32 v[164:165], v[172:173], v[172:173]
	v_pk_mul_f32 v[184:185], v[196:197], v[196:197]
	v_add_f32_e32 v164, v164, v165
	v_add_f32_e32 v164, v184, v164
	v_pk_mul_f32 v[186:187], v[180:181], v[180:181]
	v_add_f32_e32 v164, v185, v164
	v_and_b32_e32 v184, 64, v232
	v_add_f32_e32 v164, v186, v164
	v_xor_b32_e32 v165, 1, v232
	v_add_u32_e32 v184, 64, v184
	v_pk_mul_f32 v[204:205], v[170:171], v[170:171]
	v_add_f32_e32 v164, v187, v164
	v_cmp_lt_i32_e32 vcc, v165, v184
	v_add_f32_e32 v164, v204, v164
	v_add_f32_e32 v164, v205, v164
	v_cndmask_b32_e32 v165, v232, v165, vcc
	v_lshlrev_b32_e32 v165, 2, v165
	s_nop 1
	v_mov_b32_dpp v165, v164 quad_perm:[1,0,3,2] row_mask:0xf bank_mask:0xf
	s_waitcnt lgkmcnt(0)
	v_add_f32_e32 v164, v164, v165
	v_xor_b32_e32 v165, 2, v232
	v_cmp_lt_i32_e32 vcc, v165, v184
	s_nop 1
	v_cndmask_b32_e32 v165, v232, v165, vcc
	v_lshlrev_b32_e32 v165, 2, v165
	s_nop 1
	v_mov_b32_dpp v165, v164 quad_perm:[2,3,0,1] row_mask:0xf bank_mask:0xf
	s_waitcnt lgkmcnt(0)
	v_add_f32_e32 v164, v164, v165
	v_xor_b32_e32 v165, 4, v232
	v_cmp_lt_i32_e32 vcc, v165, v184
	s_nop 1
	v_cndmask_b32_e32 v165, v232, v165, vcc
	v_lshlrev_b32_e32 v165, 2, v165
	s_nop 1
	v_mov_b32_dpp v165, v164 row_half_mirror row_mask:0xf bank_mask:0xf
	s_waitcnt lgkmcnt(0)
	v_add_f32_e32 v164, v164, v165
	v_xor_b32_e32 v165, 8, v232
	v_cmp_lt_i32_e32 vcc, v165, v184
	s_nop 1
	v_cndmask_b32_e32 v165, v232, v165, vcc
	v_lshlrev_b32_e32 v165, 2, v165
	s_nop 1
	v_mov_b32_dpp v165, v164 row_mirror row_mask:0xf bank_mask:0xf
	s_waitcnt lgkmcnt(0)
	v_add_f32_e32 v164, v164, v165
	v_add_f32_e32 v164, 0x358637bd, v164
	v_rsq_f32_e32 v164, v164
	s_nop 0
	v_mul_f32_e32 v164, v219, v164
.LBB0_559:
	v_pk_mul_f32 v[172:173], v[172:173], v[164:165] op_sel_hi:[1,0]
	v_lshlrev_b32_e32 v210, 16, v88
	v_cvt_pk_bf16_f32 v204, v172, v173
	v_pk_mul_f32 v[172:173], v[196:197], v[164:165] op_sel_hi:[1,0]
	v_and_b32_e32 v211, 0xffff0000, v88
	v_cvt_pk_bf16_f32 v205, v172, v173
	v_pk_mul_f32 v[172:173], v[180:181], v[164:165] op_sel_hi:[1,0]
	v_pk_mul_f32 v[164:165], v[170:171], v[164:165] op_sel_hi:[1,0]
	v_cvt_pk_bf16_f32 v206, v172, v173
	v_cvt_pk_bf16_f32 v207, v164, v165
	v_pk_mul_f32 v[164:165], v[150:151], v[212:213]
	global_store_dwordx4 v[162:163], v[204:207], off offset:1280
	v_pk_fma_f32 v[164:165], v[146:147], v[214:215], v[164:165]
	v_and_b32_e32 v197, 0xffff0000, v90
	v_pk_fma_f32 v[164:165], v[154:155], v[216:217], v[164:165]
	v_and_b32_e32 v207, 0xffff0000, v89
	v_pk_fma_f32 v[164:165], v[158:159], v[210:211], v[164:165]
	v_lshlrev_b32_e32 v206, 16, v89
	v_mul_f32_e32 v170, 0xbfb8aa3b, v164
	v_exp_f32_e32 v171, v170
	v_lshlrev_b32_e32 v196, 16, v90
	v_and_b32_e32 v173, 0xffff0000, v91
	v_lshlrev_b32_e32 v172, 16, v91
	v_add_f32_e32 v171, 1.0, v171
	v_rcp_f32_e32 v180, v171
	v_mul_f32_e32 v171, 0xbfb8aa3b, v165
	v_exp_f32_e32 v171, v171
	v_mov_b32_e32 v170, 1.0
	s_and_b64 vcc, exec, s[38:39]
	v_add_f32_e32 v171, 1.0, v171
	v_rcp_f32_e32 v181, v171
	s_nop 0
	v_pk_mul_f32 v[164:165], v[164:165], v[180:181]
	v_pk_mul_f32 v[180:181], v[152:153], v[208:209]
	s_nop 0
	v_pk_fma_f32 v[180:181], v[148:149], v[200:201], v[180:181]
	v_mov_b32_e32 v200, 1.0
	v_pk_fma_f32 v[180:181], v[156:157], v[202:203], v[180:181]
	s_nop 0
	v_pk_fma_f32 v[180:181], v[160:161], v[206:207], v[180:181]
	s_nop 0
	v_mul_f32_e32 v171, 0xbfb8aa3b, v180
	v_exp_f32_e32 v171, v171
	s_nop 0
	v_add_f32_e32 v171, 1.0, v171
	v_rcp_f32_e32 v184, v171
	v_mul_f32_e32 v171, 0xbfb8aa3b, v181
	v_exp_f32_e32 v171, v171
	s_nop 0
	v_add_f32_e32 v171, 1.0, v171
	v_rcp_f32_e32 v185, v171
	s_nop 0
	v_pk_mul_f32 v[180:181], v[180:181], v[184:185]
	v_pk_mul_f32 v[184:185], v[134:135], v[198:199]
	s_nop 0
	v_pk_fma_f32 v[176:177], v[130:131], v[176:177], v[184:185]
	s_nop 0
	v_pk_fma_f32 v[176:177], v[138:139], v[178:179], v[176:177]
	s_nop 0
	v_pk_fma_f32 v[176:177], v[142:143], v[196:197], v[176:177]
	s_nop 0
	v_mul_f32_e32 v171, 0xbfb8aa3b, v176
	v_exp_f32_e32 v171, v171
	s_nop 0
	v_add_f32_e32 v171, 1.0, v171
	v_rcp_f32_e32 v184, v171
	v_mul_f32_e32 v171, 0xbfb8aa3b, v177
	v_exp_f32_e32 v171, v171
	s_nop 0
	v_add_f32_e32 v171, 1.0, v171
	v_rcp_f32_e32 v185, v171
	s_nop 0
	v_pk_mul_f32 v[176:177], v[176:177], v[184:185]
	v_pk_mul_f32 v[184:185], v[136:137], v[174:175]
	s_nop 0
	v_pk_fma_f32 v[168:169], v[132:133], v[168:169], v[184:185]
	s_nop 0
	v_pk_fma_f32 v[168:169], v[140:141], v[166:167], v[168:169]
	s_nop 0
	v_pk_fma_f32 v[168:169], v[144:145], v[172:173], v[168:169]
	s_nop 0
	v_mul_f32_e32 v171, 0xbfb8aa3b, v168
	v_exp_f32_e32 v171, v171
	s_nop 0
	v_add_f32_e32 v171, 1.0, v171
	v_rcp_f32_e32 v184, v171
	v_mul_f32_e32 v171, 0xbfb8aa3b, v169
	v_exp_f32_e32 v171, v171
	s_nop 0
	v_add_f32_e32 v171, 1.0, v171
	v_rcp_f32_e32 v185, v171
	s_nop 0
	v_pk_mul_f32 v[168:169], v[168:169], v[184:185]
	s_cbranch_vccnz .LBB0_561
	v_pk_mul_f32 v[184:185], v[164:165], v[164:165]
	v_pk_mul_f32 v[186:187], v[180:181], v[180:181]
	v_add_f32_e32 v171, v184, v185
	v_add_f32_e32 v171, v186, v171
	v_pk_mul_f32 v[200:201], v[176:177], v[176:177]
	v_add_f32_e32 v171, v187, v171
	v_and_b32_e32 v185, 64, v232
	v_add_f32_e32 v171, v200, v171
	v_xor_b32_e32 v184, 1, v232
	v_add_u32_e32 v185, 64, v185
	v_pk_mul_f32 v[204:205], v[168:169], v[168:169]
	v_add_f32_e32 v171, v201, v171
	v_cmp_lt_i32_e32 vcc, v184, v185
	v_add_f32_e32 v171, v204, v171
	v_add_f32_e32 v171, v205, v171
	v_cndmask_b32_e32 v184, v232, v184, vcc
	v_lshlrev_b32_e32 v184, 2, v184
	s_nop 1
	v_mov_b32_dpp v184, v171 quad_perm:[1,0,3,2] row_mask:0xf bank_mask:0xf
	s_waitcnt lgkmcnt(0)
	v_add_f32_e32 v171, v171, v184
	v_xor_b32_e32 v184, 2, v232
	v_cmp_lt_i32_e32 vcc, v184, v185
	s_nop 1
	v_cndmask_b32_e32 v184, v232, v184, vcc
	v_lshlrev_b32_e32 v184, 2, v184
	s_nop 1
	v_mov_b32_dpp v184, v171 quad_perm:[2,3,0,1] row_mask:0xf bank_mask:0xf
	s_waitcnt lgkmcnt(0)
	v_add_f32_e32 v171, v171, v184
	v_xor_b32_e32 v184, 4, v232
	v_cmp_lt_i32_e32 vcc, v184, v185
	s_nop 1
	v_cndmask_b32_e32 v184, v232, v184, vcc
	v_lshlrev_b32_e32 v184, 2, v184
	s_nop 1
	v_mov_b32_dpp v184, v171 row_half_mirror row_mask:0xf bank_mask:0xf
	s_waitcnt lgkmcnt(0)
	v_add_f32_e32 v171, v171, v184
	v_xor_b32_e32 v184, 8, v232
	v_cmp_lt_i32_e32 vcc, v184, v185
	s_nop 1
	v_cndmask_b32_e32 v184, v232, v184, vcc
	v_lshlrev_b32_e32 v184, 2, v184
	s_nop 1
	v_mov_b32_dpp v184, v171 row_mirror row_mask:0xf bank_mask:0xf
	s_waitcnt lgkmcnt(0)
	v_add_f32_e32 v171, v171, v184
	v_add_f32_e32 v171, 0x358637bd, v171
	v_rsq_f32_e32 v171, v171
	s_nop 0
	v_mul_f32_e32 v200, v219, v171
.LBB0_561:
	v_pk_mul_f32 v[164:165], v[164:165], v[200:201] op_sel_hi:[1,0]
	v_lshlrev_b32_e32 v214, 16, v92
	v_cvt_pk_bf16_f32 v220, v164, v165
	v_pk_mul_f32 v[164:165], v[180:181], v[200:201] op_sel_hi:[1,0]
	v_and_b32_e32 v215, 0xffff0000, v92
	v_cvt_pk_bf16_f32 v221, v164, v165
	v_pk_mul_f32 v[164:165], v[176:177], v[200:201] op_sel_hi:[1,0]
	v_and_b32_e32 v177, 0xffff0000, v94
	v_cvt_pk_bf16_f32 v222, v164, v165
	v_pk_mul_f32 v[164:165], v[168:169], v[200:201] op_sel_hi:[1,0]
	v_pk_mul_f32 v[168:169], v[150:151], v[216:217]
	v_and_b32_e32 v201, 0xffff0000, v93
	v_pk_fma_f32 v[168:169], v[146:147], v[212:213], v[168:169]
	v_lshlrev_b32_e32 v200, 16, v93
	v_pk_fma_f32 v[168:169], v[154:155], v[210:211], v[168:169]
	v_lshlrev_b32_e32 v176, 16, v94
	v_pk_fma_f32 v[168:169], v[158:159], v[214:215], v[168:169]
	v_cvt_pk_bf16_f32 v223, v164, v165
	v_mul_f32_e32 v171, 0xbfb8aa3b, v168
	v_exp_f32_e32 v171, v171
	v_and_b32_e32 v165, 0xffff0000, v95
	v_lshlrev_b32_e32 v164, 16, v95
	s_and_b64 vcc, exec, s[38:39]
	v_add_f32_e32 v171, 1.0, v171
	v_rcp_f32_e32 v180, v171
	v_mul_f32_e32 v171, 0xbfb8aa3b, v169
	v_exp_f32_e32 v171, v171
	global_store_dwordx4 v[162:163], v[220:223], off offset:1536
	v_add_f32_e32 v171, 1.0, v171
	v_rcp_f32_e32 v181, v171
	s_nop 0
	v_pk_mul_f32 v[168:169], v[168:169], v[180:181]
	v_pk_mul_f32 v[180:181], v[152:153], v[202:203]
	s_nop 0
	v_pk_fma_f32 v[180:181], v[148:149], v[208:209], v[180:181]
	s_nop 0
	v_pk_fma_f32 v[180:181], v[156:157], v[206:207], v[180:181]
	s_nop 0
	v_pk_fma_f32 v[180:181], v[160:161], v[200:201], v[180:181]
	s_nop 0
	v_mul_f32_e32 v171, 0xbfb8aa3b, v180
	v_exp_f32_e32 v171, v171
	s_nop 0
	v_add_f32_e32 v171, 1.0, v171
	v_rcp_f32_e32 v184, v171
	v_mul_f32_e32 v171, 0xbfb8aa3b, v181
	v_exp_f32_e32 v171, v171
	s_nop 0
	v_add_f32_e32 v171, 1.0, v171
	v_rcp_f32_e32 v185, v171
	s_nop 0
	v_pk_mul_f32 v[180:181], v[180:181], v[184:185]
	v_pk_mul_f32 v[184:185], v[134:135], v[178:179]
	s_nop 0
	v_pk_fma_f32 v[184:185], v[130:131], v[198:199], v[184:185]
	s_nop 0
	v_pk_fma_f32 v[184:185], v[138:139], v[196:197], v[184:185]
	s_nop 0
	v_pk_fma_f32 v[184:185], v[142:143], v[176:177], v[184:185]
	s_nop 0
	v_mul_f32_e32 v171, 0xbfb8aa3b, v184
	v_exp_f32_e32 v171, v171
	s_nop 0
	v_add_f32_e32 v171, 1.0, v171
	v_rcp_f32_e32 v186, v171
	v_mul_f32_e32 v171, 0xbfb8aa3b, v185
	v_exp_f32_e32 v171, v171
	s_nop 0
	v_add_f32_e32 v171, 1.0, v171
	v_rcp_f32_e32 v187, v171
	s_nop 0
	v_pk_mul_f32 v[198:199], v[184:185], v[186:187]
	v_pk_mul_f32 v[184:185], v[136:137], v[166:167]
	s_nop 0
	v_pk_fma_f32 v[174:175], v[132:133], v[174:175], v[184:185]
	s_nop 0
	v_pk_fma_f32 v[174:175], v[140:141], v[172:173], v[174:175]
	s_nop 0
	v_pk_fma_f32 v[174:175], v[144:145], v[164:165], v[174:175]
	s_nop 0
	v_mul_f32_e32 v171, 0xbfb8aa3b, v174
	v_exp_f32_e32 v171, v171
	s_nop 0
	v_add_f32_e32 v171, 1.0, v171
	v_rcp_f32_e32 v184, v171
	v_mul_f32_e32 v171, 0xbfb8aa3b, v175
	v_exp_f32_e32 v171, v171
	s_nop 0
	v_add_f32_e32 v171, 1.0, v171
	v_rcp_f32_e32 v185, v171
	s_nop 0
	v_pk_mul_f32 v[174:175], v[174:175], v[184:185]
	s_cbranch_vccnz .LBB0_563
	v_pk_mul_f32 v[170:171], v[168:169], v[168:169]
	v_pk_mul_f32 v[184:185], v[180:181], v[180:181]
	v_add_f32_e32 v170, v170, v171
	v_add_f32_e32 v170, v184, v170
	v_pk_mul_f32 v[186:187], v[198:199], v[198:199]
	v_add_f32_e32 v170, v185, v170
	v_and_b32_e32 v184, 64, v232
	v_add_f32_e32 v170, v186, v170
	v_xor_b32_e32 v171, 1, v232
	v_add_u32_e32 v184, 64, v184
	v_pk_mul_f32 v[204:205], v[174:175], v[174:175]
	v_add_f32_e32 v170, v187, v170
	v_cmp_lt_i32_e32 vcc, v171, v184
	v_add_f32_e32 v170, v204, v170
	v_add_f32_e32 v170, v205, v170
	v_cndmask_b32_e32 v171, v232, v171, vcc
	v_lshlrev_b32_e32 v171, 2, v171
	s_nop 1
	v_mov_b32_dpp v171, v170 quad_perm:[1,0,3,2] row_mask:0xf bank_mask:0xf
	s_waitcnt lgkmcnt(0)
	v_add_f32_e32 v170, v170, v171
	v_xor_b32_e32 v171, 2, v232
	v_cmp_lt_i32_e32 vcc, v171, v184
	s_nop 1
	v_cndmask_b32_e32 v171, v232, v171, vcc
	v_lshlrev_b32_e32 v171, 2, v171
	s_nop 1
	v_mov_b32_dpp v171, v170 quad_perm:[2,3,0,1] row_mask:0xf bank_mask:0xf
	s_waitcnt lgkmcnt(0)
	v_add_f32_e32 v170, v170, v171
	v_xor_b32_e32 v171, 4, v232
	v_cmp_lt_i32_e32 vcc, v171, v184
	s_nop 1
	v_cndmask_b32_e32 v171, v232, v171, vcc
	v_lshlrev_b32_e32 v171, 2, v171
	s_nop 1
	v_mov_b32_dpp v171, v170 row_half_mirror row_mask:0xf bank_mask:0xf
	s_waitcnt lgkmcnt(0)
	v_add_f32_e32 v170, v170, v171
	v_xor_b32_e32 v171, 8, v232
	v_cmp_lt_i32_e32 vcc, v171, v184
	s_nop 1
	v_cndmask_b32_e32 v171, v232, v171, vcc
	v_lshlrev_b32_e32 v171, 2, v171
	s_nop 1
	v_mov_b32_dpp v171, v170 row_mirror row_mask:0xf bank_mask:0xf
	s_waitcnt lgkmcnt(0)
	v_add_f32_e32 v170, v170, v171
	v_add_f32_e32 v170, 0x358637bd, v170
	v_rsq_f32_e32 v170, v170
	s_nop 0
	v_mul_f32_e32 v170, v219, v170
.LBB0_563:
	v_pk_mul_f32 v[168:169], v[168:169], v[170:171] op_sel_hi:[1,0]
	v_lshlrev_b32_e32 v208, 16, v98
	v_cvt_pk_bf16_f32 v220, v168, v169
	v_pk_mul_f32 v[168:169], v[180:181], v[170:171] op_sel_hi:[1,0]
	v_and_b32_e32 v209, 0xffff0000, v98
	v_cvt_pk_bf16_f32 v221, v168, v169
	v_pk_mul_f32 v[168:169], v[198:199], v[170:171] op_sel_hi:[1,0]
	v_and_b32_e32 v205, 0xffff0000, v99
	v_cvt_pk_bf16_f32 v222, v168, v169
	v_pk_mul_f32 v[168:169], v[174:175], v[170:171] op_sel_hi:[1,0]
	v_lshlrev_b32_e32 v204, 16, v99
	v_cvt_pk_bf16_f32 v223, v168, v169
	v_pk_mul_f32 v[168:169], v[150:151], v[210:211]
	v_and_b32_e32 v181, 0xffff0000, v100
	v_pk_fma_f32 v[168:169], v[146:147], v[216:217], v[168:169]
	v_lshlrev_b32_e32 v180, 16, v100
	v_pk_fma_f32 v[168:169], v[154:155], v[214:215], v[168:169]
	v_and_b32_e32 v171, 0xffff0000, v101
	v_pk_fma_f32 v[174:175], v[158:159], v[208:209], v[168:169]
	v_lshlrev_b32_e32 v170, 16, v101
	v_mul_f32_e32 v168, 0xbfb8aa3b, v174
	v_exp_f32_e32 v169, v168
	v_mov_b32_e32 v168, 1.0
	s_and_b64 vcc, exec, s[38:39]
	global_store_dwordx4 v[162:163], v[220:223], off offset:1792
	v_add_f32_e32 v169, 1.0, v169
	v_rcp_f32_e32 v184, v169
	v_mul_f32_e32 v169, 0xbfb8aa3b, v175
	v_exp_f32_e32 v169, v169
	s_nop 0
	v_add_f32_e32 v169, 1.0, v169
	v_rcp_f32_e32 v185, v169
	s_nop 0
	v_pk_mul_f32 v[174:175], v[174:175], v[184:185]
	v_pk_mul_f32 v[184:185], v[152:153], v[206:207]
	s_nop 0
	v_pk_fma_f32 v[184:185], v[148:149], v[202:203], v[184:185]
	v_mov_b32_e32 v202, 1.0
	v_pk_fma_f32 v[184:185], v[156:157], v[200:201], v[184:185]
	s_nop 0
	v_pk_fma_f32 v[184:185], v[160:161], v[204:205], v[184:185]
	s_nop 0
	v_mul_f32_e32 v169, 0xbfb8aa3b, v184
	v_exp_f32_e32 v169, v169
	s_nop 0
	v_add_f32_e32 v169, 1.0, v169
	v_rcp_f32_e32 v186, v169
	v_mul_f32_e32 v169, 0xbfb8aa3b, v185
	v_exp_f32_e32 v169, v169
	s_nop 0
	v_add_f32_e32 v169, 1.0, v169
	v_rcp_f32_e32 v187, v169
	s_nop 0
	v_pk_mul_f32 v[198:199], v[184:185], v[186:187]
	v_pk_mul_f32 v[184:185], v[134:135], v[196:197]
	s_nop 0
	v_pk_fma_f32 v[178:179], v[130:131], v[178:179], v[184:185]
	s_nop 0
	v_pk_fma_f32 v[178:179], v[138:139], v[176:177], v[178:179]
	s_nop 0
	v_pk_fma_f32 v[178:179], v[142:143], v[180:181], v[178:179]
	s_nop 0
	v_mul_f32_e32 v169, 0xbfb8aa3b, v178
	v_exp_f32_e32 v169, v169
	s_nop 0
	v_add_f32_e32 v169, 1.0, v169
	v_rcp_f32_e32 v184, v169
	v_mul_f32_e32 v169, 0xbfb8aa3b, v179
	v_exp_f32_e32 v169, v169
	s_nop 0
	v_add_f32_e32 v169, 1.0, v169
	v_rcp_f32_e32 v185, v169
	s_nop 0
	v_pk_mul_f32 v[178:179], v[178:179], v[184:185]
	v_pk_mul_f32 v[184:185], v[136:137], v[172:173]
	s_nop 0
	v_pk_fma_f32 v[166:167], v[132:133], v[166:167], v[184:185]
	s_nop 0
	v_pk_fma_f32 v[166:167], v[140:141], v[164:165], v[166:167]
	s_nop 0
	v_pk_fma_f32 v[166:167], v[144:145], v[170:171], v[166:167]
	s_nop 0
	v_mul_f32_e32 v169, 0xbfb8aa3b, v166
	v_exp_f32_e32 v169, v169
	s_nop 0
	v_add_f32_e32 v169, 1.0, v169
	v_rcp_f32_e32 v184, v169
	v_mul_f32_e32 v169, 0xbfb8aa3b, v167
	v_exp_f32_e32 v169, v169
	s_nop 0
	v_add_f32_e32 v169, 1.0, v169
	v_rcp_f32_e32 v185, v169
	s_nop 0
	v_pk_mul_f32 v[166:167], v[166:167], v[184:185]
	s_cbranch_vccnz .LBB0_565
	v_pk_mul_f32 v[184:185], v[174:175], v[174:175]
	v_pk_mul_f32 v[186:187], v[198:199], v[198:199]
	v_add_f32_e32 v169, v184, v185
	v_add_f32_e32 v169, v186, v169
	v_pk_mul_f32 v[202:203], v[178:179], v[178:179]
	v_add_f32_e32 v169, v187, v169
	v_and_b32_e32 v185, 64, v232
	v_add_f32_e32 v169, v202, v169
	v_xor_b32_e32 v184, 1, v232
	v_add_u32_e32 v185, 64, v185
	v_pk_mul_f32 v[212:213], v[166:167], v[166:167]
	v_add_f32_e32 v169, v203, v169
	v_cmp_lt_i32_e32 vcc, v184, v185
	v_add_f32_e32 v169, v212, v169
	v_add_f32_e32 v169, v213, v169
	v_cndmask_b32_e32 v184, v232, v184, vcc
	v_lshlrev_b32_e32 v184, 2, v184
	s_nop 1
	v_mov_b32_dpp v184, v169 quad_perm:[1,0,3,2] row_mask:0xf bank_mask:0xf
	s_waitcnt lgkmcnt(0)
	v_add_f32_e32 v169, v169, v184
	v_xor_b32_e32 v184, 2, v232
	v_cmp_lt_i32_e32 vcc, v184, v185
	s_nop 1
	v_cndmask_b32_e32 v184, v232, v184, vcc
	v_lshlrev_b32_e32 v184, 2, v184
	s_nop 1
	v_mov_b32_dpp v184, v169 quad_perm:[2,3,0,1] row_mask:0xf bank_mask:0xf
	s_waitcnt lgkmcnt(0)
	v_add_f32_e32 v169, v169, v184
	v_xor_b32_e32 v184, 4, v232
	v_cmp_lt_i32_e32 vcc, v184, v185
	s_nop 1
	v_cndmask_b32_e32 v184, v232, v184, vcc
	v_lshlrev_b32_e32 v184, 2, v184
	s_nop 1
	v_mov_b32_dpp v184, v169 row_half_mirror row_mask:0xf bank_mask:0xf
	s_waitcnt lgkmcnt(0)
	v_add_f32_e32 v169, v169, v184
	v_xor_b32_e32 v184, 8, v232
	v_cmp_lt_i32_e32 vcc, v184, v185
	s_nop 1
	v_cndmask_b32_e32 v184, v232, v184, vcc
	v_lshlrev_b32_e32 v184, 2, v184
	s_nop 1
	v_mov_b32_dpp v184, v169 row_mirror row_mask:0xf bank_mask:0xf
	s_waitcnt lgkmcnt(0)
	v_add_f32_e32 v169, v169, v184
	v_add_f32_e32 v169, 0x358637bd, v169
	v_rsq_f32_e32 v169, v169
	s_nop 0
	v_mul_f32_e32 v202, v219, v169
.LBB0_565:
	v_pk_mul_f32 v[174:175], v[174:175], v[202:203] op_sel_hi:[1,0]
	v_lshlrev_b32_e32 v212, 16, v102
	v_cvt_pk_bf16_f32 v220, v174, v175
	v_pk_mul_f32 v[174:175], v[198:199], v[202:203] op_sel_hi:[1,0]
	v_and_b32_e32 v213, 0xffff0000, v102
	v_cvt_pk_bf16_f32 v221, v174, v175
	v_pk_mul_f32 v[174:175], v[178:179], v[202:203] op_sel_hi:[1,0]
	v_pk_mul_f32 v[178:179], v[150:151], v[214:215]
	v_and_b32_e32 v199, 0xffff0000, v103
	v_pk_fma_f32 v[178:179], v[146:147], v[210:211], v[178:179]
	v_lshlrev_b32_e32 v198, 16, v103
	v_pk_fma_f32 v[178:179], v[154:155], v[208:209], v[178:179]
	v_pk_mul_f32 v[166:167], v[166:167], v[202:203] op_sel_hi:[1,0]
	v_pk_fma_f32 v[178:179], v[158:159], v[212:213], v[178:179]
	v_cvt_pk_bf16_f32 v222, v174, v175
	v_mul_f32_e32 v169, 0xbfb8aa3b, v178
	v_exp_f32_e32 v169, v169
	v_and_b32_e32 v175, 0xffff0000, v104
	v_lshlrev_b32_e32 v174, 16, v104
	v_cvt_pk_bf16_f32 v223, v166, v167
	v_add_f32_e32 v169, 1.0, v169
	v_rcp_f32_e32 v184, v169
	v_mul_f32_e32 v169, 0xbfb8aa3b, v179
	v_exp_f32_e32 v169, v169
	v_and_b32_e32 v167, 0xffff0000, v105
	v_lshlrev_b32_e32 v166, 16, v105
	s_and_b64 vcc, exec, s[38:39]
	v_add_f32_e32 v169, 1.0, v169
	v_rcp_f32_e32 v185, v169
	global_store_dwordx4 v[162:163], v[220:223], off offset:2048
	v_pk_mul_f32 v[178:179], v[178:179], v[184:185]
	v_pk_mul_f32 v[184:185], v[152:153], v[200:201]
	s_nop 0
	v_pk_fma_f32 v[184:185], v[148:149], v[206:207], v[184:185]
	s_nop 0
	v_pk_fma_f32 v[184:185], v[156:157], v[204:205], v[184:185]
	s_nop 0
	v_pk_fma_f32 v[184:185], v[160:161], v[198:199], v[184:185]
	s_nop 0
	v_mul_f32_e32 v169, 0xbfb8aa3b, v184
	v_exp_f32_e32 v169, v169
	s_nop 0
	v_add_f32_e32 v169, 1.0, v169
	v_rcp_f32_e32 v186, v169
	v_mul_f32_e32 v169, 0xbfb8aa3b, v185
	v_exp_f32_e32 v169, v169
	s_nop 0
	v_add_f32_e32 v169, 1.0, v169
	v_rcp_f32_e32 v187, v169
	s_nop 0
	v_pk_mul_f32 v[202:203], v[184:185], v[186:187]
	v_pk_mul_f32 v[184:185], v[134:135], v[176:177]
	s_nop 0
	v_pk_fma_f32 v[184:185], v[130:131], v[196:197], v[184:185]
	s_nop 0
	v_pk_fma_f32 v[184:185], v[138:139], v[180:181], v[184:185]
	s_nop 0
	v_pk_fma_f32 v[184:185], v[142:143], v[174:175], v[184:185]
	s_nop 0
	v_mul_f32_e32 v169, 0xbfb8aa3b, v184
	v_exp_f32_e32 v169, v169
	s_nop 0
	v_add_f32_e32 v169, 1.0, v169
	v_rcp_f32_e32 v186, v169
	v_mul_f32_e32 v169, 0xbfb8aa3b, v185
	v_exp_f32_e32 v169, v169
	s_nop 0
	v_add_f32_e32 v169, 1.0, v169
	v_rcp_f32_e32 v187, v169
	s_nop 0
	v_pk_mul_f32 v[196:197], v[184:185], v[186:187]
	v_pk_mul_f32 v[184:185], v[136:137], v[164:165]
	s_nop 0
	v_pk_fma_f32 v[172:173], v[132:133], v[172:173], v[184:185]
	s_nop 0
	v_pk_fma_f32 v[172:173], v[140:141], v[170:171], v[172:173]
	s_nop 0
	v_pk_fma_f32 v[172:173], v[144:145], v[166:167], v[172:173]
	s_nop 0
	v_mul_f32_e32 v169, 0xbfb8aa3b, v172
	v_exp_f32_e32 v169, v169
	s_nop 0
	v_add_f32_e32 v169, 1.0, v169
	v_rcp_f32_e32 v184, v169
	v_mul_f32_e32 v169, 0xbfb8aa3b, v173
	v_exp_f32_e32 v169, v169
	s_nop 0
	v_add_f32_e32 v169, 1.0, v169
	v_rcp_f32_e32 v185, v169
	s_nop 0
	v_pk_mul_f32 v[172:173], v[172:173], v[184:185]
	s_cbranch_vccnz .LBB0_567
	v_pk_mul_f32 v[168:169], v[178:179], v[178:179]
	v_pk_mul_f32 v[184:185], v[202:203], v[202:203]
	v_add_f32_e32 v168, v168, v169
	v_add_f32_e32 v168, v184, v168
	v_pk_mul_f32 v[186:187], v[196:197], v[196:197]
	v_add_f32_e32 v168, v185, v168
	v_and_b32_e32 v184, 64, v232
	v_add_f32_e32 v168, v186, v168
	v_xor_b32_e32 v169, 1, v232
	v_add_u32_e32 v184, 64, v184
	v_pk_mul_f32 v[206:207], v[172:173], v[172:173]
	v_add_f32_e32 v168, v187, v168
	v_cmp_lt_i32_e32 vcc, v169, v184
	v_add_f32_e32 v168, v206, v168
	v_add_f32_e32 v168, v207, v168
	v_cndmask_b32_e32 v169, v232, v169, vcc
	v_lshlrev_b32_e32 v169, 2, v169
	s_nop 1
	v_mov_b32_dpp v169, v168 quad_perm:[1,0,3,2] row_mask:0xf bank_mask:0xf
	s_waitcnt lgkmcnt(0)
	v_add_f32_e32 v168, v168, v169
	v_xor_b32_e32 v169, 2, v232
	v_cmp_lt_i32_e32 vcc, v169, v184
	s_nop 1
	v_cndmask_b32_e32 v169, v232, v169, vcc
	v_lshlrev_b32_e32 v169, 2, v169
	s_nop 1
	v_mov_b32_dpp v169, v168 quad_perm:[2,3,0,1] row_mask:0xf bank_mask:0xf
	s_waitcnt lgkmcnt(0)
	v_add_f32_e32 v168, v168, v169
	v_xor_b32_e32 v169, 4, v232
	v_cmp_lt_i32_e32 vcc, v169, v184
	s_nop 1
	v_cndmask_b32_e32 v169, v232, v169, vcc
	v_lshlrev_b32_e32 v169, 2, v169
	s_nop 1
	v_mov_b32_dpp v169, v168 row_half_mirror row_mask:0xf bank_mask:0xf
	s_waitcnt lgkmcnt(0)
	v_add_f32_e32 v168, v168, v169
	v_xor_b32_e32 v169, 8, v232
	v_cmp_lt_i32_e32 vcc, v169, v184
	s_nop 1
	v_cndmask_b32_e32 v169, v232, v169, vcc
	v_lshlrev_b32_e32 v169, 2, v169
	s_nop 1
	v_mov_b32_dpp v169, v168 row_mirror row_mask:0xf bank_mask:0xf
	s_waitcnt lgkmcnt(0)
	v_add_f32_e32 v168, v168, v169
	v_add_f32_e32 v168, 0x358637bd, v168
	v_rsq_f32_e32 v168, v168
	s_nop 0
	v_mul_f32_e32 v168, v219, v168
.LBB0_567:
	v_pk_mul_f32 v[178:179], v[178:179], v[168:169] op_sel_hi:[1,0]
	v_mov_b32_e32 v210, 1.0
	v_cvt_pk_bf16_f32 v220, v178, v179
	v_pk_mul_f32 v[178:179], v[202:203], v[168:169] op_sel_hi:[1,0]
	v_lshlrev_b32_e32 v202, 16, v106
	v_cvt_pk_bf16_f32 v221, v178, v179
	v_pk_mul_f32 v[178:179], v[196:197], v[168:169] op_sel_hi:[1,0]
	v_pk_mul_f32 v[168:169], v[172:173], v[168:169] op_sel_hi:[1,0]
	v_pk_mul_f32 v[172:173], v[150:151], v[208:209]
	v_and_b32_e32 v203, 0xffff0000, v106
	v_pk_fma_f32 v[172:173], v[146:147], v[214:215], v[172:173]
	v_and_b32_e32 v197, 0xffff0000, v107
	v_pk_fma_f32 v[172:173], v[154:155], v[212:213], v[172:173]
	v_lshlrev_b32_e32 v196, 16, v107
	v_pk_fma_f32 v[172:173], v[158:159], v[202:203], v[172:173]
	v_cvt_pk_bf16_f32 v222, v178, v179
	v_mul_f32_e32 v184, 0xbfb8aa3b, v172
	v_mul_f32_e32 v185, 0xbfb8aa3b, v173
	v_exp_f32_e32 v184, v184
	v_exp_f32_e32 v185, v185
	v_and_b32_e32 v179, 0xffff0000, v108
	v_lshlrev_b32_e32 v178, 16, v108
	v_add_f32_e32 v184, 1.0, v184
	v_add_f32_e32 v185, 1.0, v185
	v_rcp_f32_e32 v184, v184
	v_rcp_f32_e32 v185, v185
	v_cvt_pk_bf16_f32 v223, v168, v169
	v_and_b32_e32 v169, 0xffff0000, v109
	v_lshlrev_b32_e32 v168, 16, v109
	v_pk_mul_f32 v[172:173], v[172:173], v[184:185]
	v_pk_mul_f32 v[184:185], v[152:153], v[204:205]
	s_and_b64 vcc, exec, s[38:39]
	v_pk_fma_f32 v[184:185], v[148:149], v[200:201], v[184:185]
	v_mov_b32_e32 v206, 1.0
	v_pk_fma_f32 v[184:185], v[156:157], v[198:199], v[184:185]
	global_store_dwordx4 v[162:163], v[220:223], off offset:2304
	v_pk_fma_f32 v[184:185], v[160:161], v[196:197], v[184:185]
	s_nop 0
	v_mul_f32_e32 v186, 0xbfb8aa3b, v184
	v_mul_f32_e32 v187, 0xbfb8aa3b, v185
	v_exp_f32_e32 v186, v186
	v_exp_f32_e32 v187, v187
	v_add_f32_e32 v186, 1.0, v186
	v_add_f32_e32 v187, 1.0, v187
	v_rcp_f32_e32 v186, v186
	v_rcp_f32_e32 v187, v187
	s_nop 0
	v_pk_mul_f32 v[200:201], v[184:185], v[186:187]
	v_pk_mul_f32 v[184:185], v[134:135], v[180:181]
	s_nop 0
	v_pk_fma_f32 v[176:177], v[130:131], v[176:177], v[184:185]
	s_nop 0
	v_pk_fma_f32 v[176:177], v[138:139], v[174:175], v[176:177]
	s_nop 0
	v_pk_fma_f32 v[176:177], v[142:143], v[178:179], v[176:177]
	s_nop 0
	v_mul_f32_e32 v184, 0xbfb8aa3b, v176
	v_mul_f32_e32 v185, 0xbfb8aa3b, v177
	v_exp_f32_e32 v184, v184
	v_exp_f32_e32 v185, v185
	v_add_f32_e32 v184, 1.0, v184
	v_add_f32_e32 v185, 1.0, v185
	v_rcp_f32_e32 v184, v184
	v_rcp_f32_e32 v185, v185
	s_nop 0
	v_pk_mul_f32 v[176:177], v[176:177], v[184:185]
	v_pk_mul_f32 v[184:185], v[136:137], v[170:171]
	s_nop 0
	v_pk_fma_f32 v[164:165], v[132:133], v[164:165], v[184:185]
	s_nop 0
	v_pk_fma_f32 v[164:165], v[140:141], v[166:167], v[164:165]
	s_nop 0
	v_pk_fma_f32 v[164:165], v[144:145], v[168:169], v[164:165]
	s_nop 0
	v_mul_f32_e32 v184, 0xbfb8aa3b, v164
	v_mul_f32_e32 v185, 0xbfb8aa3b, v165
	v_exp_f32_e32 v184, v184
	v_exp_f32_e32 v185, v185
	v_add_f32_e32 v184, 1.0, v184
	v_add_f32_e32 v185, 1.0, v185
	v_rcp_f32_e32 v184, v184
	v_rcp_f32_e32 v185, v185
	s_nop 0
	v_pk_mul_f32 v[164:165], v[164:165], v[184:185]
	s_cbranch_vccnz .LBB0_569
	v_pk_mul_f32 v[184:185], v[172:173], v[172:173]
	v_pk_mul_f32 v[186:187], v[200:201], v[200:201]
	v_add_f32_e32 v184, v184, v185
	v_add_f32_e32 v184, v186, v184
	v_pk_mul_f32 v[206:207], v[176:177], v[176:177]
	v_add_f32_e32 v184, v187, v184
	v_and_b32_e32 v186, 64, v232
	v_add_f32_e32 v184, v206, v184
	v_xor_b32_e32 v185, 1, v232
	v_add_u32_e32 v186, 64, v186
	v_pk_mul_f32 v[214:215], v[164:165], v[164:165]
	v_add_f32_e32 v184, v207, v184
	v_cmp_lt_i32_e32 vcc, v185, v186
	v_add_f32_e32 v184, v214, v184
	v_add_f32_e32 v184, v215, v184
	v_cndmask_b32_e32 v185, v232, v185, vcc
	v_lshlrev_b32_e32 v185, 2, v185
	s_nop 1
	v_mov_b32_dpp v185, v184 quad_perm:[1,0,3,2] row_mask:0xf bank_mask:0xf
	s_waitcnt lgkmcnt(0)
	v_add_f32_e32 v184, v184, v185
	v_xor_b32_e32 v185, 2, v232
	v_cmp_lt_i32_e32 vcc, v185, v186
	s_nop 1
	v_cndmask_b32_e32 v185, v232, v185, vcc
	v_lshlrev_b32_e32 v185, 2, v185
	s_nop 1
	v_mov_b32_dpp v185, v184 quad_perm:[2,3,0,1] row_mask:0xf bank_mask:0xf
	s_waitcnt lgkmcnt(0)
	v_add_f32_e32 v184, v184, v185
	v_xor_b32_e32 v185, 4, v232
	v_cmp_lt_i32_e32 vcc, v185, v186
	s_nop 1
	v_cndmask_b32_e32 v185, v232, v185, vcc
	v_lshlrev_b32_e32 v185, 2, v185
	s_nop 1
	v_mov_b32_dpp v185, v184 row_half_mirror row_mask:0xf bank_mask:0xf
	s_waitcnt lgkmcnt(0)
	v_add_f32_e32 v184, v184, v185
	v_xor_b32_e32 v185, 8, v232
	v_cmp_lt_i32_e32 vcc, v185, v186
	s_nop 1
	v_cndmask_b32_e32 v185, v232, v185, vcc
	v_lshlrev_b32_e32 v185, 2, v185
	s_nop 1
	v_mov_b32_dpp v185, v184 row_mirror row_mask:0xf bank_mask:0xf
	s_waitcnt lgkmcnt(0)
	v_add_f32_e32 v184, v184, v185
	v_add_f32_e32 v184, 0x358637bd, v184
	v_rsq_f32_e32 v184, v184
	s_nop 0
	v_mul_f32_e32 v206, v219, v184
.LBB0_569:
	v_pk_mul_f32 v[172:173], v[172:173], v[206:207] op_sel_hi:[1,0]
	v_pk_mul_f32 v[184:185], v[150:151], v[212:213]
	v_cvt_pk_bf16_f32 v214, v172, v173
	v_pk_mul_f32 v[172:173], v[200:201], v[206:207] op_sel_hi:[1,0]
	v_pk_fma_f32 v[184:185], v[146:147], v[208:209], v[184:185]
	v_cvt_pk_bf16_f32 v215, v172, v173
	v_pk_mul_f32 v[172:173], v[176:177], v[206:207] op_sel_hi:[1,0]
	v_pk_mul_f32 v[164:165], v[164:165], v[206:207] op_sel_hi:[1,0]
	v_lshlrev_b32_e32 v206, 16, v110
	v_and_b32_e32 v207, 0xffff0000, v110
	v_pk_fma_f32 v[184:185], v[154:155], v[202:203], v[184:185]
	v_and_b32_e32 v177, 0xffff0000, v111
	v_pk_fma_f32 v[184:185], v[158:159], v[206:207], v[184:185]
	v_lshlrev_b32_e32 v176, 16, v111
	v_mul_f32_e32 v186, 0xbfb8aa3b, v184
	v_mul_f32_e32 v187, 0xbfb8aa3b, v185
	v_exp_f32_e32 v186, v186
	v_exp_f32_e32 v187, v187
	v_cvt_pk_bf16_f32 v216, v172, v173
	v_and_b32_e32 v173, 0xffff0000, v112
	v_add_f32_e32 v186, 1.0, v186
	v_add_f32_e32 v187, 1.0, v187
	v_rcp_f32_e32 v186, v186
	v_rcp_f32_e32 v187, v187
	v_lshlrev_b32_e32 v172, 16, v112
	v_cvt_pk_bf16_f32 v217, v164, v165
	v_and_b32_e32 v165, 0xffff0000, v113
	v_pk_mul_f32 v[200:201], v[184:185], v[186:187]
	v_pk_mul_f32 v[184:185], v[152:153], v[198:199]
	v_lshlrev_b32_e32 v164, 16, v113
	v_pk_fma_f32 v[184:185], v[148:149], v[204:205], v[184:185]
	s_and_b64 vcc, exec, s[38:39]
	v_pk_fma_f32 v[184:185], v[156:157], v[196:197], v[184:185]
	global_store_dwordx4 v[162:163], v[214:217], off offset:2560
	v_pk_fma_f32 v[184:185], v[160:161], v[176:177], v[184:185]
	s_nop 0
	v_mul_f32_e32 v186, 0xbfb8aa3b, v184
	v_mul_f32_e32 v187, 0xbfb8aa3b, v185
	v_exp_f32_e32 v186, v186
	v_exp_f32_e32 v187, v187
	v_add_f32_e32 v186, 1.0, v186
	v_add_f32_e32 v187, 1.0, v187
	v_rcp_f32_e32 v186, v186
	v_rcp_f32_e32 v187, v187
	s_nop 0
	v_pk_mul_f32 v[204:205], v[184:185], v[186:187]
	v_pk_mul_f32 v[184:185], v[134:135], v[174:175]
	s_nop 0
	v_pk_fma_f32 v[180:181], v[130:131], v[180:181], v[184:185]
	s_nop 0
	v_pk_fma_f32 v[180:181], v[138:139], v[178:179], v[180:181]
	s_nop 0
	v_pk_fma_f32 v[180:181], v[142:143], v[172:173], v[180:181]
	s_nop 0
	v_mul_f32_e32 v184, 0xbfb8aa3b, v180
	v_mul_f32_e32 v185, 0xbfb8aa3b, v181
	v_exp_f32_e32 v184, v184
	v_exp_f32_e32 v185, v185
	v_add_f32_e32 v184, 1.0, v184
	v_add_f32_e32 v185, 1.0, v185
	v_rcp_f32_e32 v184, v184
	v_rcp_f32_e32 v185, v185
	s_nop 0
	v_pk_mul_f32 v[180:181], v[180:181], v[184:185]
	v_pk_mul_f32 v[184:185], v[136:137], v[166:167]
	s_nop 0
	v_pk_fma_f32 v[170:171], v[132:133], v[170:171], v[184:185]
	s_nop 0
	v_pk_fma_f32 v[170:171], v[140:141], v[168:169], v[170:171]
	s_nop 0
	v_pk_fma_f32 v[170:171], v[144:145], v[164:165], v[170:171]
	s_nop 0
	v_mul_f32_e32 v184, 0xbfb8aa3b, v170
	v_mul_f32_e32 v185, 0xbfb8aa3b, v171
	v_exp_f32_e32 v184, v184
	v_exp_f32_e32 v185, v185
	v_add_f32_e32 v184, 1.0, v184
	v_add_f32_e32 v185, 1.0, v185
	v_rcp_f32_e32 v184, v184
	v_rcp_f32_e32 v185, v185
	s_nop 0
	v_pk_mul_f32 v[170:171], v[170:171], v[184:185]
	s_cbranch_vccnz .LBB0_571
	v_pk_mul_f32 v[184:185], v[200:201], v[200:201]
	v_pk_mul_f32 v[186:187], v[204:205], v[204:205]
	v_add_f32_e32 v184, v184, v185
	v_add_f32_e32 v184, v186, v184
	v_pk_mul_f32 v[208:209], v[180:181], v[180:181]
	v_add_f32_e32 v184, v187, v184
	v_and_b32_e32 v186, 64, v232
	v_add_f32_e32 v184, v208, v184
	v_xor_b32_e32 v185, 1, v232
	v_add_u32_e32 v186, 64, v186
	v_pk_mul_f32 v[210:211], v[170:171], v[170:171]
	v_add_f32_e32 v184, v209, v184
	v_cmp_lt_i32_e32 vcc, v185, v186
	v_add_f32_e32 v184, v210, v184
	v_add_f32_e32 v184, v211, v184
	v_cndmask_b32_e32 v185, v232, v185, vcc
	v_lshlrev_b32_e32 v185, 2, v185
	s_nop 1
	v_mov_b32_dpp v185, v184 quad_perm:[1,0,3,2] row_mask:0xf bank_mask:0xf
	s_waitcnt lgkmcnt(0)
	v_add_f32_e32 v184, v184, v185
	v_xor_b32_e32 v185, 2, v232
	v_cmp_lt_i32_e32 vcc, v185, v186
	s_nop 1
	v_cndmask_b32_e32 v185, v232, v185, vcc
	v_lshlrev_b32_e32 v185, 2, v185
	s_nop 1
	v_mov_b32_dpp v185, v184 quad_perm:[2,3,0,1] row_mask:0xf bank_mask:0xf
	s_waitcnt lgkmcnt(0)
	v_add_f32_e32 v184, v184, v185
	v_xor_b32_e32 v185, 4, v232
	v_cmp_lt_i32_e32 vcc, v185, v186
	s_nop 1
	v_cndmask_b32_e32 v185, v232, v185, vcc
	v_lshlrev_b32_e32 v185, 2, v185
	s_nop 1
	v_mov_b32_dpp v185, v184 row_half_mirror row_mask:0xf bank_mask:0xf
	s_waitcnt lgkmcnt(0)
	v_add_f32_e32 v184, v184, v185
	v_xor_b32_e32 v185, 8, v232
	v_cmp_lt_i32_e32 vcc, v185, v186
	s_nop 1
	v_cndmask_b32_e32 v185, v232, v185, vcc
	v_lshlrev_b32_e32 v185, 2, v185
	s_nop 1
	v_mov_b32_dpp v185, v184 row_mirror row_mask:0xf bank_mask:0xf
	s_waitcnt lgkmcnt(0)
	v_add_f32_e32 v184, v184, v185
	v_add_f32_e32 v184, 0x358637bd, v184
	v_rsq_f32_e32 v184, v184
	s_nop 0
	v_mul_f32_e32 v210, v219, v184
.LBB0_571:
	v_pk_mul_f32 v[184:185], v[200:201], v[210:211] op_sel_hi:[1,0]
	v_and_b32_e32 v201, 0xffff0000, v115
	v_cvt_pk_bf16_f32 v214, v184, v185
	v_pk_mul_f32 v[184:185], v[204:205], v[210:211] op_sel_hi:[1,0]
	v_lshlrev_b32_e32 v204, 16, v114
	v_cvt_pk_bf16_f32 v215, v184, v185
	v_pk_mul_f32 v[184:185], v[150:151], v[202:203]
	v_and_b32_e32 v205, 0xffff0000, v114
	v_pk_fma_f32 v[184:185], v[146:147], v[212:213], v[184:185]
	v_lshlrev_b32_e32 v200, 16, v115
	v_pk_fma_f32 v[184:185], v[154:155], v[206:207], v[184:185]
	v_pk_mul_f32 v[180:181], v[180:181], v[210:211] op_sel_hi:[1,0]
	v_pk_fma_f32 v[184:185], v[158:159], v[204:205], v[184:185]
	v_cvt_pk_bf16_f32 v216, v180, v181
	v_mul_f32_e32 v186, 0xbfb8aa3b, v184
	v_mul_f32_e32 v187, 0xbfb8aa3b, v185
	v_exp_f32_e32 v186, v186
	v_exp_f32_e32 v187, v187
	v_and_b32_e32 v181, 0xffff0000, v116
	v_lshlrev_b32_e32 v180, 16, v116
	v_add_f32_e32 v186, 1.0, v186
	v_add_f32_e32 v187, 1.0, v187
	v_rcp_f32_e32 v186, v186
	v_rcp_f32_e32 v187, v187
	v_pk_mul_f32 v[170:171], v[170:171], v[210:211] op_sel_hi:[1,0]
	v_mov_b32_e32 v210, 1.0
	v_cvt_pk_bf16_f32 v217, v170, v171
	v_pk_mul_f32 v[208:209], v[184:185], v[186:187]
	v_pk_mul_f32 v[184:185], v[152:153], v[196:197]
	v_and_b32_e32 v171, 0xffff0000, v117
	v_pk_fma_f32 v[184:185], v[148:149], v[198:199], v[184:185]
	v_lshlrev_b32_e32 v170, 16, v117
	v_pk_fma_f32 v[184:185], v[156:157], v[176:177], v[184:185]
	s_and_b64 vcc, exec, s[38:39]
	v_pk_fma_f32 v[184:185], v[160:161], v[200:201], v[184:185]
	v_mov_b32_e32 v212, 1.0
	v_mul_f32_e32 v186, 0xbfb8aa3b, v184
	v_mul_f32_e32 v187, 0xbfb8aa3b, v185
	v_exp_f32_e32 v186, v186
	v_exp_f32_e32 v187, v187
	global_store_dwordx4 v[162:163], v[214:217], off offset:2816
	v_add_f32_e32 v186, 1.0, v186
	v_add_f32_e32 v187, 1.0, v187
	v_rcp_f32_e32 v186, v186
	v_rcp_f32_e32 v187, v187
	s_nop 0
	v_pk_mul_f32 v[198:199], v[184:185], v[186:187]
	v_pk_mul_f32 v[184:185], v[134:135], v[178:179]
	s_nop 0
	v_pk_fma_f32 v[174:175], v[130:131], v[174:175], v[184:185]
	s_nop 0
	v_pk_fma_f32 v[174:175], v[138:139], v[172:173], v[174:175]
	s_nop 0
	v_pk_fma_f32 v[174:175], v[142:143], v[180:181], v[174:175]
	s_nop 0
	v_mul_f32_e32 v184, 0xbfb8aa3b, v174
	v_mul_f32_e32 v185, 0xbfb8aa3b, v175
	v_exp_f32_e32 v184, v184
	v_exp_f32_e32 v185, v185
	v_add_f32_e32 v184, 1.0, v184
	v_add_f32_e32 v185, 1.0, v185
	v_rcp_f32_e32 v184, v184
	v_rcp_f32_e32 v185, v185
	s_nop 0
	v_pk_mul_f32 v[174:175], v[174:175], v[184:185]
	v_pk_mul_f32 v[184:185], v[136:137], v[168:169]
	s_nop 0
	v_pk_fma_f32 v[166:167], v[132:133], v[166:167], v[184:185]
	s_nop 0
	v_pk_fma_f32 v[166:167], v[140:141], v[164:165], v[166:167]
	s_nop 0
	v_pk_fma_f32 v[166:167], v[144:145], v[170:171], v[166:167]
	s_nop 0
	v_mul_f32_e32 v184, 0xbfb8aa3b, v166
	v_mul_f32_e32 v185, 0xbfb8aa3b, v167
	v_exp_f32_e32 v184, v184
	v_exp_f32_e32 v185, v185
	v_add_f32_e32 v184, 1.0, v184
	v_add_f32_e32 v185, 1.0, v185
	v_rcp_f32_e32 v184, v184
	v_rcp_f32_e32 v185, v185
	s_nop 0
	v_pk_mul_f32 v[166:167], v[166:167], v[184:185]
	s_cbranch_vccnz .LBB0_573
	v_pk_mul_f32 v[184:185], v[208:209], v[208:209]
	v_pk_mul_f32 v[186:187], v[198:199], v[198:199]
	v_add_f32_e32 v184, v184, v185
	v_add_f32_e32 v184, v186, v184
	v_pk_mul_f32 v[212:213], v[174:175], v[174:175]
	v_add_f32_e32 v184, v187, v184
	v_and_b32_e32 v186, 64, v232
	v_add_f32_e32 v184, v212, v184
	v_xor_b32_e32 v185, 1, v232
	v_add_u32_e32 v186, 64, v186
	v_pk_mul_f32 v[214:215], v[166:167], v[166:167]
	v_add_f32_e32 v184, v213, v184
	v_cmp_lt_i32_e32 vcc, v185, v186
	v_add_f32_e32 v184, v214, v184
	v_add_f32_e32 v184, v215, v184
	v_cndmask_b32_e32 v185, v232, v185, vcc
	v_lshlrev_b32_e32 v185, 2, v185
	s_nop 1
	v_mov_b32_dpp v185, v184 quad_perm:[1,0,3,2] row_mask:0xf bank_mask:0xf
	s_waitcnt lgkmcnt(0)
	v_add_f32_e32 v184, v184, v185
	v_xor_b32_e32 v185, 2, v232
	v_cmp_lt_i32_e32 vcc, v185, v186
	s_nop 1
	v_cndmask_b32_e32 v185, v232, v185, vcc
	v_lshlrev_b32_e32 v185, 2, v185
	s_nop 1
	v_mov_b32_dpp v185, v184 quad_perm:[2,3,0,1] row_mask:0xf bank_mask:0xf
	s_waitcnt lgkmcnt(0)
	v_add_f32_e32 v184, v184, v185
	v_xor_b32_e32 v185, 4, v232
	v_cmp_lt_i32_e32 vcc, v185, v186
	s_nop 1
	v_cndmask_b32_e32 v185, v232, v185, vcc
	v_lshlrev_b32_e32 v185, 2, v185
	s_nop 1
	v_mov_b32_dpp v185, v184 row_half_mirror row_mask:0xf bank_mask:0xf
	s_waitcnt lgkmcnt(0)
	v_add_f32_e32 v184, v184, v185
	v_xor_b32_e32 v185, 8, v232
	v_cmp_lt_i32_e32 vcc, v185, v186
	s_nop 1
	v_cndmask_b32_e32 v185, v232, v185, vcc
	v_lshlrev_b32_e32 v185, 2, v185
	s_nop 1
	v_mov_b32_dpp v185, v184 row_mirror row_mask:0xf bank_mask:0xf
	s_waitcnt lgkmcnt(0)
	v_add_f32_e32 v184, v184, v185
	v_add_f32_e32 v184, 0x358637bd, v184
	v_rsq_f32_e32 v184, v184
	s_nop 0
	v_mul_f32_e32 v212, v219, v184
.LBB0_573:
	v_pk_mul_f32 v[184:185], v[208:209], v[212:213] op_sel_hi:[1,0]
	v_lshlrev_b32_e32 v208, 16, v118
	v_cvt_pk_bf16_f32 v214, v184, v185
	v_pk_mul_f32 v[184:185], v[198:199], v[212:213] op_sel_hi:[1,0]
	v_and_b32_e32 v209, 0xffff0000, v118
	v_cvt_pk_bf16_f32 v215, v184, v185
	v_pk_mul_f32 v[184:185], v[150:151], v[206:207]
	v_and_b32_e32 v199, 0xffff0000, v119
	v_pk_fma_f32 v[184:185], v[146:147], v[202:203], v[184:185]
	v_lshlrev_b32_e32 v198, 16, v119
	v_pk_fma_f32 v[184:185], v[154:155], v[204:205], v[184:185]
	v_pk_mul_f32 v[174:175], v[174:175], v[212:213] op_sel_hi:[1,0]
	v_pk_fma_f32 v[184:185], v[158:159], v[208:209], v[184:185]
	v_cvt_pk_bf16_f32 v216, v174, v175
	v_mul_f32_e32 v186, 0xbfb8aa3b, v184
	v_mul_f32_e32 v187, 0xbfb8aa3b, v185
	v_exp_f32_e32 v186, v186
	v_exp_f32_e32 v187, v187
	v_and_b32_e32 v175, 0xffff0000, v120
	v_lshlrev_b32_e32 v174, 16, v120
	v_add_f32_e32 v186, 1.0, v186
	v_add_f32_e32 v187, 1.0, v187
	v_rcp_f32_e32 v186, v186
	v_rcp_f32_e32 v187, v187
	v_pk_mul_f32 v[166:167], v[166:167], v[212:213] op_sel_hi:[1,0]
	s_and_b64 vcc, exec, s[38:39]
	v_cvt_pk_bf16_f32 v217, v166, v167
	v_pk_mul_f32 v[202:203], v[184:185], v[186:187]
	v_pk_mul_f32 v[184:185], v[152:153], v[176:177]
	v_and_b32_e32 v167, 0xffff0000, v121
	v_pk_fma_f32 v[184:185], v[148:149], v[196:197], v[184:185]
	v_lshlrev_b32_e32 v166, 16, v121
	v_pk_fma_f32 v[184:185], v[156:157], v[200:201], v[184:185]
	global_store_dwordx4 v[162:163], v[214:217], off offset:3072
	v_pk_fma_f32 v[184:185], v[160:161], v[198:199], v[184:185]
	s_nop 0
	v_mul_f32_e32 v186, 0xbfb8aa3b, v184
	v_mul_f32_e32 v187, 0xbfb8aa3b, v185
	v_exp_f32_e32 v186, v186
	v_exp_f32_e32 v187, v187
	v_add_f32_e32 v186, 1.0, v186
	v_add_f32_e32 v187, 1.0, v187
	v_rcp_f32_e32 v186, v186
	v_rcp_f32_e32 v187, v187
	s_nop 0
	v_pk_mul_f32 v[196:197], v[184:185], v[186:187]
	v_pk_mul_f32 v[184:185], v[134:135], v[172:173]
	s_nop 0
	v_pk_fma_f32 v[178:179], v[130:131], v[178:179], v[184:185]
	s_nop 0
	v_pk_fma_f32 v[178:179], v[138:139], v[180:181], v[178:179]
	s_nop 0
	v_pk_fma_f32 v[178:179], v[142:143], v[174:175], v[178:179]
	s_nop 0
	v_mul_f32_e32 v184, 0xbfb8aa3b, v178
	v_mul_f32_e32 v185, 0xbfb8aa3b, v179
	v_exp_f32_e32 v184, v184
	v_exp_f32_e32 v185, v185
	v_add_f32_e32 v184, 1.0, v184
	v_add_f32_e32 v185, 1.0, v185
	v_rcp_f32_e32 v184, v184
	v_rcp_f32_e32 v185, v185
	s_nop 0
	v_pk_mul_f32 v[178:179], v[178:179], v[184:185]
	v_pk_mul_f32 v[184:185], v[136:137], v[164:165]
	s_nop 0
	v_pk_fma_f32 v[168:169], v[132:133], v[168:169], v[184:185]
	s_nop 0
	v_pk_fma_f32 v[168:169], v[140:141], v[170:171], v[168:169]
	s_nop 0
	v_pk_fma_f32 v[168:169], v[144:145], v[166:167], v[168:169]
	s_nop 0
	v_mul_f32_e32 v184, 0xbfb8aa3b, v168
	v_mul_f32_e32 v185, 0xbfb8aa3b, v169
	v_exp_f32_e32 v184, v184
	v_exp_f32_e32 v185, v185
	v_add_f32_e32 v184, 1.0, v184
	v_add_f32_e32 v185, 1.0, v185
	v_rcp_f32_e32 v184, v184
	v_rcp_f32_e32 v185, v185
	s_nop 0
	v_pk_mul_f32 v[168:169], v[168:169], v[184:185]
	s_cbranch_vccnz .LBB0_575
	v_pk_mul_f32 v[184:185], v[202:203], v[202:203]
	v_pk_mul_f32 v[186:187], v[196:197], v[196:197]
	v_add_f32_e32 v184, v184, v185
	v_add_f32_e32 v184, v186, v184
	v_pk_mul_f32 v[210:211], v[178:179], v[178:179]
	v_add_f32_e32 v184, v187, v184
	v_and_b32_e32 v186, 64, v232
	v_add_f32_e32 v184, v210, v184
	v_xor_b32_e32 v185, 1, v232
	v_add_u32_e32 v186, 64, v186
	v_pk_mul_f32 v[212:213], v[168:169], v[168:169]
	v_add_f32_e32 v184, v211, v184
	v_cmp_lt_i32_e32 vcc, v185, v186
	v_add_f32_e32 v184, v212, v184
	v_add_f32_e32 v184, v213, v184
	v_cndmask_b32_e32 v185, v232, v185, vcc
	v_lshlrev_b32_e32 v185, 2, v185
	s_nop 1
	v_mov_b32_dpp v185, v184 quad_perm:[1,0,3,2] row_mask:0xf bank_mask:0xf
	s_waitcnt lgkmcnt(0)
	v_add_f32_e32 v184, v184, v185
	v_xor_b32_e32 v185, 2, v232
	v_cmp_lt_i32_e32 vcc, v185, v186
	s_nop 1
	v_cndmask_b32_e32 v185, v232, v185, vcc
	v_lshlrev_b32_e32 v185, 2, v185
	s_nop 1
	v_mov_b32_dpp v185, v184 quad_perm:[2,3,0,1] row_mask:0xf bank_mask:0xf
	s_waitcnt lgkmcnt(0)
	v_add_f32_e32 v184, v184, v185
	v_xor_b32_e32 v185, 4, v232
	v_cmp_lt_i32_e32 vcc, v185, v186
	s_nop 1
	v_cndmask_b32_e32 v185, v232, v185, vcc
	v_lshlrev_b32_e32 v185, 2, v185
	s_nop 1
	v_mov_b32_dpp v185, v184 row_half_mirror row_mask:0xf bank_mask:0xf
	s_waitcnt lgkmcnt(0)
	v_add_f32_e32 v184, v184, v185
	v_xor_b32_e32 v185, 8, v232
	v_cmp_lt_i32_e32 vcc, v185, v186
	s_nop 1
	v_cndmask_b32_e32 v185, v232, v185, vcc
	v_lshlrev_b32_e32 v185, 2, v185
	s_nop 1
	v_mov_b32_dpp v185, v184 row_mirror row_mask:0xf bank_mask:0xf
	s_waitcnt lgkmcnt(0)
	v_add_f32_e32 v184, v184, v185
	v_add_f32_e32 v184, 0x358637bd, v184
	v_rsq_f32_e32 v184, v184
	s_nop 0
	v_mul_f32_e32 v210, v219, v184
.LBB0_575:
	v_pk_mul_f32 v[168:169], v[168:169], v[210:211] op_sel_hi:[1,0]
	v_pk_mul_f32 v[184:185], v[202:203], v[210:211] op_sel_hi:[1,0]
	v_cvt_pk_bf16_f32 v215, v168, v169
	v_pk_mul_f32 v[168:169], v[150:151], v[204:205]
	v_cvt_pk_bf16_f32 v212, v184, v185
	v_pk_fma_f32 v[168:169], v[146:147], v[206:207], v[168:169]
	v_pk_mul_f32 v[184:185], v[196:197], v[210:211] op_sel_hi:[1,0]
	v_pk_mul_f32 v[178:179], v[178:179], v[210:211] op_sel_hi:[1,0]
	v_lshlrev_b32_e32 v210, 16, v122
	v_and_b32_e32 v211, 0xffff0000, v122
	v_pk_fma_f32 v[168:169], v[154:155], v[208:209], v[168:169]
	v_cvt_pk_bf16_f32 v213, v184, v185
	v_pk_fma_f32 v[184:185], v[158:159], v[210:211], v[168:169]
	v_and_b32_e32 v203, 0xffff0000, v123
	v_mul_f32_e32 v168, 0xbfb8aa3b, v184
	v_exp_f32_e32 v169, v168
	v_lshlrev_b32_e32 v202, 16, v123
	v_and_b32_e32 v197, 0xffff0000, v124
	v_lshlrev_b32_e32 v196, 16, v124
	v_add_f32_e32 v169, 1.0, v169
	v_rcp_f32_e32 v186, v169
	v_mul_f32_e32 v169, 0xbfb8aa3b, v185
	v_exp_f32_e32 v169, v169
	v_cvt_pk_bf16_f32 v214, v178, v179
	v_and_b32_e32 v179, 0xffff0000, v125
	v_lshlrev_b32_e32 v178, 16, v125
	v_add_f32_e32 v169, 1.0, v169
	v_rcp_f32_e32 v187, v169
	global_store_dwordx4 v[162:163], v[212:215], off offset:3328
	v_mov_b32_e32 v168, 1.0
	s_and_b64 vcc, exec, s[38:39]
	v_pk_mul_f32 v[206:207], v[184:185], v[186:187]
	v_pk_mul_f32 v[184:185], v[152:153], v[200:201]
	v_mov_b32_e32 v212, 1.0
	v_pk_fma_f32 v[176:177], v[148:149], v[176:177], v[184:185]
	s_nop 0
	v_pk_fma_f32 v[176:177], v[156:157], v[198:199], v[176:177]
	s_nop 0
	v_pk_fma_f32 v[176:177], v[160:161], v[202:203], v[176:177]
	s_nop 0
	v_mul_f32_e32 v169, 0xbfb8aa3b, v176
	v_exp_f32_e32 v169, v169
	s_nop 0
	v_add_f32_e32 v169, 1.0, v169
	v_rcp_f32_e32 v184, v169
	v_mul_f32_e32 v169, 0xbfb8aa3b, v177
	v_exp_f32_e32 v169, v169
	s_nop 0
	v_add_f32_e32 v169, 1.0, v169
	v_rcp_f32_e32 v185, v169
	s_nop 0
	v_pk_mul_f32 v[176:177], v[176:177], v[184:185]
	v_pk_mul_f32 v[184:185], v[134:135], v[180:181]
	s_nop 0
	v_pk_fma_f32 v[172:173], v[130:131], v[172:173], v[184:185]
	s_nop 0
	v_pk_fma_f32 v[172:173], v[138:139], v[174:175], v[172:173]
	s_nop 0
	v_pk_fma_f32 v[172:173], v[142:143], v[196:197], v[172:173]
	s_nop 0
	v_mul_f32_e32 v169, 0xbfb8aa3b, v172
	v_exp_f32_e32 v169, v169
	s_nop 0
	v_add_f32_e32 v169, 1.0, v169
	v_rcp_f32_e32 v184, v169
	v_mul_f32_e32 v169, 0xbfb8aa3b, v173
	v_exp_f32_e32 v169, v169
	s_nop 0
	v_add_f32_e32 v169, 1.0, v169
	v_rcp_f32_e32 v185, v169
	s_nop 0
	v_pk_mul_f32 v[172:173], v[172:173], v[184:185]
	v_pk_mul_f32 v[184:185], v[136:137], v[170:171]
	s_nop 0
	v_pk_fma_f32 v[164:165], v[132:133], v[164:165], v[184:185]
	s_nop 0
	v_pk_fma_f32 v[164:165], v[140:141], v[166:167], v[164:165]
	s_nop 0
	v_pk_fma_f32 v[164:165], v[144:145], v[178:179], v[164:165]
	s_nop 0
	v_mul_f32_e32 v169, 0xbfb8aa3b, v164
	v_exp_f32_e32 v169, v169
	s_nop 0
	v_add_f32_e32 v169, 1.0, v169
	v_rcp_f32_e32 v184, v169
	v_mul_f32_e32 v169, 0xbfb8aa3b, v165
	v_exp_f32_e32 v169, v169
	s_nop 0
	v_add_f32_e32 v169, 1.0, v169
	v_rcp_f32_e32 v185, v169
	s_nop 0
	v_pk_mul_f32 v[164:165], v[164:165], v[184:185]
	s_cbranch_vccnz .LBB0_577
	v_pk_mul_f32 v[184:185], v[206:207], v[206:207]
	v_pk_mul_f32 v[186:187], v[176:177], v[176:177]
	v_add_f32_e32 v169, v184, v185
	v_add_f32_e32 v169, v186, v169
	v_pk_mul_f32 v[212:213], v[172:173], v[172:173]
	v_add_f32_e32 v169, v187, v169
	v_and_b32_e32 v185, 64, v232
	v_add_f32_e32 v169, v212, v169
	v_xor_b32_e32 v184, 1, v232
	v_add_u32_e32 v185, 64, v185
	v_pk_mul_f32 v[214:215], v[164:165], v[164:165]
	v_add_f32_e32 v169, v213, v169
	v_cmp_lt_i32_e32 vcc, v184, v185
	v_add_f32_e32 v169, v214, v169
	v_add_f32_e32 v169, v215, v169
	v_cndmask_b32_e32 v184, v232, v184, vcc
	v_lshlrev_b32_e32 v184, 2, v184
	s_nop 1
	v_mov_b32_dpp v184, v169 quad_perm:[1,0,3,2] row_mask:0xf bank_mask:0xf
	s_waitcnt lgkmcnt(0)
	v_add_f32_e32 v169, v169, v184
	v_xor_b32_e32 v184, 2, v232
	v_cmp_lt_i32_e32 vcc, v184, v185
	s_nop 1
	v_cndmask_b32_e32 v184, v232, v184, vcc
	v_lshlrev_b32_e32 v184, 2, v184
	s_nop 1
	v_mov_b32_dpp v184, v169 quad_perm:[2,3,0,1] row_mask:0xf bank_mask:0xf
	s_waitcnt lgkmcnt(0)
	v_add_f32_e32 v169, v169, v184
	v_xor_b32_e32 v184, 4, v232
	v_cmp_lt_i32_e32 vcc, v184, v185
	s_nop 1
	v_cndmask_b32_e32 v184, v232, v184, vcc
	v_lshlrev_b32_e32 v184, 2, v184
	s_nop 1
	v_mov_b32_dpp v184, v169 row_half_mirror row_mask:0xf bank_mask:0xf
	s_waitcnt lgkmcnt(0)
	v_add_f32_e32 v169, v169, v184
	v_xor_b32_e32 v184, 8, v232
	v_cmp_lt_i32_e32 vcc, v184, v185
	s_nop 1
	v_cndmask_b32_e32 v184, v232, v184, vcc
	v_lshlrev_b32_e32 v184, 2, v184
	s_nop 1
	v_mov_b32_dpp v184, v169 row_mirror row_mask:0xf bank_mask:0xf
	s_waitcnt lgkmcnt(0)
	v_add_f32_e32 v169, v169, v184
	v_add_f32_e32 v169, 0x358637bd, v169
	v_rsq_f32_e32 v169, v169
	s_nop 0
	v_mul_f32_e32 v212, v219, v169
.LBB0_577:
	v_pk_mul_f32 v[150:151], v[150:151], v[208:209]
	v_pk_mul_f32 v[164:165], v[164:165], v[212:213] op_sel_hi:[1,0]
	v_pk_fma_f32 v[146:147], v[146:147], v[204:205], v[150:151]
	v_cvt_pk_bf16_f32 v217, v164, v165
	v_lshlrev_b32_e32 v164, 16, v126
	v_and_b32_e32 v165, 0xffff0000, v126
	v_pk_fma_f32 v[146:147], v[154:155], v[210:211], v[146:147]
	v_pk_mul_f32 v[152:153], v[152:153], v[198:199]
	v_pk_fma_f32 v[146:147], v[158:159], v[164:165], v[146:147]
	v_pk_fma_f32 v[148:149], v[148:149], v[200:201], v[152:153]
	v_mul_f32_e32 v150, 0xbfb8aa3b, v146
	v_mul_f32_e32 v151, 0xbfb8aa3b, v147
	v_exp_f32_e32 v150, v150
	v_exp_f32_e32 v151, v151
	v_and_b32_e32 v155, 0xffff0000, v127
	v_lshlrev_b32_e32 v154, 16, v127
	v_pk_fma_f32 v[148:149], v[156:157], v[202:203], v[148:149]
	v_add_f32_e32 v150, 1.0, v150
	v_pk_fma_f32 v[148:149], v[160:161], v[154:155], v[148:149]
	v_add_f32_e32 v151, 1.0, v151
	v_mul_f32_e32 v152, 0xbfb8aa3b, v148
	v_mul_f32_e32 v153, 0xbfb8aa3b, v149
	v_rcp_f32_e32 v150, v150
	v_rcp_f32_e32 v151, v151
	v_exp_f32_e32 v152, v152
	v_exp_f32_e32 v153, v153
	v_pk_mul_f32 v[134:135], v[134:135], v[174:175]
	v_pk_mul_f32 v[136:137], v[136:137], v[166:167]
	v_pk_fma_f32 v[130:131], v[130:131], v[180:181], v[134:135]
	v_pk_fma_f32 v[132:133], v[132:133], v[170:171], v[136:137]
	v_pk_fma_f32 v[130:131], v[138:139], v[196:197], v[130:131]
	v_and_b32_e32 v139, 0xffff0000, v129
	v_lshlrev_b32_e32 v138, 16, v129
	v_pk_fma_f32 v[132:133], v[140:141], v[178:179], v[132:133]
	v_pk_mul_f32 v[146:147], v[146:147], v[150:151]
	v_add_f32_e32 v150, 1.0, v152
	v_add_f32_e32 v151, 1.0, v153
	v_and_b32_e32 v153, 0xffff0000, v128
	v_lshlrev_b32_e32 v152, 16, v128
	v_pk_fma_f32 v[136:137], v[144:145], v[138:139], v[132:133]
	v_pk_fma_f32 v[130:131], v[142:143], v[152:153], v[130:131]
	v_mul_f32_e32 v132, 0xbfb8aa3b, v136
	v_mul_f32_e32 v134, 0xbfb8aa3b, v130
	v_mul_f32_e32 v135, 0xbfb8aa3b, v131
	v_exp_f32_e32 v132, v132
	v_mul_f32_e32 v133, 0xbfb8aa3b, v137
	v_exp_f32_e32 v134, v134
	v_exp_f32_e32 v135, v135
	v_exp_f32_e32 v133, v133
	v_add_f32_e32 v132, 1.0, v132
	v_add_f32_e32 v134, 1.0, v134
	v_add_f32_e32 v135, 1.0, v135
	v_rcp_f32_e32 v138, v132
	v_add_f32_e32 v132, 1.0, v133
	v_rcp_f32_e32 v150, v150
	v_rcp_f32_e32 v151, v151
	v_rcp_f32_e32 v134, v134
	v_rcp_f32_e32 v135, v135
	v_rcp_f32_e32 v139, v132
	v_pk_mul_f32 v[184:185], v[206:207], v[212:213] op_sel_hi:[1,0]
	v_pk_mul_f32 v[176:177], v[176:177], v[212:213] op_sel_hi:[1,0]
	v_pk_mul_f32 v[172:173], v[172:173], v[212:213] op_sel_hi:[1,0]
	v_cvt_pk_bf16_f32 v214, v184, v185
	v_cvt_pk_bf16_f32 v215, v176, v177
	v_cvt_pk_bf16_f32 v216, v172, v173
	v_pk_mul_f32 v[132:133], v[148:149], v[150:151]
	v_pk_mul_f32 v[130:131], v[130:131], v[134:135]
	s_and_b64 vcc, exec, s[38:39]
	v_pk_mul_f32 v[134:135], v[136:137], v[138:139]
	global_store_dwordx4 v[162:163], v[214:217], off offset:3584
	s_cbranch_vccnz .LBB0_494
	v_pk_mul_f32 v[136:137], v[146:147], v[146:147]
	v_pk_mul_f32 v[138:139], v[132:133], v[132:133]
	v_add_f32_e32 v136, v136, v137
	v_add_f32_e32 v136, v138, v136
	v_pk_mul_f32 v[140:141], v[130:131], v[130:131]
	v_add_f32_e32 v136, v139, v136
	v_and_b32_e32 v138, 64, v232
	v_add_f32_e32 v136, v140, v136
	v_xor_b32_e32 v137, 1, v232
	v_add_u32_e32 v138, 64, v138
	v_pk_mul_f32 v[142:143], v[134:135], v[134:135]
	v_add_f32_e32 v136, v141, v136
	v_cmp_lt_i32_e32 vcc, v137, v138
	v_add_f32_e32 v136, v142, v136
	v_add_f32_e32 v136, v143, v136
	v_cndmask_b32_e32 v137, v232, v137, vcc
	v_lshlrev_b32_e32 v137, 2, v137
	s_nop 1
	v_mov_b32_dpp v137, v136 quad_perm:[1,0,3,2] row_mask:0xf bank_mask:0xf
	s_waitcnt lgkmcnt(0)
	v_add_f32_e32 v136, v136, v137
	v_xor_b32_e32 v137, 2, v232
	v_cmp_lt_i32_e32 vcc, v137, v138
	s_nop 1
	v_cndmask_b32_e32 v137, v232, v137, vcc
	v_lshlrev_b32_e32 v137, 2, v137
	s_nop 1
	v_mov_b32_dpp v137, v136 quad_perm:[2,3,0,1] row_mask:0xf bank_mask:0xf
	s_waitcnt lgkmcnt(0)
	v_add_f32_e32 v136, v136, v137
	v_xor_b32_e32 v137, 4, v232
	v_cmp_lt_i32_e32 vcc, v137, v138
	s_nop 1
	v_cndmask_b32_e32 v137, v232, v137, vcc
	v_lshlrev_b32_e32 v137, 2, v137
	s_nop 1
	v_mov_b32_dpp v137, v136 row_half_mirror row_mask:0xf bank_mask:0xf
	s_waitcnt lgkmcnt(0)
	v_add_f32_e32 v136, v136, v137
	v_xor_b32_e32 v137, 8, v232
	v_cmp_lt_i32_e32 vcc, v137, v138
	s_nop 1
	v_cndmask_b32_e32 v137, v232, v137, vcc
	v_lshlrev_b32_e32 v137, 2, v137
	s_nop 1
	v_mov_b32_dpp v137, v136 row_mirror row_mask:0xf bank_mask:0xf
	s_waitcnt lgkmcnt(0)
	v_add_f32_e32 v136, v136, v137
	v_add_f32_e32 v136, 0x358637bd, v136
	v_rsq_f32_e32 v136, v136
	s_nop 0
	v_mul_f32_e32 v168, v219, v136
	s_branch .LBB0_494
